# first K iteration peeled (no accumulator zeroing) also in the QK, U, V and down-projection GEMMs
# baseline (speedup 1.0000x reference)
.LBB0_263:
	s_ashr_i32 s13, s12, 31
	s_lshl_b64 s[14:15], s[12:13], 19
	s_add_u32 s14, s28, s14
	s_addc_u32 s15, s29, s15
	s_and_b64 s[16:17], s[2:3], exec
	s_cselect_b32 s13, s15, s21
	s_cselect_b32 s39, s14, s20
	s_ashr_i32 s11, s10, 31
	s_lshl_b64 s[16:17], s[10:11], 19
	s_add_u32 s16, s26, s16
	s_addc_u32 s17, s27, s17
	s_and_b64 s[24:25], s[2:3], exec
	s_cselect_b32 s11, s17, s23
	s_cselect_b32 s62, s16, s22
	s_add_u32 s20, s20, 0x40080
	s_addc_u32 s21, s21, 0
	s_add_u32 s63, s22, 0x100
	s_addc_u32 s64, s23, 0
	s_mov_b32 s65, -2
	ds_read_b128 v[148:151], v190
	ds_read_b128 v[152:155], v190 offset:1024
	ds_read_b128 v[156:159], v190 offset:2048
	ds_read_b128 v[160:163], v190 offset:3072
	ds_read_b128 v[196:199], v191
	ds_read_b128 v[200:203], v191 offset:1024
	ds_read_b128 v[204:207], v191 offset:2048
	ds_read_b128 v[208:211], v191 offset:3072
	s_add_u32 s22, s20, 0xfffc0080
	s_addc_u32 s23, s21, -1
	s_cmp_eq_u32 s65, 12
	s_cselect_b32 s25, s13, s23
	s_cselect_b32 s24, s39, s22
	s_cselect_b32 s23, s11, s64
	s_cselect_b32 s22, s62, s63
	v_lshl_add_u64 v[166:167], s[20:21], 0, v[140:141]
	s_add_i32 m0, s19, 0xc000
	ds_read_b128 v[212:215], v192
	ds_read_b128 v[216:219], v192 offset:1024
	ds_read_b128 v[220:223], v192 offset:2048
	ds_read_b128 v[224:227], v192 offset:3072
	ds_read_b128 v[228:231], v192 offset:4096
	ds_read_b128 v[232:235], v192 offset:5120
	ds_read_b128 v[236:239], v192 offset:6144
	ds_read_b128 v[240:243], v192 offset:7168
	global_load_lds_dwordx4 v[166:167], off
	v_lshl_add_u64 v[166:167], s[20:21], 0, v[142:143]
	s_add_i32 m0, s19, 0xe000
	s_nop 0
	global_load_lds_dwordx4 v[166:167], off
	s_waitcnt vmcnt(8)
	s_waitcnt lgkmcnt(0)
	s_setprio 1
	s_barrier
	v_mfma_f32_16x16x32_bf16 v[124:127], v[148:151], v[212:215], 0
	v_mfma_f32_16x16x32_bf16 v[120:123], v[156:159], v[212:215], 0
	v_mfma_f32_16x16x32_bf16 v[112:115], v[148:151], v[220:223], 0
	v_mfma_f32_16x16x32_bf16 v[104:107], v[156:159], v[220:223], 0
	v_mfma_f32_16x16x32_bf16 v[96:99], v[148:151], v[228:231], 0
	v_mfma_f32_16x16x32_bf16 v[88:91], v[156:159], v[228:231], 0
	v_mfma_f32_16x16x32_bf16 v[80:83], v[148:151], v[236:239], 0
	v_mfma_f32_16x16x32_bf16 v[72:75], v[156:159], v[236:239], 0
	v_mfma_f32_16x16x32_bf16 v[124:127], v[152:155], v[216:219], v[124:127]
	v_mfma_f32_16x16x32_bf16 v[120:123], v[160:163], v[216:219], v[120:123]
	v_mfma_f32_16x16x32_bf16 v[112:115], v[152:155], v[224:227], v[112:115]
	v_mfma_f32_16x16x32_bf16 v[104:107], v[160:163], v[224:227], v[104:107]
	v_mfma_f32_16x16x32_bf16 v[96:99], v[152:155], v[232:235], v[96:99]
	v_mfma_f32_16x16x32_bf16 v[88:91], v[160:163], v[232:235], v[88:91]
	v_mfma_f32_16x16x32_bf16 v[80:83], v[152:155], v[240:243], v[80:83]
	v_mfma_f32_16x16x32_bf16 v[72:75], v[160:163], v[240:243], v[72:75]
	v_mfma_f32_16x16x32_bf16 v[116:119], v[196:199], v[212:215], 0
	v_mfma_f32_16x16x32_bf16 v[108:111], v[204:207], v[212:215], 0
	v_mfma_f32_16x16x32_bf16 v[100:103], v[196:199], v[220:223], 0
	v_mfma_f32_16x16x32_bf16 v[92:95], v[204:207], v[220:223], 0
	v_mfma_f32_16x16x32_bf16 v[84:87], v[196:199], v[228:231], 0
	v_mfma_f32_16x16x32_bf16 v[76:79], v[204:207], v[228:231], 0
	v_mfma_f32_16x16x32_bf16 v[68:71], v[196:199], v[236:239], 0
	v_mfma_f32_16x16x32_bf16 v[64:67], v[204:207], v[236:239], 0
	v_mfma_f32_16x16x32_bf16 v[116:119], v[200:203], v[216:219], v[116:119]
	v_mfma_f32_16x16x32_bf16 v[108:111], v[208:211], v[216:219], v[108:111]
	v_mfma_f32_16x16x32_bf16 v[100:103], v[200:203], v[224:227], v[100:103]
	v_mfma_f32_16x16x32_bf16 v[92:95], v[208:211], v[224:227], v[92:95]
	v_mfma_f32_16x16x32_bf16 v[84:87], v[200:203], v[232:235], v[84:87]
	v_mfma_f32_16x16x32_bf16 v[76:79], v[208:211], v[232:235], v[76:79]
	v_mfma_f32_16x16x32_bf16 v[68:71], v[200:203], v[240:243], v[68:71]
	v_mfma_f32_16x16x32_bf16 v[64:67], v[208:211], v[240:243], v[64:67]
	s_barrier
	s_setprio 0
	s_add_i32 s66, s52, s31
	v_lshl_add_u64 v[166:167], s[22:23], 0, v[130:131]
	s_mov_b32 m0, s66
	ds_read_b128 v[212:215], v192 offset:16384
	ds_read_b128 v[216:219], v192 offset:17408
	ds_read_b128 v[220:223], v192 offset:18432
	ds_read_b128 v[224:227], v192 offset:19456
	ds_read_b128 v[228:231], v192 offset:20480
	ds_read_b128 v[232:235], v192 offset:21504
	ds_read_b128 v[236:239], v192 offset:22528
	ds_read_b128 v[240:243], v192 offset:23552
	global_load_lds_dwordx4 v[166:167], off
	s_add_i32 m0, s66, 0x2000
	s_add_u32 s66, s22, 0x40000
	v_lshl_add_u64 v[244:245], s[22:23], 0, v[134:135]
	s_addc_u32 s67, s23, 0
	s_add_i32 s68, s53, s31
	global_load_lds_dwordx4 v[244:245], off
	v_lshl_add_u64 v[246:247], s[66:67], 0, v[130:131]
	s_mov_b32 m0, s68
	v_lshl_add_u64 v[248:249], s[24:25], 0, v[132:133]
	global_load_lds_dwordx4 v[246:247], off
	v_lshl_add_u64 v[246:247], s[66:67], 0, v[134:135]
	s_add_i32 m0, s68, 0x2000
	s_nop 0
	global_load_lds_dwordx4 v[246:247], off
	v_lshl_add_u64 v[246:247], s[24:25], 0, v[128:129]
	s_mov_b32 m0, s19
	s_nop 0
	global_load_lds_dwordx4 v[246:247], off
	s_mov_b32 m0, s35
	s_nop 0
	global_load_lds_dwordx4 v[248:249], off
	s_waitcnt vmcnt(8)
	s_waitcnt lgkmcnt(0)
	s_setprio 1
	s_barrier
	v_mfma_f32_16x16x32_bf16 v[60:63], v[148:151], v[212:215], 0
	v_mfma_f32_16x16x32_bf16 v[56:59], v[156:159], v[212:215], 0
	v_mfma_f32_16x16x32_bf16 v[48:51], v[148:151], v[220:223], 0
	v_mfma_f32_16x16x32_bf16 v[40:43], v[156:159], v[220:223], 0
	v_mfma_f32_16x16x32_bf16 v[32:35], v[148:151], v[228:231], 0
	v_mfma_f32_16x16x32_bf16 v[24:27], v[156:159], v[228:231], 0
	v_mfma_f32_16x16x32_bf16 v[16:19], v[148:151], v[236:239], 0
	v_mfma_f32_16x16x32_bf16 v[8:11], v[156:159], v[236:239], 0
	v_mfma_f32_16x16x32_bf16 v[60:63], v[152:155], v[216:219], v[60:63]
	v_mfma_f32_16x16x32_bf16 v[56:59], v[160:163], v[216:219], v[56:59]
	v_mfma_f32_16x16x32_bf16 v[48:51], v[152:155], v[224:227], v[48:51]
	v_mfma_f32_16x16x32_bf16 v[40:43], v[160:163], v[224:227], v[40:43]
	v_mfma_f32_16x16x32_bf16 v[32:35], v[152:155], v[232:235], v[32:35]
	v_mfma_f32_16x16x32_bf16 v[24:27], v[160:163], v[232:235], v[24:27]
	v_mfma_f32_16x16x32_bf16 v[16:19], v[152:155], v[240:243], v[16:19]
	v_mfma_f32_16x16x32_bf16 v[8:11], v[160:163], v[240:243], v[8:11]
	v_mfma_f32_16x16x32_bf16 v[52:55], v[196:199], v[212:215], 0
	v_mfma_f32_16x16x32_bf16 v[44:47], v[204:207], v[212:215], 0
	v_mfma_f32_16x16x32_bf16 v[36:39], v[196:199], v[220:223], 0
	v_mfma_f32_16x16x32_bf16 v[28:31], v[204:207], v[220:223], 0
	v_mfma_f32_16x16x32_bf16 v[20:23], v[196:199], v[228:231], 0
	v_mfma_f32_16x16x32_bf16 v[12:15], v[204:207], v[228:231], 0
	v_mfma_f32_16x16x32_bf16 v[4:7], v[196:199], v[236:239], 0
	v_mfma_f32_16x16x32_bf16 v[0:3], v[204:207], v[236:239], 0
	v_mfma_f32_16x16x32_bf16 v[52:55], v[200:203], v[216:219], v[52:55]
	v_mfma_f32_16x16x32_bf16 v[44:47], v[208:211], v[216:219], v[44:47]
	v_mfma_f32_16x16x32_bf16 v[36:39], v[200:203], v[224:227], v[36:39]
	v_mfma_f32_16x16x32_bf16 v[28:31], v[208:211], v[224:227], v[28:31]
	v_mfma_f32_16x16x32_bf16 v[20:23], v[200:203], v[232:235], v[20:23]
	v_mfma_f32_16x16x32_bf16 v[12:15], v[208:211], v[232:235], v[12:15]
	v_mfma_f32_16x16x32_bf16 v[4:7], v[200:203], v[240:243], v[4:7]
	v_mfma_f32_16x16x32_bf16 v[0:3], v[208:211], v[240:243], v[0:3]
	s_barrier
	s_setprio 0
	s_add_i32 s66, 0, 0x18000
	v_add_u32_e32 v138, s66, v182
	s_add_i32 s67, 0, 0x1c000
	ds_read_b128 v[148:151], v138
	ds_read_b128 v[152:155], v138 offset:1024
	ds_read_b128 v[156:159], v138 offset:2048
	ds_read_b128 v[160:163], v138 offset:3072
	v_add_u32_e32 v138, s67, v182
	ds_read_b128 v[196:199], v138
	ds_read_b128 v[200:203], v138 offset:1024
	ds_read_b128 v[204:207], v138 offset:2048
	ds_read_b128 v[208:211], v138 offset:3072
	s_add_u32 s24, s24, 0x40000
	s_addc_u32 s25, s25, 0
	s_mov_b32 m0, s36
	v_lshl_add_u64 v[250:251], s[24:25], 0, v[128:129]
	ds_read_b128 v[212:215], v192 offset:32768
	ds_read_b128 v[216:219], v192 offset:33792
	ds_read_b128 v[220:223], v192 offset:34816
	ds_read_b128 v[224:227], v192 offset:35840
	ds_read_b128 v[228:231], v192 offset:36864
	ds_read_b128 v[232:235], v192 offset:37888
	ds_read_b128 v[236:239], v192 offset:38912
	ds_read_b128 v[240:243], v192 offset:39936
	global_load_lds_dwordx4 v[250:251], off
	v_lshl_add_u64 v[250:251], s[24:25], 0, v[132:133]
	s_mov_b32 m0, s37
	s_nop 0
	global_load_lds_dwordx4 v[250:251], off
	s_waitcnt vmcnt(8)
	s_waitcnt lgkmcnt(0)
	s_setprio 1
	s_barrier
	v_mfma_f32_16x16x32_bf16 v[124:127], v[148:151], v[212:215], v[124:127]
	v_mfma_f32_16x16x32_bf16 v[120:123], v[156:159], v[212:215], v[120:123]
	v_mfma_f32_16x16x32_bf16 v[112:115], v[148:151], v[220:223], v[112:115]
	v_mfma_f32_16x16x32_bf16 v[104:107], v[156:159], v[220:223], v[104:107]
	v_mfma_f32_16x16x32_bf16 v[96:99], v[148:151], v[228:231], v[96:99]
	v_mfma_f32_16x16x32_bf16 v[88:91], v[156:159], v[228:231], v[88:91]
	v_mfma_f32_16x16x32_bf16 v[80:83], v[148:151], v[236:239], v[80:83]
	v_mfma_f32_16x16x32_bf16 v[72:75], v[156:159], v[236:239], v[72:75]
	v_mfma_f32_16x16x32_bf16 v[124:127], v[152:155], v[216:219], v[124:127]
	v_mfma_f32_16x16x32_bf16 v[120:123], v[160:163], v[216:219], v[120:123]
	v_mfma_f32_16x16x32_bf16 v[112:115], v[152:155], v[224:227], v[112:115]
	v_mfma_f32_16x16x32_bf16 v[104:107], v[160:163], v[224:227], v[104:107]
	v_mfma_f32_16x16x32_bf16 v[96:99], v[152:155], v[232:235], v[96:99]
	v_mfma_f32_16x16x32_bf16 v[88:91], v[160:163], v[232:235], v[88:91]
	v_mfma_f32_16x16x32_bf16 v[80:83], v[152:155], v[240:243], v[80:83]
	v_mfma_f32_16x16x32_bf16 v[72:75], v[160:163], v[240:243], v[72:75]
	v_mfma_f32_16x16x32_bf16 v[116:119], v[196:199], v[212:215], v[116:119]
	v_mfma_f32_16x16x32_bf16 v[108:111], v[204:207], v[212:215], v[108:111]
	v_mfma_f32_16x16x32_bf16 v[100:103], v[196:199], v[220:223], v[100:103]
	v_mfma_f32_16x16x32_bf16 v[92:95], v[204:207], v[220:223], v[92:95]
	v_mfma_f32_16x16x32_bf16 v[84:87], v[196:199], v[228:231], v[84:87]
	v_mfma_f32_16x16x32_bf16 v[76:79], v[204:207], v[228:231], v[76:79]
	v_mfma_f32_16x16x32_bf16 v[68:71], v[196:199], v[236:239], v[68:71]
	v_mfma_f32_16x16x32_bf16 v[64:67], v[204:207], v[236:239], v[64:67]
	v_mfma_f32_16x16x32_bf16 v[116:119], v[200:203], v[216:219], v[116:119]
	v_mfma_f32_16x16x32_bf16 v[108:111], v[208:211], v[216:219], v[108:111]
	v_mfma_f32_16x16x32_bf16 v[100:103], v[200:203], v[224:227], v[100:103]
	v_mfma_f32_16x16x32_bf16 v[92:95], v[208:211], v[224:227], v[92:95]
	v_mfma_f32_16x16x32_bf16 v[84:87], v[200:203], v[232:235], v[84:87]
	v_mfma_f32_16x16x32_bf16 v[76:79], v[208:211], v[232:235], v[76:79]
	v_mfma_f32_16x16x32_bf16 v[68:71], v[200:203], v[240:243], v[68:71]
	v_mfma_f32_16x16x32_bf16 v[64:67], v[208:211], v[240:243], v[64:67]
	s_barrier
	s_setprio 0
	s_add_i32 s24, s66, s31
	v_lshl_add_u64 v[166:167], v[166:167], 0, s[6:7]
	s_mov_b32 m0, s24
	ds_read_b128 v[212:215], v192 offset:49152
	ds_read_b128 v[216:219], v192 offset:50176
	ds_read_b128 v[220:223], v192 offset:51200
	ds_read_b128 v[224:227], v192 offset:52224
	ds_read_b128 v[228:231], v192 offset:53248
	ds_read_b128 v[232:235], v192 offset:54272
	ds_read_b128 v[236:239], v192 offset:55296
	ds_read_b128 v[240:243], v192 offset:56320
	global_load_lds_dwordx4 v[166:167], off
	s_add_i32 m0, s24, 0x2000
	s_add_u32 s22, s22, 0x40080
	v_lshl_add_u64 v[166:167], v[244:245], 0, s[6:7]
	s_addc_u32 s23, s23, 0
	s_add_i32 s24, s67, s31
	global_load_lds_dwordx4 v[166:167], off
	v_lshl_add_u64 v[166:167], s[22:23], 0, v[130:131]
	s_mov_b32 m0, s24
	s_nop 0
	global_load_lds_dwordx4 v[166:167], off
	v_lshl_add_u64 v[166:167], s[22:23], 0, v[134:135]
	s_add_i32 m0, s24, 0x2000
	s_nop 0
	global_load_lds_dwordx4 v[166:167], off
	v_lshl_add_u64 v[166:167], v[246:247], 0, s[6:7]
	s_mov_b32 m0, s48
	s_nop 0
	global_load_lds_dwordx4 v[166:167], off
	v_lshl_add_u64 v[166:167], v[248:249], 0, s[6:7]
	s_mov_b32 m0, s49
	s_nop 0
	global_load_lds_dwordx4 v[166:167], off
	s_waitcnt vmcnt(8)
	s_waitcnt lgkmcnt(0)
	s_setprio 1
	s_barrier
	v_mfma_f32_16x16x32_bf16 v[60:63], v[148:151], v[212:215], v[60:63]
	v_mfma_f32_16x16x32_bf16 v[56:59], v[156:159], v[212:215], v[56:59]
	v_mfma_f32_16x16x32_bf16 v[48:51], v[148:151], v[220:223], v[48:51]
	v_mfma_f32_16x16x32_bf16 v[40:43], v[156:159], v[220:223], v[40:43]
	v_mfma_f32_16x16x32_bf16 v[32:35], v[148:151], v[228:231], v[32:35]
	v_mfma_f32_16x16x32_bf16 v[24:27], v[156:159], v[228:231], v[24:27]
	v_mfma_f32_16x16x32_bf16 v[16:19], v[148:151], v[236:239], v[16:19]
	v_mfma_f32_16x16x32_bf16 v[8:11], v[156:159], v[236:239], v[8:11]
	v_mfma_f32_16x16x32_bf16 v[60:63], v[152:155], v[216:219], v[60:63]
	v_mfma_f32_16x16x32_bf16 v[56:59], v[160:163], v[216:219], v[56:59]
	v_mfma_f32_16x16x32_bf16 v[48:51], v[152:155], v[224:227], v[48:51]
	v_mfma_f32_16x16x32_bf16 v[40:43], v[160:163], v[224:227], v[40:43]
	v_mfma_f32_16x16x32_bf16 v[32:35], v[152:155], v[232:235], v[32:35]
	v_mfma_f32_16x16x32_bf16 v[24:27], v[160:163], v[232:235], v[24:27]
	v_mfma_f32_16x16x32_bf16 v[16:19], v[152:155], v[240:243], v[16:19]
	v_mfma_f32_16x16x32_bf16 v[8:11], v[160:163], v[240:243], v[8:11]
	v_mfma_f32_16x16x32_bf16 v[52:55], v[196:199], v[212:215], v[52:55]
	v_mfma_f32_16x16x32_bf16 v[44:47], v[204:207], v[212:215], v[44:47]
	v_mfma_f32_16x16x32_bf16 v[36:39], v[196:199], v[220:223], v[36:39]
	v_mfma_f32_16x16x32_bf16 v[28:31], v[204:207], v[220:223], v[28:31]
	v_mfma_f32_16x16x32_bf16 v[20:23], v[196:199], v[228:231], v[20:23]
	v_mfma_f32_16x16x32_bf16 v[12:15], v[204:207], v[228:231], v[12:15]
	v_mfma_f32_16x16x32_bf16 v[4:7], v[196:199], v[236:239], v[4:7]
	v_mfma_f32_16x16x32_bf16 v[0:3], v[204:207], v[236:239], v[0:3]
	v_mfma_f32_16x16x32_bf16 v[52:55], v[200:203], v[216:219], v[52:55]
	v_mfma_f32_16x16x32_bf16 v[44:47], v[208:211], v[216:219], v[44:47]
	v_mfma_f32_16x16x32_bf16 v[36:39], v[200:203], v[224:227], v[36:39]
	v_mfma_f32_16x16x32_bf16 v[28:31], v[208:211], v[224:227], v[28:31]
	v_mfma_f32_16x16x32_bf16 v[20:23], v[200:203], v[232:235], v[20:23]
	v_mfma_f32_16x16x32_bf16 v[12:15], v[208:211], v[232:235], v[12:15]
	v_mfma_f32_16x16x32_bf16 v[4:7], v[200:203], v[240:243], v[4:7]
	v_mfma_f32_16x16x32_bf16 v[0:3], v[208:211], v[240:243], v[0:3]
	s_barrier
	s_setprio 0
	s_add_i32 s65, s65, 2
	s_add_u32 s20, s20, 0x100
	s_addc_u32 s21, s21, 0
	s_add_u32 s63, s63, 0x100
	s_addc_u32 s64, s64, 0
	s_cmp_gt_u32 s65, 13
	s_cbranch_scc0 .LBB0_264
	s_branch .Lpeel_exit_qk
.LBB0_264:
	ds_read_b128 v[148:151], v190
	ds_read_b128 v[152:155], v190 offset:1024
	ds_read_b128 v[156:159], v190 offset:2048
	ds_read_b128 v[160:163], v190 offset:3072
	ds_read_b128 v[196:199], v191
	ds_read_b128 v[200:203], v191 offset:1024
	ds_read_b128 v[204:207], v191 offset:2048
	ds_read_b128 v[208:211], v191 offset:3072
	s_add_u32 s22, s20, 0xfffc0080
	s_addc_u32 s23, s21, -1
	s_cmp_eq_u32 s65, 12
	s_cselect_b32 s25, s13, s23
	s_cselect_b32 s24, s39, s22
	s_cselect_b32 s23, s11, s64
	s_cselect_b32 s22, s62, s63
	v_lshl_add_u64 v[166:167], s[20:21], 0, v[140:141]
	s_add_i32 m0, s19, 0xc000
	ds_read_b128 v[212:215], v192
	ds_read_b128 v[216:219], v192 offset:1024
	ds_read_b128 v[220:223], v192 offset:2048
	ds_read_b128 v[224:227], v192 offset:3072
	ds_read_b128 v[228:231], v192 offset:4096
	ds_read_b128 v[232:235], v192 offset:5120
	ds_read_b128 v[236:239], v192 offset:6144
	ds_read_b128 v[240:243], v192 offset:7168
	global_load_lds_dwordx4 v[166:167], off
	v_lshl_add_u64 v[166:167], s[20:21], 0, v[142:143]
	s_add_i32 m0, s19, 0xe000
	s_nop 0
	global_load_lds_dwordx4 v[166:167], off
	s_waitcnt vmcnt(8)
	s_waitcnt lgkmcnt(0)
	s_setprio 1
	s_barrier
	v_mfma_f32_16x16x32_bf16 v[124:127], v[148:151], v[212:215], v[124:127]
	v_mfma_f32_16x16x32_bf16 v[120:123], v[156:159], v[212:215], v[120:123]
	v_mfma_f32_16x16x32_bf16 v[112:115], v[148:151], v[220:223], v[112:115]
	v_mfma_f32_16x16x32_bf16 v[104:107], v[156:159], v[220:223], v[104:107]
	v_mfma_f32_16x16x32_bf16 v[96:99], v[148:151], v[228:231], v[96:99]
	v_mfma_f32_16x16x32_bf16 v[88:91], v[156:159], v[228:231], v[88:91]
	v_mfma_f32_16x16x32_bf16 v[80:83], v[148:151], v[236:239], v[80:83]
	v_mfma_f32_16x16x32_bf16 v[72:75], v[156:159], v[236:239], v[72:75]
	v_mfma_f32_16x16x32_bf16 v[124:127], v[152:155], v[216:219], v[124:127]
	v_mfma_f32_16x16x32_bf16 v[120:123], v[160:163], v[216:219], v[120:123]
	v_mfma_f32_16x16x32_bf16 v[112:115], v[152:155], v[224:227], v[112:115]
	v_mfma_f32_16x16x32_bf16 v[104:107], v[160:163], v[224:227], v[104:107]
	v_mfma_f32_16x16x32_bf16 v[96:99], v[152:155], v[232:235], v[96:99]
	v_mfma_f32_16x16x32_bf16 v[88:91], v[160:163], v[232:235], v[88:91]
	v_mfma_f32_16x16x32_bf16 v[80:83], v[152:155], v[240:243], v[80:83]
	v_mfma_f32_16x16x32_bf16 v[72:75], v[160:163], v[240:243], v[72:75]
	v_mfma_f32_16x16x32_bf16 v[116:119], v[196:199], v[212:215], v[116:119]
	v_mfma_f32_16x16x32_bf16 v[108:111], v[204:207], v[212:215], v[108:111]
	v_mfma_f32_16x16x32_bf16 v[100:103], v[196:199], v[220:223], v[100:103]
	v_mfma_f32_16x16x32_bf16 v[92:95], v[204:207], v[220:223], v[92:95]
	v_mfma_f32_16x16x32_bf16 v[84:87], v[196:199], v[228:231], v[84:87]
	v_mfma_f32_16x16x32_bf16 v[76:79], v[204:207], v[228:231], v[76:79]
	v_mfma_f32_16x16x32_bf16 v[68:71], v[196:199], v[236:239], v[68:71]
	v_mfma_f32_16x16x32_bf16 v[64:67], v[204:207], v[236:239], v[64:67]
	v_mfma_f32_16x16x32_bf16 v[116:119], v[200:203], v[216:219], v[116:119]
	v_mfma_f32_16x16x32_bf16 v[108:111], v[208:211], v[216:219], v[108:111]
	v_mfma_f32_16x16x32_bf16 v[100:103], v[200:203], v[224:227], v[100:103]
	v_mfma_f32_16x16x32_bf16 v[92:95], v[208:211], v[224:227], v[92:95]
	v_mfma_f32_16x16x32_bf16 v[84:87], v[200:203], v[232:235], v[84:87]
	v_mfma_f32_16x16x32_bf16 v[76:79], v[208:211], v[232:235], v[76:79]
	v_mfma_f32_16x16x32_bf16 v[68:71], v[200:203], v[240:243], v[68:71]
	v_mfma_f32_16x16x32_bf16 v[64:67], v[208:211], v[240:243], v[64:67]
	s_barrier
	s_setprio 0
	s_add_i32 s66, s52, s31
	v_lshl_add_u64 v[166:167], s[22:23], 0, v[130:131]
	s_mov_b32 m0, s66
	ds_read_b128 v[212:215], v192 offset:16384
	ds_read_b128 v[216:219], v192 offset:17408
	ds_read_b128 v[220:223], v192 offset:18432
	ds_read_b128 v[224:227], v192 offset:19456
	ds_read_b128 v[228:231], v192 offset:20480
	ds_read_b128 v[232:235], v192 offset:21504
	ds_read_b128 v[236:239], v192 offset:22528
	ds_read_b128 v[240:243], v192 offset:23552
	global_load_lds_dwordx4 v[166:167], off
	s_add_i32 m0, s66, 0x2000
	s_add_u32 s66, s22, 0x40000
	v_lshl_add_u64 v[244:245], s[22:23], 0, v[134:135]
	s_addc_u32 s67, s23, 0
	s_add_i32 s68, s53, s31
	global_load_lds_dwordx4 v[244:245], off
	v_lshl_add_u64 v[246:247], s[66:67], 0, v[130:131]
	s_mov_b32 m0, s68
	v_lshl_add_u64 v[248:249], s[24:25], 0, v[132:133]
	global_load_lds_dwordx4 v[246:247], off
	v_lshl_add_u64 v[246:247], s[66:67], 0, v[134:135]
	s_add_i32 m0, s68, 0x2000
	s_nop 0
	global_load_lds_dwordx4 v[246:247], off
	v_lshl_add_u64 v[246:247], s[24:25], 0, v[128:129]
	s_mov_b32 m0, s19
	s_nop 0
	global_load_lds_dwordx4 v[246:247], off
	s_mov_b32 m0, s35
	s_nop 0
	global_load_lds_dwordx4 v[248:249], off
	s_waitcnt vmcnt(8)
	s_waitcnt lgkmcnt(0)
	s_setprio 1
	s_barrier
	v_mfma_f32_16x16x32_bf16 v[60:63], v[148:151], v[212:215], v[60:63]
	v_mfma_f32_16x16x32_bf16 v[56:59], v[156:159], v[212:215], v[56:59]
	v_mfma_f32_16x16x32_bf16 v[48:51], v[148:151], v[220:223], v[48:51]
	v_mfma_f32_16x16x32_bf16 v[40:43], v[156:159], v[220:223], v[40:43]
	v_mfma_f32_16x16x32_bf16 v[32:35], v[148:151], v[228:231], v[32:35]
	v_mfma_f32_16x16x32_bf16 v[24:27], v[156:159], v[228:231], v[24:27]
	v_mfma_f32_16x16x32_bf16 v[16:19], v[148:151], v[236:239], v[16:19]
	v_mfma_f32_16x16x32_bf16 v[8:11], v[156:159], v[236:239], v[8:11]
	v_mfma_f32_16x16x32_bf16 v[60:63], v[152:155], v[216:219], v[60:63]
	v_mfma_f32_16x16x32_bf16 v[56:59], v[160:163], v[216:219], v[56:59]
	v_mfma_f32_16x16x32_bf16 v[48:51], v[152:155], v[224:227], v[48:51]
	v_mfma_f32_16x16x32_bf16 v[40:43], v[160:163], v[224:227], v[40:43]
	v_mfma_f32_16x16x32_bf16 v[32:35], v[152:155], v[232:235], v[32:35]
	v_mfma_f32_16x16x32_bf16 v[24:27], v[160:163], v[232:235], v[24:27]
	v_mfma_f32_16x16x32_bf16 v[16:19], v[152:155], v[240:243], v[16:19]
	v_mfma_f32_16x16x32_bf16 v[8:11], v[160:163], v[240:243], v[8:11]
	v_mfma_f32_16x16x32_bf16 v[52:55], v[196:199], v[212:215], v[52:55]
	v_mfma_f32_16x16x32_bf16 v[44:47], v[204:207], v[212:215], v[44:47]
	v_mfma_f32_16x16x32_bf16 v[36:39], v[196:199], v[220:223], v[36:39]
	v_mfma_f32_16x16x32_bf16 v[28:31], v[204:207], v[220:223], v[28:31]
	v_mfma_f32_16x16x32_bf16 v[20:23], v[196:199], v[228:231], v[20:23]
	v_mfma_f32_16x16x32_bf16 v[12:15], v[204:207], v[228:231], v[12:15]
	v_mfma_f32_16x16x32_bf16 v[4:7], v[196:199], v[236:239], v[4:7]
	v_mfma_f32_16x16x32_bf16 v[0:3], v[204:207], v[236:239], v[0:3]
	v_mfma_f32_16x16x32_bf16 v[52:55], v[200:203], v[216:219], v[52:55]
	v_mfma_f32_16x16x32_bf16 v[44:47], v[208:211], v[216:219], v[44:47]
	v_mfma_f32_16x16x32_bf16 v[36:39], v[200:203], v[224:227], v[36:39]
	v_mfma_f32_16x16x32_bf16 v[28:31], v[208:211], v[224:227], v[28:31]
	v_mfma_f32_16x16x32_bf16 v[20:23], v[200:203], v[232:235], v[20:23]
	v_mfma_f32_16x16x32_bf16 v[12:15], v[208:211], v[232:235], v[12:15]
	v_mfma_f32_16x16x32_bf16 v[4:7], v[200:203], v[240:243], v[4:7]
	v_mfma_f32_16x16x32_bf16 v[0:3], v[208:211], v[240:243], v[0:3]
	s_barrier
	s_setprio 0
	s_add_i32 s66, 0, 0x18000
	v_add_u32_e32 v138, s66, v182
	s_add_i32 s67, 0, 0x1c000
	ds_read_b128 v[148:151], v138
	ds_read_b128 v[152:155], v138 offset:1024
	ds_read_b128 v[156:159], v138 offset:2048
	ds_read_b128 v[160:163], v138 offset:3072
	v_add_u32_e32 v138, s67, v182
	ds_read_b128 v[196:199], v138
	ds_read_b128 v[200:203], v138 offset:1024
	ds_read_b128 v[204:207], v138 offset:2048
	ds_read_b128 v[208:211], v138 offset:3072
	s_add_u32 s24, s24, 0x40000
	s_addc_u32 s25, s25, 0
	s_mov_b32 m0, s36
	v_lshl_add_u64 v[250:251], s[24:25], 0, v[128:129]
	ds_read_b128 v[212:215], v192 offset:32768
	ds_read_b128 v[216:219], v192 offset:33792
	ds_read_b128 v[220:223], v192 offset:34816
	ds_read_b128 v[224:227], v192 offset:35840
	ds_read_b128 v[228:231], v192 offset:36864
	ds_read_b128 v[232:235], v192 offset:37888
	ds_read_b128 v[236:239], v192 offset:38912
	ds_read_b128 v[240:243], v192 offset:39936
	global_load_lds_dwordx4 v[250:251], off
	v_lshl_add_u64 v[250:251], s[24:25], 0, v[132:133]
	s_mov_b32 m0, s37
	s_nop 0
	global_load_lds_dwordx4 v[250:251], off
	s_waitcnt vmcnt(8)
	s_waitcnt lgkmcnt(0)
	s_setprio 1
	s_barrier
	v_mfma_f32_16x16x32_bf16 v[124:127], v[148:151], v[212:215], v[124:127]
	v_mfma_f32_16x16x32_bf16 v[120:123], v[156:159], v[212:215], v[120:123]
	v_mfma_f32_16x16x32_bf16 v[112:115], v[148:151], v[220:223], v[112:115]
	v_mfma_f32_16x16x32_bf16 v[104:107], v[156:159], v[220:223], v[104:107]
	v_mfma_f32_16x16x32_bf16 v[96:99], v[148:151], v[228:231], v[96:99]
	v_mfma_f32_16x16x32_bf16 v[88:91], v[156:159], v[228:231], v[88:91]
	v_mfma_f32_16x16x32_bf16 v[80:83], v[148:151], v[236:239], v[80:83]
	v_mfma_f32_16x16x32_bf16 v[72:75], v[156:159], v[236:239], v[72:75]
	v_mfma_f32_16x16x32_bf16 v[124:127], v[152:155], v[216:219], v[124:127]
	v_mfma_f32_16x16x32_bf16 v[120:123], v[160:163], v[216:219], v[120:123]
	v_mfma_f32_16x16x32_bf16 v[112:115], v[152:155], v[224:227], v[112:115]
	v_mfma_f32_16x16x32_bf16 v[104:107], v[160:163], v[224:227], v[104:107]
	v_mfma_f32_16x16x32_bf16 v[96:99], v[152:155], v[232:235], v[96:99]
	v_mfma_f32_16x16x32_bf16 v[88:91], v[160:163], v[232:235], v[88:91]
	v_mfma_f32_16x16x32_bf16 v[80:83], v[152:155], v[240:243], v[80:83]
	v_mfma_f32_16x16x32_bf16 v[72:75], v[160:163], v[240:243], v[72:75]
	v_mfma_f32_16x16x32_bf16 v[116:119], v[196:199], v[212:215], v[116:119]
	v_mfma_f32_16x16x32_bf16 v[108:111], v[204:207], v[212:215], v[108:111]
	v_mfma_f32_16x16x32_bf16 v[100:103], v[196:199], v[220:223], v[100:103]
	v_mfma_f32_16x16x32_bf16 v[92:95], v[204:207], v[220:223], v[92:95]
	v_mfma_f32_16x16x32_bf16 v[84:87], v[196:199], v[228:231], v[84:87]
	v_mfma_f32_16x16x32_bf16 v[76:79], v[204:207], v[228:231], v[76:79]
	v_mfma_f32_16x16x32_bf16 v[68:71], v[196:199], v[236:239], v[68:71]
	v_mfma_f32_16x16x32_bf16 v[64:67], v[204:207], v[236:239], v[64:67]
	v_mfma_f32_16x16x32_bf16 v[116:119], v[200:203], v[216:219], v[116:119]
	v_mfma_f32_16x16x32_bf16 v[108:111], v[208:211], v[216:219], v[108:111]
	v_mfma_f32_16x16x32_bf16 v[100:103], v[200:203], v[224:227], v[100:103]
	v_mfma_f32_16x16x32_bf16 v[92:95], v[208:211], v[224:227], v[92:95]
	v_mfma_f32_16x16x32_bf16 v[84:87], v[200:203], v[232:235], v[84:87]
	v_mfma_f32_16x16x32_bf16 v[76:79], v[208:211], v[232:235], v[76:79]
	v_mfma_f32_16x16x32_bf16 v[68:71], v[200:203], v[240:243], v[68:71]
	v_mfma_f32_16x16x32_bf16 v[64:67], v[208:211], v[240:243], v[64:67]
	s_barrier
	s_setprio 0
	s_add_i32 s24, s66, s31
	v_lshl_add_u64 v[166:167], v[166:167], 0, s[6:7]
	s_mov_b32 m0, s24
	ds_read_b128 v[212:215], v192 offset:49152
	ds_read_b128 v[216:219], v192 offset:50176
	ds_read_b128 v[220:223], v192 offset:51200
	ds_read_b128 v[224:227], v192 offset:52224
	ds_read_b128 v[228:231], v192 offset:53248
	ds_read_b128 v[232:235], v192 offset:54272
	ds_read_b128 v[236:239], v192 offset:55296
	ds_read_b128 v[240:243], v192 offset:56320
	global_load_lds_dwordx4 v[166:167], off
	s_add_i32 m0, s24, 0x2000
	s_add_u32 s22, s22, 0x40080
	v_lshl_add_u64 v[166:167], v[244:245], 0, s[6:7]
	s_addc_u32 s23, s23, 0
	s_add_i32 s24, s67, s31
	global_load_lds_dwordx4 v[166:167], off
	v_lshl_add_u64 v[166:167], s[22:23], 0, v[130:131]
	s_mov_b32 m0, s24
	s_nop 0
	global_load_lds_dwordx4 v[166:167], off
	v_lshl_add_u64 v[166:167], s[22:23], 0, v[134:135]
	s_add_i32 m0, s24, 0x2000
	s_nop 0
	global_load_lds_dwordx4 v[166:167], off
	v_lshl_add_u64 v[166:167], v[246:247], 0, s[6:7]
	s_mov_b32 m0, s48
	s_nop 0
	global_load_lds_dwordx4 v[166:167], off
	v_lshl_add_u64 v[166:167], v[248:249], 0, s[6:7]
	s_mov_b32 m0, s49
	s_nop 0
	global_load_lds_dwordx4 v[166:167], off
	s_waitcnt vmcnt(8)
	s_waitcnt lgkmcnt(0)
	s_setprio 1
	s_barrier
	v_mfma_f32_16x16x32_bf16 v[60:63], v[148:151], v[212:215], v[60:63]
	v_mfma_f32_16x16x32_bf16 v[56:59], v[156:159], v[212:215], v[56:59]
	v_mfma_f32_16x16x32_bf16 v[48:51], v[148:151], v[220:223], v[48:51]
	v_mfma_f32_16x16x32_bf16 v[40:43], v[156:159], v[220:223], v[40:43]
	v_mfma_f32_16x16x32_bf16 v[32:35], v[148:151], v[228:231], v[32:35]
	v_mfma_f32_16x16x32_bf16 v[24:27], v[156:159], v[228:231], v[24:27]
	v_mfma_f32_16x16x32_bf16 v[16:19], v[148:151], v[236:239], v[16:19]
	v_mfma_f32_16x16x32_bf16 v[8:11], v[156:159], v[236:239], v[8:11]
	v_mfma_f32_16x16x32_bf16 v[60:63], v[152:155], v[216:219], v[60:63]
	v_mfma_f32_16x16x32_bf16 v[56:59], v[160:163], v[216:219], v[56:59]
	v_mfma_f32_16x16x32_bf16 v[48:51], v[152:155], v[224:227], v[48:51]
	v_mfma_f32_16x16x32_bf16 v[40:43], v[160:163], v[224:227], v[40:43]
	v_mfma_f32_16x16x32_bf16 v[32:35], v[152:155], v[232:235], v[32:35]
	v_mfma_f32_16x16x32_bf16 v[24:27], v[160:163], v[232:235], v[24:27]
	v_mfma_f32_16x16x32_bf16 v[16:19], v[152:155], v[240:243], v[16:19]
	v_mfma_f32_16x16x32_bf16 v[8:11], v[160:163], v[240:243], v[8:11]
	v_mfma_f32_16x16x32_bf16 v[52:55], v[196:199], v[212:215], v[52:55]
	v_mfma_f32_16x16x32_bf16 v[44:47], v[204:207], v[212:215], v[44:47]
	v_mfma_f32_16x16x32_bf16 v[36:39], v[196:199], v[220:223], v[36:39]
	v_mfma_f32_16x16x32_bf16 v[28:31], v[204:207], v[220:223], v[28:31]
	v_mfma_f32_16x16x32_bf16 v[20:23], v[196:199], v[228:231], v[20:23]
	v_mfma_f32_16x16x32_bf16 v[12:15], v[204:207], v[228:231], v[12:15]
	v_mfma_f32_16x16x32_bf16 v[4:7], v[196:199], v[236:239], v[4:7]
	v_mfma_f32_16x16x32_bf16 v[0:3], v[204:207], v[236:239], v[0:3]
	v_mfma_f32_16x16x32_bf16 v[52:55], v[200:203], v[216:219], v[52:55]
	v_mfma_f32_16x16x32_bf16 v[44:47], v[208:211], v[216:219], v[44:47]
	v_mfma_f32_16x16x32_bf16 v[36:39], v[200:203], v[224:227], v[36:39]
	v_mfma_f32_16x16x32_bf16 v[28:31], v[208:211], v[224:227], v[28:31]
	v_mfma_f32_16x16x32_bf16 v[20:23], v[200:203], v[232:235], v[20:23]
	v_mfma_f32_16x16x32_bf16 v[12:15], v[208:211], v[232:235], v[12:15]
	v_mfma_f32_16x16x32_bf16 v[4:7], v[200:203], v[240:243], v[4:7]
	v_mfma_f32_16x16x32_bf16 v[0:3], v[208:211], v[240:243], v[0:3]
	s_barrier
	s_setprio 0
	s_add_i32 s65, s65, 2
	s_add_u32 s20, s20, 0x100
	s_addc_u32 s21, s21, 0
	s_add_u32 s63, s63, 0x100
	s_addc_u32 s64, s64, 0
	s_cmp_gt_u32 s65, 13
	s_cbranch_scc0 .LBB0_264
.Lpeel_exit_qk:
	s_and_b64 vcc, exec, s[8:9]
	s_cbranch_vccz .LBB0_267
	s_barrier
.LBB0_267:
	s_cmp_lt_i32 s38, 2
	s_cselect_b64 vcc, -1, 0
	s_and_b64 s[20:21], vcc, exec
	s_cselect_b32 s20, s40, s42
	s_cselect_b32 s21, s41, s43
	v_lshlrev_b32_e32 v138, 2, v136
	global_load_dwordx4 v[148:151], v138, s[20:21]
	global_load_dwordx4 v[152:155], v138, s[20:21] offset:16
	global_load_dwordx4 v[198:201], v138, s[20:21] offset:128
	global_load_dwordx4 v[202:205], v138, s[20:21] offset:144
	v_pk_mul_f32 v[156:157], v[126:127], v[126:127]
	v_pk_mul_f32 v[158:159], v[124:125], v[124:125]
	v_pk_mul_f32 v[160:161], v[122:123], v[122:123]
	v_pk_mul_f32 v[162:163], v[120:121], v[120:121]
	v_pk_mov_b32 v[208:209], v[158:159], v[156:157] op_sel:[1,0]
	v_mov_b32_e32 v159, v157
	v_pk_mov_b32 v[156:157], v[162:163], v[160:161] op_sel:[1,0]
	v_mov_b32_e32 v163, v161
	v_xor_b32_e32 v197, 16, v193
	v_and_b32_e32 v167, 64, v193
	v_mul_f32_e32 v166, v117, v117
	v_mul_f32_e32 v196, v119, v119
	v_pk_add_f32 v[158:159], v[208:209], v[158:159]
	v_pk_add_f32 v[156:157], v[156:157], v[162:163]
	v_mul_f32_e32 v210, v108, v108
	v_mul_f32_e32 v211, v109, v109
	v_mul_f32_e32 v212, v110, v110
	v_mul_f32_e32 v213, v111, v111
	v_add_u32_e32 v214, 64, v167
	v_pk_fma_f32 v[160:161], v[116:117], v[116:117], v[166:167] op_sel_hi:[1,1,0]
	v_pk_fma_f32 v[166:167], v[118:119], v[118:119], v[196:197] op_sel_hi:[1,1,0]
	v_pk_add_f32 v[158:159], v[158:159], v[158:159] op_sel:[0,1] op_sel_hi:[1,0]
	v_pk_add_f32 v[156:157], v[156:157], v[156:157] op_sel:[0,1] op_sel_hi:[1,0]
	v_mov_b32_e32 v161, v212
	v_mov_b32_e32 v167, v213
	v_mov_b32_e32 v159, v210
	v_mov_b32_e32 v157, v211
	v_cndmask_b32_e32 v206, 1.0, v195, vcc
	v_cmp_lt_i32_e32 vcc, v197, v214
	v_pk_add_f32 v[160:161], v[160:161], v[166:167]
	v_pk_add_f32 v[156:157], v[158:159], v[156:157]
	v_cndmask_b32_e32 v196, v193, v197, vcc
	v_pk_add_f32 v[156:157], v[156:157], v[160:161]
	v_lshlrev_b32_e32 v197, 2, v196
	v_add_f32_e32 v156, v156, v157
	ds_bpermute_b32 v157, v197, v156
	v_xor_b32_e32 v207, 32, v193
	v_cmp_lt_i32_e32 vcc, v207, v214
	s_cselect_b32 s11, s60, 0x11000000
	s_add_u32 s11, s80, s11
	v_cndmask_b32_e32 v207, v193, v207, vcc
	v_lshlrev_b32_e32 v196, 2, v207
	s_addc_u32 s13, s81, 0
	s_lshl_b32 s20, s38, 2
	s_waitcnt lgkmcnt(0)
	v_add_f32_e32 v159, v156, v157
	s_and_b32 s20, s20, 4
	ds_bpermute_b32 v160, v196, v159
	s_or_b32 s20, s20, s45
	s_lshl_b32 s20, s20, 7
	s_add_u32 s20, s11, s20
	v_lshlrev_b32_e32 v138, 1, v136
	s_addc_u32 s21, s13, 0
	v_lshl_add_u64 v[156:157], s[20:21], 0, v[138:139]
	s_waitcnt lgkmcnt(0)
	v_add_f32_e32 v138, v159, v160
	v_fmamk_f32 v138, v138, 0x3c800000, v194
	v_mul_f32_e32 v159, 0x4b800000, v138
	v_cmp_gt_f32_e32 vcc, s61, v138
	s_lshl_b32 s11, s18, 8
	v_add_u32_e32 v158, s11, v181
	v_cndmask_b32_e32 v138, v138, v159, vcc
	v_rsq_f32_e32 v138, v138
	v_ashrrev_i32_e32 v159, 31, v158
	v_lshlrev_b64 v[158:159], 10, v[158:159]
	v_lshl_add_u64 v[208:209], v[156:157], 0, v[158:159]
	v_mul_f32_e32 v158, 0x45800000, v138
	v_cndmask_b32_e32 v138, v138, v158, vcc
	s_waitcnt vmcnt(0)
	v_pk_mul_f32 v[162:163], v[206:207], v[150:151] op_sel_hi:[0,1]
	v_pk_mul_f32 v[158:159], v[206:207], v[154:155] op_sel_hi:[0,1]
	v_pk_mul_f32 v[160:161], v[206:207], v[152:153] op_sel_hi:[0,1]
	v_pk_mul_f32 v[166:167], v[206:207], v[148:149] op_sel_hi:[0,1]
	v_pk_mul_f32 v[122:123], v[122:123], v[158:159]
	v_pk_mul_f32 v[120:121], v[120:121], v[160:161]
	v_pk_mul_f32 v[154:155], v[206:207], v[198:199] op_sel_hi:[0,1]
	v_pk_mul_f32 v[126:127], v[126:127], v[162:163]
	v_pk_mul_f32 v[124:125], v[124:125], v[166:167]
	v_pk_mul_f32 v[198:199], v[122:123], v[138:139] op_sel_hi:[1,0]
	v_pk_mul_f32 v[122:123], v[120:121], v[138:139] op_sel_hi:[1,0]
	v_pk_mul_f32 v[126:127], v[126:127], v[138:139] op_sel_hi:[1,0]
	v_pk_mul_f32 v[124:125], v[124:125], v[138:139] op_sel_hi:[1,0]
	v_pk_mul_f32 v[148:149], v[206:207], v[204:205] op_sel_hi:[0,1]
	v_cvt_pk_bf16_f32 v120, v124, v125
	v_cvt_pk_bf16_f32 v121, v126, v127
	v_cvt_pk_bf16_f32 v122, v122, v123
	v_cvt_pk_bf16_f32 v123, v198, v199
	global_store_dwordx4 v[208:209], v[120:123], off
	v_pk_mul_f32 v[150:151], v[206:207], v[202:203] op_sel_hi:[0,1]
	v_pk_mul_f32 v[116:117], v[116:117], v[154:155]
	v_pk_mul_f32 v[120:121], v[114:115], v[114:115]
	v_pk_mul_f32 v[122:123], v[112:113], v[112:113]
	v_pk_mul_f32 v[116:117], v[116:117], v[138:139] op_sel_hi:[1,0]
	v_pk_mov_b32 v[124:125], v[122:123], v[120:121] op_sel:[1,0]
	v_mov_b32_e32 v123, v121
	v_pk_add_f32 v[120:121], v[124:125], v[122:123]
	v_pk_mul_f32 v[122:123], v[106:107], v[106:107]
	v_pk_mul_f32 v[124:125], v[104:105], v[104:105]
	v_pk_add_f32 v[120:121], v[120:121], v[120:121] op_sel:[0,1] op_sel_hi:[1,0]
	v_pk_mov_b32 v[126:127], v[124:125], v[122:123] op_sel:[1,0]
	v_mov_b32_e32 v125, v123
	v_pk_add_f32 v[122:123], v[126:127], v[124:125]
	v_mul_f32_e32 v124, v92, v92
	v_mul_f32_e32 v125, v93, v93
	v_pk_add_f32 v[122:123], v[122:123], v[122:123] op_sel:[0,1] op_sel_hi:[1,0]
	v_mov_b32_e32 v121, v124
	v_mov_b32_e32 v123, v125
	v_pk_add_f32 v[120:121], v[120:121], v[122:123]
	v_mul_f32_e32 v122, v101, v101
	v_mul_f32_e32 v124, v103, v103
	v_mul_f32_e32 v126, v94, v94
	v_mul_f32_e32 v127, v95, v95
	v_pk_fma_f32 v[122:123], v[100:101], v[100:101], v[122:123] op_sel_hi:[1,1,0]
	v_pk_fma_f32 v[124:125], v[102:103], v[102:103], v[124:125] op_sel_hi:[1,1,0]
	v_mov_b32_e32 v123, v126
	v_mov_b32_e32 v125, v127
	v_pk_add_f32 v[122:123], v[122:123], v[124:125]
	v_pk_mul_f32 v[110:111], v[110:111], v[148:149]
	v_pk_add_f32 v[120:121], v[120:121], v[122:123]
	v_pk_mul_f32 v[108:109], v[108:109], v[150:151]
	v_add_f32_e32 v120, v120, v121
	ds_bpermute_b32 v121, v197, v120
	v_pk_mul_f32 v[152:153], v[206:207], v[200:201] op_sel_hi:[0,1]
	v_pk_mul_f32 v[118:119], v[118:119], v[152:153]
	v_pk_mul_f32 v[106:107], v[106:107], v[158:159]
	v_pk_mul_f32 v[118:119], v[118:119], v[138:139] op_sel_hi:[1,0]
	s_waitcnt lgkmcnt(0)
	v_add_f32_e32 v122, v120, v121
	ds_bpermute_b32 v123, v196, v122
	v_pk_mul_f32 v[120:121], v[110:111], v[138:139] op_sel_hi:[1,0]
	v_pk_mul_f32 v[110:111], v[108:109], v[138:139] op_sel_hi:[1,0]
	v_cvt_pk_bf16_f32 v108, v116, v117
	v_cvt_pk_bf16_f32 v109, v118, v119
	s_waitcnt lgkmcnt(0)
	v_add_f32_e32 v116, v122, v123
	v_fmamk_f32 v116, v116, 0x3c800000, v194
	v_mul_f32_e32 v117, 0x4b800000, v116
	v_cmp_gt_f32_e32 vcc, s61, v116
	v_cvt_pk_bf16_f32 v110, v110, v111
	v_cvt_pk_bf16_f32 v111, v120, v121
	global_store_dwordx4 v[208:209], v[108:111], off offset:64
	v_pk_mul_f32 v[104:105], v[104:105], v[160:161]
	v_cndmask_b32_e32 v116, v116, v117, vcc
	v_rsq_f32_e32 v116, v116
	v_add_u32_e32 v110, s11, v183
	v_ashrrev_i32_e32 v111, 31, v110
	v_lshlrev_b64 v[110:111], 10, v[110:111]
	v_mul_f32_e32 v108, 0x45800000, v116
	v_cndmask_b32_e32 v108, v116, v108, vcc
	v_pk_mul_f32 v[114:115], v[114:115], v[162:163]
	v_pk_mul_f32 v[112:113], v[112:113], v[166:167]
	v_pk_mul_f32 v[116:117], v[106:107], v[108:109] op_sel_hi:[1,0]
	v_pk_mul_f32 v[106:107], v[104:105], v[108:109] op_sel_hi:[1,0]
	v_lshl_add_u64 v[110:111], v[156:157], 0, v[110:111]
	v_pk_mul_f32 v[114:115], v[114:115], v[108:109] op_sel_hi:[1,0]
	v_pk_mul_f32 v[112:113], v[112:113], v[108:109] op_sel_hi:[1,0]
	v_mul_f32_e32 v109, v76, v76
	v_cvt_pk_bf16_f32 v104, v112, v113
	v_cvt_pk_bf16_f32 v105, v114, v115
	v_cvt_pk_bf16_f32 v106, v106, v107
	v_cvt_pk_bf16_f32 v107, v116, v117
	global_store_dwordx4 v[110:111], v[104:107], off
	v_pk_mul_f32 v[100:101], v[100:101], v[154:155]
	v_pk_mul_f32 v[94:95], v[94:95], v[148:149]
	v_pk_mul_f32 v[104:105], v[98:99], v[98:99]
	v_pk_mul_f32 v[106:107], v[96:97], v[96:97]
	v_pk_mul_f32 v[100:101], v[100:101], v[108:109] op_sel_hi:[1,0]
	v_pk_mov_b32 v[112:113], v[106:107], v[104:105] op_sel:[1,0]
	v_mov_b32_e32 v107, v105
	v_pk_add_f32 v[104:105], v[112:113], v[106:107]
	v_pk_mul_f32 v[106:107], v[90:91], v[90:91]
	v_pk_mul_f32 v[112:113], v[88:89], v[88:89]
	v_pk_add_f32 v[104:105], v[104:105], v[104:105] op_sel:[0,1] op_sel_hi:[1,0]
	v_pk_mov_b32 v[114:115], v[112:113], v[106:107] op_sel:[1,0]
	v_mov_b32_e32 v113, v107
	v_pk_add_f32 v[106:107], v[114:115], v[112:113]
	v_mul_f32_e32 v112, v77, v77
	v_pk_add_f32 v[106:107], v[106:107], v[106:107] op_sel:[0,1] op_sel_hi:[1,0]
	v_mov_b32_e32 v105, v109
	v_mov_b32_e32 v107, v112
	v_pk_add_f32 v[104:105], v[104:105], v[106:107]
	v_mul_f32_e32 v106, v85, v85
	v_mul_f32_e32 v113, v78, v78
	v_pk_fma_f32 v[106:107], v[84:85], v[84:85], v[106:107] op_sel_hi:[1,1,0]
	v_mul_f32_e32 v112, v87, v87
	v_mul_f32_e32 v114, v79, v79
	v_mov_b32_e32 v107, v113
	v_pk_fma_f32 v[112:113], v[86:87], v[86:87], v[112:113] op_sel_hi:[1,1,0]
	v_pk_mul_f32 v[92:93], v[92:93], v[150:151]
	v_mov_b32_e32 v113, v114
	v_pk_add_f32 v[106:107], v[106:107], v[112:113]
	v_pk_mul_f32 v[102:103], v[102:103], v[152:153]
	v_pk_add_f32 v[104:105], v[104:105], v[106:107]
	v_pk_mul_f32 v[102:103], v[102:103], v[108:109] op_sel_hi:[1,0]
	v_add_f32_e32 v104, v104, v105
	ds_bpermute_b32 v105, v197, v104
	v_pk_mul_f32 v[90:91], v[90:91], v[158:159]
	v_pk_mul_f32 v[88:89], v[88:89], v[160:161]
	v_pk_mul_f32 v[98:99], v[98:99], v[162:163]
	v_pk_mul_f32 v[96:97], v[96:97], v[166:167]
	s_waitcnt lgkmcnt(0)
	v_add_f32_e32 v106, v104, v105
	ds_bpermute_b32 v107, v196, v106
	v_pk_mul_f32 v[104:105], v[94:95], v[108:109] op_sel_hi:[1,0]
	v_pk_mul_f32 v[94:95], v[92:93], v[108:109] op_sel_hi:[1,0]
	v_cvt_pk_bf16_f32 v92, v100, v101
	v_cvt_pk_bf16_f32 v93, v102, v103
	s_waitcnt lgkmcnt(0)
	v_add_f32_e32 v100, v106, v107
	v_fmamk_f32 v100, v100, 0x3c800000, v194
	v_mul_f32_e32 v101, 0x4b800000, v100
	v_cmp_gt_f32_e32 vcc, s61, v100
	v_cvt_pk_bf16_f32 v94, v94, v95
	v_cvt_pk_bf16_f32 v95, v104, v105
	global_store_dwordx4 v[110:111], v[92:95], off offset:64
	v_pk_mul_f32 v[84:85], v[84:85], v[154:155]
	v_cndmask_b32_e32 v100, v100, v101, vcc
	v_rsq_f32_e32 v100, v100
	v_add_u32_e32 v94, s11, v184
	v_ashrrev_i32_e32 v95, 31, v94
	v_lshlrev_b64 v[94:95], 10, v[94:95]
	v_mul_f32_e32 v92, 0x45800000, v100
	v_cndmask_b32_e32 v92, v100, v92, vcc
	v_pk_mul_f32 v[100:101], v[90:91], v[92:93] op_sel_hi:[1,0]
	v_pk_mul_f32 v[90:91], v[88:89], v[92:93] op_sel_hi:[1,0]
	v_lshl_add_u64 v[94:95], v[156:157], 0, v[94:95]
	v_pk_mul_f32 v[98:99], v[98:99], v[92:93] op_sel_hi:[1,0]
	v_pk_mul_f32 v[96:97], v[96:97], v[92:93] op_sel_hi:[1,0]
	v_mul_f32_e32 v93, v64, v64
	v_cvt_pk_bf16_f32 v88, v96, v97
	v_cvt_pk_bf16_f32 v89, v98, v99
	v_cvt_pk_bf16_f32 v90, v90, v91
	v_cvt_pk_bf16_f32 v91, v100, v101
	global_store_dwordx4 v[94:95], v[88:91], off
	v_pk_mul_f32 v[84:85], v[84:85], v[92:93] op_sel_hi:[1,0]
	v_pk_mul_f32 v[78:79], v[78:79], v[148:149]
	v_pk_mul_f32 v[88:89], v[82:83], v[82:83]
	v_pk_mul_f32 v[90:91], v[80:81], v[80:81]
	v_pk_mul_f32 v[76:77], v[76:77], v[150:151]
	v_pk_mov_b32 v[96:97], v[90:91], v[88:89] op_sel:[1,0]
	v_mov_b32_e32 v91, v89
	v_pk_add_f32 v[88:89], v[96:97], v[90:91]
	v_pk_mul_f32 v[90:91], v[74:75], v[74:75]
	v_pk_mul_f32 v[96:97], v[72:73], v[72:73]
	v_pk_add_f32 v[88:89], v[88:89], v[88:89] op_sel:[0,1] op_sel_hi:[1,0]
	v_pk_mov_b32 v[98:99], v[96:97], v[90:91] op_sel:[1,0]
	v_mov_b32_e32 v97, v91
	v_pk_add_f32 v[90:91], v[98:99], v[96:97]
	v_mul_f32_e32 v96, v65, v65
	v_pk_add_f32 v[90:91], v[90:91], v[90:91] op_sel:[0,1] op_sel_hi:[1,0]
	v_mov_b32_e32 v89, v93
	v_mov_b32_e32 v91, v96
	v_pk_add_f32 v[88:89], v[88:89], v[90:91]
	v_mul_f32_e32 v90, v69, v69
	v_mul_f32_e32 v97, v66, v66
	v_pk_fma_f32 v[90:91], v[68:69], v[68:69], v[90:91] op_sel_hi:[1,1,0]
	v_mul_f32_e32 v96, v71, v71
	v_mul_f32_e32 v98, v67, v67
	v_mov_b32_e32 v91, v97
	v_pk_fma_f32 v[96:97], v[70:71], v[70:71], v[96:97] op_sel_hi:[1,1,0]
	v_pk_mul_f32 v[86:87], v[86:87], v[152:153]
	v_mov_b32_e32 v97, v98
	v_pk_add_f32 v[90:91], v[90:91], v[96:97]
	v_pk_mul_f32 v[86:87], v[86:87], v[92:93] op_sel_hi:[1,0]
	v_pk_add_f32 v[88:89], v[88:89], v[90:91]
	v_pk_mul_f32 v[74:75], v[74:75], v[158:159]
	v_add_f32_e32 v88, v88, v89
	ds_bpermute_b32 v89, v197, v88
	v_pk_mul_f32 v[72:73], v[72:73], v[160:161]
	v_pk_mul_f32 v[82:83], v[82:83], v[162:163]
	v_pk_mul_f32 v[80:81], v[80:81], v[166:167]
	v_pk_mul_f32 v[68:69], v[68:69], v[154:155]
	s_waitcnt lgkmcnt(0)
	v_add_f32_e32 v90, v88, v89
	ds_bpermute_b32 v91, v196, v90
	v_pk_mul_f32 v[88:89], v[78:79], v[92:93] op_sel_hi:[1,0]
	v_pk_mul_f32 v[78:79], v[76:77], v[92:93] op_sel_hi:[1,0]
	v_cvt_pk_bf16_f32 v76, v84, v85
	v_cvt_pk_bf16_f32 v77, v86, v87
	s_waitcnt lgkmcnt(0)
	v_add_f32_e32 v84, v90, v91
	v_fmamk_f32 v84, v84, 0x3c800000, v194
	v_mul_f32_e32 v85, 0x4b800000, v84
	v_cmp_gt_f32_e32 vcc, s61, v84
	v_cvt_pk_bf16_f32 v78, v78, v79
	v_cvt_pk_bf16_f32 v79, v88, v89
	global_store_dwordx4 v[94:95], v[76:79], off offset:64
	v_pk_mul_f32 v[66:67], v[66:67], v[148:149]
	v_cndmask_b32_e32 v84, v84, v85, vcc
	v_rsq_f32_e32 v84, v84
	v_add_u32_e32 v78, s11, v185
	v_ashrrev_i32_e32 v79, 31, v78
	v_lshlrev_b64 v[78:79], 10, v[78:79]
	v_mul_f32_e32 v76, 0x45800000, v84
	v_cndmask_b32_e32 v76, v84, v76, vcc
	v_pk_mul_f32 v[84:85], v[74:75], v[76:77] op_sel_hi:[1,0]
	v_pk_mul_f32 v[74:75], v[72:73], v[76:77] op_sel_hi:[1,0]
	v_lshl_add_u64 v[78:79], v[156:157], 0, v[78:79]
	v_pk_mul_f32 v[82:83], v[82:83], v[76:77] op_sel_hi:[1,0]
	v_pk_mul_f32 v[80:81], v[80:81], v[76:77] op_sel_hi:[1,0]
	v_mul_f32_e32 v77, v44, v44
	v_cvt_pk_bf16_f32 v72, v80, v81
	v_cvt_pk_bf16_f32 v73, v82, v83
	v_cvt_pk_bf16_f32 v74, v74, v75
	v_cvt_pk_bf16_f32 v75, v84, v85
	global_store_dwordx4 v[78:79], v[72:75], off
	v_pk_mul_f32 v[68:69], v[68:69], v[76:77] op_sel_hi:[1,0]
	v_pk_mul_f32 v[64:65], v[64:65], v[150:151]
	v_pk_mul_f32 v[72:73], v[62:63], v[62:63]
	v_pk_mul_f32 v[74:75], v[60:61], v[60:61]
	v_pk_mul_f32 v[70:71], v[70:71], v[152:153]
	v_pk_mov_b32 v[80:81], v[74:75], v[72:73] op_sel:[1,0]
	v_mov_b32_e32 v75, v73
	v_pk_add_f32 v[72:73], v[80:81], v[74:75]
	v_pk_mul_f32 v[74:75], v[58:59], v[58:59]
	v_pk_mul_f32 v[80:81], v[56:57], v[56:57]
	v_pk_add_f32 v[72:73], v[72:73], v[72:73] op_sel:[0,1] op_sel_hi:[1,0]
	v_pk_mov_b32 v[82:83], v[80:81], v[74:75] op_sel:[1,0]
	v_mov_b32_e32 v81, v75
	v_pk_add_f32 v[74:75], v[82:83], v[80:81]
	v_mul_f32_e32 v80, v45, v45
	v_pk_add_f32 v[74:75], v[74:75], v[74:75] op_sel:[0,1] op_sel_hi:[1,0]
	v_mov_b32_e32 v73, v77
	v_mov_b32_e32 v75, v80
	v_pk_add_f32 v[72:73], v[72:73], v[74:75]
	v_mul_f32_e32 v74, v53, v53
	v_mul_f32_e32 v81, v46, v46
	v_pk_fma_f32 v[74:75], v[52:53], v[52:53], v[74:75] op_sel_hi:[1,1,0]
	v_mul_f32_e32 v80, v55, v55
	v_mul_f32_e32 v82, v47, v47
	v_mov_b32_e32 v75, v81
	v_pk_fma_f32 v[80:81], v[54:55], v[54:55], v[80:81] op_sel_hi:[1,1,0]
	v_pk_mul_f32 v[70:71], v[70:71], v[76:77] op_sel_hi:[1,0]
	v_mov_b32_e32 v81, v82
	v_pk_add_f32 v[74:75], v[74:75], v[80:81]
	v_pk_mul_f32 v[58:59], v[58:59], v[158:159]
	v_pk_add_f32 v[72:73], v[72:73], v[74:75]
	v_pk_mul_f32 v[56:57], v[56:57], v[160:161]
	v_add_f32_e32 v72, v72, v73
	ds_bpermute_b32 v73, v197, v72
	v_pk_mul_f32 v[62:63], v[62:63], v[162:163]
	v_pk_mul_f32 v[60:61], v[60:61], v[166:167]
	v_pk_mul_f32 v[52:53], v[52:53], v[154:155]
	v_pk_mul_f32 v[46:47], v[46:47], v[148:149]
	s_waitcnt lgkmcnt(0)
	v_add_f32_e32 v74, v72, v73
	ds_bpermute_b32 v75, v196, v74
	v_pk_mul_f32 v[72:73], v[66:67], v[76:77] op_sel_hi:[1,0]
	v_pk_mul_f32 v[66:67], v[64:65], v[76:77] op_sel_hi:[1,0]
	v_cvt_pk_bf16_f32 v64, v68, v69
	v_cvt_pk_bf16_f32 v65, v70, v71
	s_waitcnt lgkmcnt(0)
	v_add_f32_e32 v68, v74, v75
	v_fmamk_f32 v68, v68, 0x3c800000, v194
	v_mul_f32_e32 v69, 0x4b800000, v68
	v_cmp_gt_f32_e32 vcc, s61, v68
	v_cvt_pk_bf16_f32 v66, v66, v67
	v_cvt_pk_bf16_f32 v67, v72, v73
	global_store_dwordx4 v[78:79], v[64:67], off offset:64
	v_pk_mul_f32 v[44:45], v[44:45], v[150:151]
	v_cndmask_b32_e32 v68, v68, v69, vcc
	v_rsq_f32_e32 v68, v68
	v_add_u32_e32 v66, s11, v186
	v_ashrrev_i32_e32 v67, 31, v66
	v_lshlrev_b64 v[66:67], 10, v[66:67]
	v_mul_f32_e32 v64, 0x45800000, v68
	v_cndmask_b32_e32 v64, v68, v64, vcc
	v_pk_mul_f32 v[68:69], v[58:59], v[64:65] op_sel_hi:[1,0]
	v_pk_mul_f32 v[58:59], v[56:57], v[64:65] op_sel_hi:[1,0]
	v_lshl_add_u64 v[66:67], v[156:157], 0, v[66:67]
	v_pk_mul_f32 v[62:63], v[62:63], v[64:65] op_sel_hi:[1,0]
	v_pk_mul_f32 v[60:61], v[60:61], v[64:65] op_sel_hi:[1,0]
	v_pk_mul_f32 v[52:53], v[52:53], v[64:65] op_sel_hi:[1,0]
	v_cvt_pk_bf16_f32 v56, v60, v61
	v_cvt_pk_bf16_f32 v57, v62, v63
	v_cvt_pk_bf16_f32 v58, v58, v59
	v_cvt_pk_bf16_f32 v59, v68, v69
	global_store_dwordx4 v[66:67], v[56:59], off
	v_pk_mul_f32 v[54:55], v[54:55], v[152:153]
	s_nop 0
	v_pk_mul_f32 v[56:57], v[50:51], v[50:51]
	v_pk_mul_f32 v[58:59], v[48:49], v[48:49]
	v_pk_mul_f32 v[54:55], v[54:55], v[64:65] op_sel_hi:[1,0]
	v_pk_mov_b32 v[60:61], v[58:59], v[56:57] op_sel:[1,0]
	v_mov_b32_e32 v59, v57
	v_pk_add_f32 v[56:57], v[60:61], v[58:59]
	v_pk_mul_f32 v[58:59], v[42:43], v[42:43]
	v_pk_mul_f32 v[60:61], v[40:41], v[40:41]
	v_pk_add_f32 v[56:57], v[56:57], v[56:57] op_sel:[0,1] op_sel_hi:[1,0]
	v_pk_mov_b32 v[62:63], v[60:61], v[58:59] op_sel:[1,0]
	v_mov_b32_e32 v61, v59
	v_pk_add_f32 v[58:59], v[62:63], v[60:61]
	v_mul_f32_e32 v60, v28, v28
	v_mul_f32_e32 v61, v29, v29
	v_pk_add_f32 v[58:59], v[58:59], v[58:59] op_sel:[0,1] op_sel_hi:[1,0]
	v_mov_b32_e32 v57, v60
	v_mov_b32_e32 v59, v61
	v_pk_add_f32 v[56:57], v[56:57], v[58:59]
	v_mul_f32_e32 v58, v37, v37
	v_mul_f32_e32 v60, v39, v39
	v_mul_f32_e32 v62, v30, v30
	v_mul_f32_e32 v63, v31, v31
	v_pk_fma_f32 v[58:59], v[36:37], v[36:37], v[58:59] op_sel_hi:[1,1,0]
	v_pk_fma_f32 v[60:61], v[38:39], v[38:39], v[60:61] op_sel_hi:[1,1,0]
	v_mov_b32_e32 v59, v62
	v_mov_b32_e32 v61, v63
	v_pk_add_f32 v[58:59], v[58:59], v[60:61]
	v_pk_mul_f32 v[42:43], v[42:43], v[158:159]
	v_pk_add_f32 v[56:57], v[56:57], v[58:59]
	v_pk_mul_f32 v[40:41], v[40:41], v[160:161]
	v_add_f32_e32 v56, v56, v57
	ds_bpermute_b32 v57, v197, v56
	v_pk_mul_f32 v[50:51], v[50:51], v[162:163]
	v_pk_mul_f32 v[48:49], v[48:49], v[166:167]
	v_pk_mul_f32 v[36:37], v[36:37], v[154:155]
	v_pk_mul_f32 v[30:31], v[30:31], v[148:149]
	s_waitcnt lgkmcnt(0)
	v_add_f32_e32 v58, v56, v57
	ds_bpermute_b32 v59, v196, v58
	v_pk_mul_f32 v[56:57], v[46:47], v[64:65] op_sel_hi:[1,0]
	v_pk_mul_f32 v[46:47], v[44:45], v[64:65] op_sel_hi:[1,0]
	v_cvt_pk_bf16_f32 v44, v52, v53
	v_cvt_pk_bf16_f32 v45, v54, v55
	s_waitcnt lgkmcnt(0)
	v_add_f32_e32 v52, v58, v59
	v_fmamk_f32 v52, v52, 0x3c800000, v194
	v_mul_f32_e32 v53, 0x4b800000, v52
	v_cmp_gt_f32_e32 vcc, s61, v52
	v_cvt_pk_bf16_f32 v46, v46, v47
	v_cvt_pk_bf16_f32 v47, v56, v57
	global_store_dwordx4 v[66:67], v[44:47], off offset:64
	v_pk_mul_f32 v[28:29], v[28:29], v[150:151]
	v_cndmask_b32_e32 v52, v52, v53, vcc
	v_rsq_f32_e32 v52, v52
	v_add_u32_e32 v46, s11, v187
	v_ashrrev_i32_e32 v47, 31, v46
	v_lshlrev_b64 v[46:47], 10, v[46:47]
	v_mul_f32_e32 v44, 0x45800000, v52
	v_cndmask_b32_e32 v44, v52, v44, vcc
	v_pk_mul_f32 v[52:53], v[42:43], v[44:45] op_sel_hi:[1,0]
	v_pk_mul_f32 v[42:43], v[40:41], v[44:45] op_sel_hi:[1,0]
	v_lshl_add_u64 v[46:47], v[156:157], 0, v[46:47]
	v_pk_mul_f32 v[50:51], v[50:51], v[44:45] op_sel_hi:[1,0]
	v_pk_mul_f32 v[48:49], v[48:49], v[44:45] op_sel_hi:[1,0]
	v_mul_f32_e32 v45, v12, v12
	v_cvt_pk_bf16_f32 v40, v48, v49
	v_cvt_pk_bf16_f32 v41, v50, v51
	v_cvt_pk_bf16_f32 v42, v42, v43
	v_cvt_pk_bf16_f32 v43, v52, v53
	global_store_dwordx4 v[46:47], v[40:43], off
	v_pk_mul_f32 v[36:37], v[36:37], v[44:45] op_sel_hi:[1,0]
	v_pk_mul_f32 v[38:39], v[38:39], v[152:153]
	v_pk_mul_f32 v[40:41], v[34:35], v[34:35]
	v_pk_mul_f32 v[42:43], v[32:33], v[32:33]
	v_pk_mul_f32 v[38:39], v[38:39], v[44:45] op_sel_hi:[1,0]
	v_pk_mov_b32 v[48:49], v[42:43], v[40:41] op_sel:[1,0]
	v_mov_b32_e32 v43, v41
	v_pk_add_f32 v[40:41], v[48:49], v[42:43]
	v_pk_mul_f32 v[42:43], v[26:27], v[26:27]
	v_pk_mul_f32 v[48:49], v[24:25], v[24:25]
	v_pk_add_f32 v[40:41], v[40:41], v[40:41] op_sel:[0,1] op_sel_hi:[1,0]
	v_pk_mov_b32 v[50:51], v[48:49], v[42:43] op_sel:[1,0]
	v_mov_b32_e32 v49, v43
	v_pk_add_f32 v[42:43], v[50:51], v[48:49]
	v_mul_f32_e32 v48, v13, v13
	v_pk_add_f32 v[42:43], v[42:43], v[42:43] op_sel:[0,1] op_sel_hi:[1,0]
	v_mov_b32_e32 v41, v45
	v_mov_b32_e32 v43, v48
	v_pk_add_f32 v[40:41], v[40:41], v[42:43]
	v_mul_f32_e32 v42, v21, v21
	v_mul_f32_e32 v49, v14, v14
	v_pk_fma_f32 v[42:43], v[20:21], v[20:21], v[42:43] op_sel_hi:[1,1,0]
	v_mul_f32_e32 v48, v23, v23
	v_mul_f32_e32 v50, v15, v15
	v_mov_b32_e32 v43, v49
	v_pk_fma_f32 v[48:49], v[22:23], v[22:23], v[48:49] op_sel_hi:[1,1,0]
	v_pk_mul_f32 v[26:27], v[26:27], v[158:159]
	v_mov_b32_e32 v49, v50
	v_pk_add_f32 v[42:43], v[42:43], v[48:49]
	v_pk_mul_f32 v[24:25], v[24:25], v[160:161]
	v_pk_add_f32 v[40:41], v[40:41], v[42:43]
	v_pk_mul_f32 v[34:35], v[34:35], v[162:163]
	v_add_f32_e32 v40, v40, v41
	ds_bpermute_b32 v41, v197, v40
	v_pk_mul_f32 v[32:33], v[32:33], v[166:167]
	v_pk_mul_f32 v[20:21], v[20:21], v[154:155]
	v_pk_mul_f32 v[14:15], v[14:15], v[148:149]
	v_pk_mul_f32 v[12:13], v[12:13], v[150:151]
	s_waitcnt lgkmcnt(0)
	v_add_f32_e32 v42, v40, v41
	ds_bpermute_b32 v43, v196, v42
	v_pk_mul_f32 v[40:41], v[30:31], v[44:45] op_sel_hi:[1,0]
	v_pk_mul_f32 v[30:31], v[28:29], v[44:45] op_sel_hi:[1,0]
	v_cvt_pk_bf16_f32 v28, v36, v37
	v_cvt_pk_bf16_f32 v29, v38, v39
	s_waitcnt lgkmcnt(0)
	v_add_f32_e32 v36, v42, v43
	v_fmamk_f32 v36, v36, 0x3c800000, v194
	v_mul_f32_e32 v37, 0x4b800000, v36
	v_cmp_gt_f32_e32 vcc, s61, v36
	v_cvt_pk_bf16_f32 v30, v30, v31
	v_cvt_pk_bf16_f32 v31, v40, v41
	global_store_dwordx4 v[46:47], v[28:31], off offset:64
	v_pk_mul_f32 v[22:23], v[22:23], v[152:153]
	v_cndmask_b32_e32 v36, v36, v37, vcc
	v_rsq_f32_e32 v36, v36
	v_add_u32_e32 v30, s11, v188
	v_ashrrev_i32_e32 v31, 31, v30
	v_lshlrev_b64 v[30:31], 10, v[30:31]
	v_mul_f32_e32 v28, 0x45800000, v36
	v_cndmask_b32_e32 v28, v36, v28, vcc
	v_pk_mul_f32 v[36:37], v[26:27], v[28:29] op_sel_hi:[1,0]
	v_pk_mul_f32 v[26:27], v[24:25], v[28:29] op_sel_hi:[1,0]
	v_lshl_add_u64 v[30:31], v[156:157], 0, v[30:31]
	v_pk_mul_f32 v[34:35], v[34:35], v[28:29] op_sel_hi:[1,0]
	v_pk_mul_f32 v[32:33], v[32:33], v[28:29] op_sel_hi:[1,0]
	v_mul_f32_e32 v29, v0, v0
	v_cvt_pk_bf16_f32 v24, v32, v33
	v_cvt_pk_bf16_f32 v25, v34, v35
	v_cvt_pk_bf16_f32 v26, v26, v27
	v_cvt_pk_bf16_f32 v27, v36, v37
	global_store_dwordx4 v[30:31], v[24:27], off
	v_pk_mul_f32 v[20:21], v[20:21], v[28:29] op_sel_hi:[1,0]
	v_pk_mul_f32 v[22:23], v[22:23], v[28:29] op_sel_hi:[1,0]
	v_pk_mul_f32 v[24:25], v[18:19], v[18:19]
	v_pk_mul_f32 v[26:27], v[16:17], v[16:17]
	v_pk_mul_f32 v[18:19], v[18:19], v[162:163]
	v_pk_mov_b32 v[32:33], v[26:27], v[24:25] op_sel:[1,0]
	v_mov_b32_e32 v27, v25
	v_pk_add_f32 v[24:25], v[32:33], v[26:27]
	v_pk_mul_f32 v[26:27], v[10:11], v[10:11]
	v_pk_mul_f32 v[32:33], v[8:9], v[8:9]
	v_pk_add_f32 v[24:25], v[24:25], v[24:25] op_sel:[0,1] op_sel_hi:[1,0]
	v_pk_mov_b32 v[34:35], v[32:33], v[26:27] op_sel:[1,0]
	v_mov_b32_e32 v33, v27
	v_pk_add_f32 v[26:27], v[34:35], v[32:33]
	v_mul_f32_e32 v32, v1, v1
	v_pk_add_f32 v[26:27], v[26:27], v[26:27] op_sel:[0,1] op_sel_hi:[1,0]
	v_mov_b32_e32 v25, v29
	v_mov_b32_e32 v27, v32
	v_pk_add_f32 v[24:25], v[24:25], v[26:27]
	v_mul_f32_e32 v26, v5, v5
	v_mul_f32_e32 v33, v2, v2
	v_pk_fma_f32 v[26:27], v[4:5], v[4:5], v[26:27] op_sel_hi:[1,1,0]
	v_mul_f32_e32 v32, v7, v7
	v_mul_f32_e32 v34, v3, v3
	v_mov_b32_e32 v27, v33
	v_pk_fma_f32 v[32:33], v[6:7], v[6:7], v[32:33] op_sel_hi:[1,1,0]
	v_pk_mul_f32 v[16:17], v[16:17], v[166:167]
	v_mov_b32_e32 v33, v34
	v_pk_add_f32 v[26:27], v[26:27], v[32:33]
	v_pk_mul_f32 v[10:11], v[10:11], v[158:159]
	v_pk_add_f32 v[24:25], v[24:25], v[26:27]
	v_pk_mul_f32 v[8:9], v[8:9], v[160:161]
	v_add_f32_e32 v24, v24, v25
	ds_bpermute_b32 v25, v197, v24
	v_pk_mul_f32 v[2:3], v[2:3], v[148:149]
	v_pk_mul_f32 v[0:1], v[0:1], v[150:151]
	v_pk_mul_f32 v[6:7], v[6:7], v[152:153]
	v_pk_mul_f32 v[4:5], v[4:5], v[154:155]
	s_waitcnt lgkmcnt(0)
	v_add_f32_e32 v26, v24, v25
	ds_bpermute_b32 v27, v196, v26
	v_pk_mul_f32 v[24:25], v[14:15], v[28:29] op_sel_hi:[1,0]
	v_pk_mul_f32 v[14:15], v[12:13], v[28:29] op_sel_hi:[1,0]
	v_cvt_pk_bf16_f32 v12, v20, v21
	v_cvt_pk_bf16_f32 v13, v22, v23
	s_waitcnt lgkmcnt(0)
	v_add_f32_e32 v20, v26, v27
	v_fmamk_f32 v20, v20, 0x3c800000, v194
	v_mul_f32_e32 v21, 0x4b800000, v20
	v_cmp_gt_f32_e32 vcc, s61, v20
	v_cvt_pk_bf16_f32 v14, v14, v15
	v_cvt_pk_bf16_f32 v15, v24, v25
	global_store_dwordx4 v[30:31], v[12:15], off offset:64
	s_nop 0
	v_cndmask_b32_e32 v20, v20, v21, vcc
	v_rsq_f32_e32 v20, v20
	v_add_u32_e32 v14, s11, v189
	v_ashrrev_i32_e32 v15, 31, v14
	v_lshlrev_b64 v[14:15], 10, v[14:15]
	v_mul_f32_e32 v12, 0x45800000, v20
	v_cndmask_b32_e32 v12, v20, v12, vcc
	v_lshl_add_u64 v[14:15], v[156:157], 0, v[14:15]
	v_pk_mul_f32 v[18:19], v[18:19], v[12:13] op_sel_hi:[1,0]
	v_pk_mul_f32 v[16:17], v[16:17], v[12:13] op_sel_hi:[1,0]
	v_pk_mul_f32 v[20:21], v[10:11], v[12:13] op_sel_hi:[1,0]
	v_pk_mul_f32 v[10:11], v[8:9], v[12:13] op_sel_hi:[1,0]
	v_cvt_pk_bf16_f32 v8, v16, v17
	v_cvt_pk_bf16_f32 v9, v18, v19
	s_andn2_b64 vcc, exec, s[2:3]
	v_cvt_pk_bf16_f32 v10, v10, v11
	v_cvt_pk_bf16_f32 v11, v20, v21
	global_store_dwordx4 v[14:15], v[8:11], off
	s_mov_b64 s[2:3], -1
	v_pk_mul_f32 v[6:7], v[6:7], v[12:13] op_sel_hi:[1,0]
	v_pk_mul_f32 v[8:9], v[2:3], v[12:13] op_sel_hi:[1,0]
	v_pk_mul_f32 v[2:3], v[0:1], v[12:13] op_sel_hi:[1,0]
	v_pk_mul_f32 v[4:5], v[4:5], v[12:13] op_sel_hi:[1,0]
	s_nop 0
	v_cvt_pk_bf16_f32 v0, v4, v5
	v_cvt_pk_bf16_f32 v1, v6, v7
	v_cvt_pk_bf16_f32 v2, v2, v3
	v_cvt_pk_bf16_f32 v3, v8, v9
	global_store_dwordx4 v[14:15], v[0:3], off offset:64
	s_cbranch_vccnz .LBB0_260
	s_andn2_b64 vcc, exec, s[4:5]
	s_cbranch_vccnz .LBB0_259
	s_barrier
	s_branch .LBB0_259

.LBB0_279:
	s_and_b32 s21, s22, 3
	s_and_b64 s[22:23], s[2:3], exec
	s_cselect_b32 s22, s21, s39
	s_ashr_i32 s23, s22, 31
	s_lshl_b64 s[22:23], s[22:23], 19
	s_add_u32 s22, s31, s22
	s_addc_u32 s23, s34, s23
	s_and_b64 s[68:69], s[2:3], exec
	s_cselect_b32 s39, s23, s25
	s_cselect_b32 s67, s22, s24
	s_add_u32 s24, s24, 0x40080
	s_addc_u32 s25, s25, 0
	s_add_u32 s68, s26, 0x100
	s_addc_u32 s69, s27, 0
	s_mov_b32 s70, -2
	ds_read_b128 v[158:161], v154
	ds_read_b128 v[182:185], v154 offset:1024
	ds_read_b128 v[186:189], v154 offset:2048
	ds_read_b128 v[190:193], v154 offset:3072
	ds_read_b128 v[194:197], v155
	ds_read_b128 v[198:201], v155 offset:1024
	ds_read_b128 v[202:205], v155 offset:2048
	ds_read_b128 v[206:209], v155 offset:3072
	s_add_u32 s26, s24, 0xfffc0080
	s_addc_u32 s27, s25, -1
	s_cmp_eq_u32 s70, 12
	s_cselect_b32 s27, s39, s27
	s_cselect_b32 s26, s67, s26
	s_cselect_b32 s73, s19, s69
	s_cselect_b32 s72, s18, s68
	s_mov_b32 m0, s61
	v_lshl_add_u64 v[162:163], s[24:25], 0, v[144:145]
	ds_read_b128 v[210:213], v156
	ds_read_b128 v[214:217], v156 offset:1024
	ds_read_b128 v[218:221], v156 offset:2048
	ds_read_b128 v[222:225], v156 offset:3072
	ds_read_b128 v[226:229], v156 offset:4096
	ds_read_b128 v[230:233], v156 offset:5120
	ds_read_b128 v[234:237], v156 offset:6144
	ds_read_b128 v[238:241], v156 offset:7168
	global_load_lds_dwordx4 v[162:163], off
	v_lshl_add_u64 v[162:163], s[24:25], 0, v[146:147]
	s_mov_b32 m0, s62
	s_nop 0
	global_load_lds_dwordx4 v[162:163], off
	s_waitcnt vmcnt(8)
	s_waitcnt lgkmcnt(0)
	s_setprio 1
	s_barrier
	v_mfma_f32_16x16x32_bf16 v[124:127], v[158:161], v[210:213], 0
	v_mfma_f32_16x16x32_bf16 v[120:123], v[186:189], v[210:213], 0
	v_mfma_f32_16x16x32_bf16 v[112:115], v[158:161], v[218:221], 0
	v_mfma_f32_16x16x32_bf16 v[104:107], v[186:189], v[218:221], 0
	v_mfma_f32_16x16x32_bf16 v[96:99], v[158:161], v[226:229], 0
	v_mfma_f32_16x16x32_bf16 v[88:91], v[186:189], v[226:229], 0
	v_mfma_f32_16x16x32_bf16 v[80:83], v[158:161], v[234:237], 0
	v_mfma_f32_16x16x32_bf16 v[72:75], v[186:189], v[234:237], 0
	v_mfma_f32_16x16x32_bf16 v[124:127], v[182:185], v[214:217], v[124:127]
	v_mfma_f32_16x16x32_bf16 v[120:123], v[190:193], v[214:217], v[120:123]
	v_mfma_f32_16x16x32_bf16 v[112:115], v[182:185], v[222:225], v[112:115]
	v_mfma_f32_16x16x32_bf16 v[104:107], v[190:193], v[222:225], v[104:107]
	v_mfma_f32_16x16x32_bf16 v[96:99], v[182:185], v[230:233], v[96:99]
	v_mfma_f32_16x16x32_bf16 v[88:91], v[190:193], v[230:233], v[88:91]
	v_mfma_f32_16x16x32_bf16 v[80:83], v[182:185], v[238:241], v[80:83]
	v_mfma_f32_16x16x32_bf16 v[72:75], v[190:193], v[238:241], v[72:75]
	v_mfma_f32_16x16x32_bf16 v[116:119], v[194:197], v[210:213], 0
	v_mfma_f32_16x16x32_bf16 v[108:111], v[202:205], v[210:213], 0
	v_mfma_f32_16x16x32_bf16 v[100:103], v[194:197], v[218:221], 0
	v_mfma_f32_16x16x32_bf16 v[92:95], v[202:205], v[218:221], 0
	v_mfma_f32_16x16x32_bf16 v[84:87], v[194:197], v[226:229], 0
	v_mfma_f32_16x16x32_bf16 v[76:79], v[202:205], v[226:229], 0
	v_mfma_f32_16x16x32_bf16 v[68:71], v[194:197], v[234:237], 0
	v_mfma_f32_16x16x32_bf16 v[64:67], v[202:205], v[234:237], 0
	v_mfma_f32_16x16x32_bf16 v[116:119], v[198:201], v[214:217], v[116:119]
	v_mfma_f32_16x16x32_bf16 v[108:111], v[206:209], v[214:217], v[108:111]
	v_mfma_f32_16x16x32_bf16 v[100:103], v[198:201], v[222:225], v[100:103]
	v_mfma_f32_16x16x32_bf16 v[92:95], v[206:209], v[222:225], v[92:95]
	v_mfma_f32_16x16x32_bf16 v[84:87], v[198:201], v[230:233], v[84:87]
	v_mfma_f32_16x16x32_bf16 v[76:79], v[206:209], v[230:233], v[76:79]
	v_mfma_f32_16x16x32_bf16 v[68:71], v[198:201], v[238:241], v[68:71]
	v_mfma_f32_16x16x32_bf16 v[64:67], v[206:209], v[238:241], v[64:67]
	s_barrier
	s_setprio 0
	s_mov_b32 m0, s63
	v_lshl_add_u64 v[162:163], s[72:73], 0, v[140:141]
	ds_read_b128 v[210:213], v156 offset:16384
	ds_read_b128 v[214:217], v156 offset:17408
	ds_read_b128 v[218:221], v156 offset:18432
	ds_read_b128 v[222:225], v156 offset:19456
	ds_read_b128 v[226:229], v156 offset:20480
	ds_read_b128 v[230:233], v156 offset:21504
	ds_read_b128 v[234:237], v156 offset:22528
	ds_read_b128 v[238:241], v156 offset:23552
	global_load_lds_dwordx4 v[162:163], off
	v_lshl_add_u64 v[166:167], s[72:73], 0, v[138:139]
	s_mov_b32 m0, s64
	v_lshl_add_u64 v[178:179], v[162:163], 0, s[4:5]
	global_load_lds_dwordx4 v[166:167], off
	s_mov_b32 m0, s65
	v_lshl_add_u64 v[242:243], s[26:27], 0, v[132:133]
	global_load_lds_dwordx4 v[178:179], off
	v_lshl_add_u64 v[178:179], v[166:167], 0, s[4:5]
	s_add_i32 m0, s65, 0x2000
	s_nop 0
	global_load_lds_dwordx4 v[178:179], off
	v_lshl_add_u64 v[178:179], s[26:27], 0, v[128:129]
	s_mov_b32 m0, s44
	s_nop 0
	global_load_lds_dwordx4 v[178:179], off
	s_mov_b32 m0, s45
	s_nop 0
	global_load_lds_dwordx4 v[242:243], off
	s_waitcnt vmcnt(8)
	s_waitcnt lgkmcnt(0)
	s_setprio 1
	s_barrier
	v_mfma_f32_16x16x32_bf16 v[60:63], v[158:161], v[210:213], 0
	v_mfma_f32_16x16x32_bf16 v[56:59], v[186:189], v[210:213], 0
	v_mfma_f32_16x16x32_bf16 v[48:51], v[158:161], v[218:221], 0
	v_mfma_f32_16x16x32_bf16 v[40:43], v[186:189], v[218:221], 0
	v_mfma_f32_16x16x32_bf16 v[32:35], v[158:161], v[226:229], 0
	v_mfma_f32_16x16x32_bf16 v[24:27], v[186:189], v[226:229], 0
	v_mfma_f32_16x16x32_bf16 v[16:19], v[158:161], v[234:237], 0
	v_mfma_f32_16x16x32_bf16 v[8:11], v[186:189], v[234:237], 0
	v_mfma_f32_16x16x32_bf16 v[60:63], v[182:185], v[214:217], v[60:63]
	v_mfma_f32_16x16x32_bf16 v[56:59], v[190:193], v[214:217], v[56:59]
	v_mfma_f32_16x16x32_bf16 v[48:51], v[182:185], v[222:225], v[48:51]
	v_mfma_f32_16x16x32_bf16 v[40:43], v[190:193], v[222:225], v[40:43]
	v_mfma_f32_16x16x32_bf16 v[32:35], v[182:185], v[230:233], v[32:35]
	v_mfma_f32_16x16x32_bf16 v[24:27], v[190:193], v[230:233], v[24:27]
	v_mfma_f32_16x16x32_bf16 v[16:19], v[182:185], v[238:241], v[16:19]
	v_mfma_f32_16x16x32_bf16 v[8:11], v[190:193], v[238:241], v[8:11]
	v_mfma_f32_16x16x32_bf16 v[52:55], v[194:197], v[210:213], 0
	v_mfma_f32_16x16x32_bf16 v[44:47], v[202:205], v[210:213], 0
	v_mfma_f32_16x16x32_bf16 v[36:39], v[194:197], v[218:221], 0
	v_mfma_f32_16x16x32_bf16 v[28:31], v[202:205], v[218:221], 0
	v_mfma_f32_16x16x32_bf16 v[20:23], v[194:197], v[226:229], 0
	v_mfma_f32_16x16x32_bf16 v[12:15], v[202:205], v[226:229], 0
	v_mfma_f32_16x16x32_bf16 v[4:7], v[194:197], v[234:237], 0
	v_mfma_f32_16x16x32_bf16 v[0:3], v[202:205], v[234:237], 0
	v_mfma_f32_16x16x32_bf16 v[52:55], v[198:201], v[214:217], v[52:55]
	v_mfma_f32_16x16x32_bf16 v[44:47], v[206:209], v[214:217], v[44:47]
	v_mfma_f32_16x16x32_bf16 v[36:39], v[198:201], v[222:225], v[36:39]
	v_mfma_f32_16x16x32_bf16 v[28:31], v[206:209], v[222:225], v[28:31]
	v_mfma_f32_16x16x32_bf16 v[20:23], v[198:201], v[230:233], v[20:23]
	v_mfma_f32_16x16x32_bf16 v[12:15], v[206:209], v[230:233], v[12:15]
	v_mfma_f32_16x16x32_bf16 v[4:7], v[198:201], v[238:241], v[4:7]
	v_mfma_f32_16x16x32_bf16 v[0:3], v[206:209], v[238:241], v[0:3]
	s_barrier
	s_setprio 0
	s_add_i32 s71, 0, 0x18000
	v_add_u32_e32 v157, s71, v131
	s_add_i32 s72, 0, 0x1c000
	ds_read_b128 v[158:161], v157
	ds_read_b128 v[182:185], v157 offset:1024
	ds_read_b128 v[186:189], v157 offset:2048
	ds_read_b128 v[190:193], v157 offset:3072
	v_add_u32_e32 v157, s72, v131
	ds_read_b128 v[194:197], v157
	ds_read_b128 v[198:201], v157 offset:1024
	ds_read_b128 v[202:205], v157 offset:2048
	ds_read_b128 v[206:209], v157 offset:3072
	s_add_u32 s26, s26, 0x40000
	s_addc_u32 s27, s27, 0
	s_mov_b32 m0, s48
	v_lshl_add_u64 v[244:245], s[26:27], 0, v[128:129]
	ds_read_b128 v[210:213], v156 offset:32768
	ds_read_b128 v[214:217], v156 offset:33792
	ds_read_b128 v[218:221], v156 offset:34816
	ds_read_b128 v[222:225], v156 offset:35840
	ds_read_b128 v[226:229], v156 offset:36864
	ds_read_b128 v[230:233], v156 offset:37888
	ds_read_b128 v[234:237], v156 offset:38912
	ds_read_b128 v[238:241], v156 offset:39936
	global_load_lds_dwordx4 v[244:245], off
	v_lshl_add_u64 v[244:245], s[26:27], 0, v[132:133]
	s_mov_b32 m0, s49
	s_nop 0
	global_load_lds_dwordx4 v[244:245], off
	s_waitcnt vmcnt(8)
	s_waitcnt lgkmcnt(0)
	s_setprio 1
	s_barrier
	v_mfma_f32_16x16x32_bf16 v[124:127], v[158:161], v[210:213], v[124:127]
	v_mfma_f32_16x16x32_bf16 v[120:123], v[186:189], v[210:213], v[120:123]
	v_mfma_f32_16x16x32_bf16 v[112:115], v[158:161], v[218:221], v[112:115]
	v_mfma_f32_16x16x32_bf16 v[104:107], v[186:189], v[218:221], v[104:107]
	v_mfma_f32_16x16x32_bf16 v[96:99], v[158:161], v[226:229], v[96:99]
	v_mfma_f32_16x16x32_bf16 v[88:91], v[186:189], v[226:229], v[88:91]
	v_mfma_f32_16x16x32_bf16 v[80:83], v[158:161], v[234:237], v[80:83]
	v_mfma_f32_16x16x32_bf16 v[72:75], v[186:189], v[234:237], v[72:75]
	v_mfma_f32_16x16x32_bf16 v[124:127], v[182:185], v[214:217], v[124:127]
	v_mfma_f32_16x16x32_bf16 v[120:123], v[190:193], v[214:217], v[120:123]
	v_mfma_f32_16x16x32_bf16 v[112:115], v[182:185], v[222:225], v[112:115]
	v_mfma_f32_16x16x32_bf16 v[104:107], v[190:193], v[222:225], v[104:107]
	v_mfma_f32_16x16x32_bf16 v[96:99], v[182:185], v[230:233], v[96:99]
	v_mfma_f32_16x16x32_bf16 v[88:91], v[190:193], v[230:233], v[88:91]
	v_mfma_f32_16x16x32_bf16 v[80:83], v[182:185], v[238:241], v[80:83]
	v_mfma_f32_16x16x32_bf16 v[72:75], v[190:193], v[238:241], v[72:75]
	v_mfma_f32_16x16x32_bf16 v[116:119], v[194:197], v[210:213], v[116:119]
	v_mfma_f32_16x16x32_bf16 v[108:111], v[202:205], v[210:213], v[108:111]
	v_mfma_f32_16x16x32_bf16 v[100:103], v[194:197], v[218:221], v[100:103]
	v_mfma_f32_16x16x32_bf16 v[92:95], v[202:205], v[218:221], v[92:95]
	v_mfma_f32_16x16x32_bf16 v[84:87], v[194:197], v[226:229], v[84:87]
	v_mfma_f32_16x16x32_bf16 v[76:79], v[202:205], v[226:229], v[76:79]
	v_mfma_f32_16x16x32_bf16 v[68:71], v[194:197], v[234:237], v[68:71]
	v_mfma_f32_16x16x32_bf16 v[64:67], v[202:205], v[234:237], v[64:67]
	v_mfma_f32_16x16x32_bf16 v[116:119], v[198:201], v[214:217], v[116:119]
	v_mfma_f32_16x16x32_bf16 v[108:111], v[206:209], v[214:217], v[108:111]
	v_mfma_f32_16x16x32_bf16 v[100:103], v[198:201], v[222:225], v[100:103]
	v_mfma_f32_16x16x32_bf16 v[92:95], v[206:209], v[222:225], v[92:95]
	v_mfma_f32_16x16x32_bf16 v[84:87], v[198:201], v[230:233], v[84:87]
	v_mfma_f32_16x16x32_bf16 v[76:79], v[206:209], v[230:233], v[76:79]
	v_mfma_f32_16x16x32_bf16 v[68:71], v[198:201], v[238:241], v[68:71]
	v_mfma_f32_16x16x32_bf16 v[64:67], v[206:209], v[238:241], v[64:67]
	s_barrier
	s_setprio 0
	s_add_i32 s26, s71, s37
	v_lshl_add_u64 v[244:245], v[162:163], 0, s[12:13]
	s_mov_b32 m0, s26
	ds_read_b128 v[210:213], v156 offset:49152
	ds_read_b128 v[214:217], v156 offset:50176
	ds_read_b128 v[218:221], v156 offset:51200
	ds_read_b128 v[222:225], v156 offset:52224
	ds_read_b128 v[226:229], v156 offset:53248
	ds_read_b128 v[230:233], v156 offset:54272
	ds_read_b128 v[234:237], v156 offset:55296
	ds_read_b128 v[238:241], v156 offset:56320
	global_load_lds_dwordx4 v[244:245], off
	v_lshl_add_u64 v[244:245], v[166:167], 0, s[12:13]
	s_add_i32 m0, s26, 0x2000
	s_add_i32 s26, s72, s37
	global_load_lds_dwordx4 v[244:245], off
	v_lshl_add_u64 v[162:163], v[162:163], 0, s[14:15]
	s_mov_b32 m0, s26
	s_nop 0
	global_load_lds_dwordx4 v[162:163], off
	v_lshl_add_u64 v[162:163], v[166:167], 0, s[14:15]
	s_add_i32 m0, s26, 0x2000
	s_nop 0
	global_load_lds_dwordx4 v[162:163], off
	v_lshl_add_u64 v[162:163], v[178:179], 0, s[12:13]
	s_mov_b32 m0, s50
	s_nop 0
	global_load_lds_dwordx4 v[162:163], off
	v_lshl_add_u64 v[162:163], v[242:243], 0, s[12:13]
	s_mov_b32 m0, s51
	s_nop 0
	global_load_lds_dwordx4 v[162:163], off
	s_waitcnt vmcnt(8)
	s_waitcnt lgkmcnt(0)
	s_setprio 1
	s_barrier
	v_mfma_f32_16x16x32_bf16 v[60:63], v[158:161], v[210:213], v[60:63]
	v_mfma_f32_16x16x32_bf16 v[56:59], v[186:189], v[210:213], v[56:59]
	v_mfma_f32_16x16x32_bf16 v[48:51], v[158:161], v[218:221], v[48:51]
	v_mfma_f32_16x16x32_bf16 v[40:43], v[186:189], v[218:221], v[40:43]
	v_mfma_f32_16x16x32_bf16 v[32:35], v[158:161], v[226:229], v[32:35]
	v_mfma_f32_16x16x32_bf16 v[24:27], v[186:189], v[226:229], v[24:27]
	v_mfma_f32_16x16x32_bf16 v[16:19], v[158:161], v[234:237], v[16:19]
	v_mfma_f32_16x16x32_bf16 v[8:11], v[186:189], v[234:237], v[8:11]
	v_mfma_f32_16x16x32_bf16 v[60:63], v[182:185], v[214:217], v[60:63]
	v_mfma_f32_16x16x32_bf16 v[56:59], v[190:193], v[214:217], v[56:59]
	v_mfma_f32_16x16x32_bf16 v[48:51], v[182:185], v[222:225], v[48:51]
	v_mfma_f32_16x16x32_bf16 v[40:43], v[190:193], v[222:225], v[40:43]
	v_mfma_f32_16x16x32_bf16 v[32:35], v[182:185], v[230:233], v[32:35]
	v_mfma_f32_16x16x32_bf16 v[24:27], v[190:193], v[230:233], v[24:27]
	v_mfma_f32_16x16x32_bf16 v[16:19], v[182:185], v[238:241], v[16:19]
	v_mfma_f32_16x16x32_bf16 v[8:11], v[190:193], v[238:241], v[8:11]
	v_mfma_f32_16x16x32_bf16 v[52:55], v[194:197], v[210:213], v[52:55]
	v_mfma_f32_16x16x32_bf16 v[44:47], v[202:205], v[210:213], v[44:47]
	v_mfma_f32_16x16x32_bf16 v[36:39], v[194:197], v[218:221], v[36:39]
	v_mfma_f32_16x16x32_bf16 v[28:31], v[202:205], v[218:221], v[28:31]
	v_mfma_f32_16x16x32_bf16 v[20:23], v[194:197], v[226:229], v[20:23]
	v_mfma_f32_16x16x32_bf16 v[12:15], v[202:205], v[226:229], v[12:15]
	v_mfma_f32_16x16x32_bf16 v[4:7], v[194:197], v[234:237], v[4:7]
	v_mfma_f32_16x16x32_bf16 v[0:3], v[202:205], v[234:237], v[0:3]
	v_mfma_f32_16x16x32_bf16 v[52:55], v[198:201], v[214:217], v[52:55]
	v_mfma_f32_16x16x32_bf16 v[44:47], v[206:209], v[214:217], v[44:47]
	v_mfma_f32_16x16x32_bf16 v[36:39], v[198:201], v[222:225], v[36:39]
	v_mfma_f32_16x16x32_bf16 v[28:31], v[206:209], v[222:225], v[28:31]
	v_mfma_f32_16x16x32_bf16 v[20:23], v[198:201], v[230:233], v[20:23]
	v_mfma_f32_16x16x32_bf16 v[12:15], v[206:209], v[230:233], v[12:15]
	v_mfma_f32_16x16x32_bf16 v[4:7], v[198:201], v[238:241], v[4:7]
	v_mfma_f32_16x16x32_bf16 v[0:3], v[206:209], v[238:241], v[0:3]
	s_barrier
	s_setprio 0
	s_add_i32 s70, s70, 2
	s_add_u32 s24, s24, 0x100
	s_addc_u32 s25, s25, 0
	s_add_u32 s68, s68, 0x100
	s_addc_u32 s69, s69, 0
	s_cmp_gt_u32 s70, 13
	s_cbranch_scc0 .LBB0_280
	s_branch .Lpeel_exit_us

.Lpeel_exit_us:
	s_and_b64 vcc, exec, s[16:17]
	s_cbranch_vccz .LBB0_283
	s_barrier

.LBB0_295:
	s_and_b32 s17, s18, 3
	s_and_b64 s[18:19], s[2:3], exec
	s_cselect_b32 s18, s17, s4
	s_ashr_i32 s19, s18, 31
	s_lshl_b64 s[18:19], s[18:19], 19
	s_add_u32 s18, s31, s18
	s_addc_u32 s19, s34, s19
	s_and_b64 s[24:25], s[2:3], exec
	s_cselect_b32 s4, s19, s21
	s_cselect_b32 s38, s18, s20
	s_add_u32 s20, s20, 0x40080
	s_addc_u32 s21, s21, 0
	s_add_u32 s39, s22, 0x100
	s_addc_u32 s64, s23, 0
	s_mov_b32 s65, -2
	ds_read_b128 v[156:159], v153
	ds_read_b128 v[160:163], v153 offset:1024
	ds_read_b128 v[174:177], v153 offset:2048
	ds_read_b128 v[182:185], v153 offset:3072
	ds_read_b128 v[186:189], v154
	ds_read_b128 v[190:193], v154 offset:1024
	ds_read_b128 v[194:197], v154 offset:2048
	ds_read_b128 v[198:201], v154 offset:3072
	s_add_u32 s22, s20, 0xfffc0080
	s_addc_u32 s23, s21, -1
	s_cmp_eq_u32 s65, 12
	s_cselect_b32 s25, s4, s23
	s_cselect_b32 s24, s38, s22
	s_cselect_b32 s23, s15, s64
	s_cselect_b32 s22, s14, s39
	s_mov_b32 m0, s62
	v_lshl_add_u64 v[166:167], s[20:21], 0, v[144:145]
	ds_read_b128 v[202:205], v155
	ds_read_b128 v[206:209], v155 offset:1024
	ds_read_b128 v[210:213], v155 offset:2048
	ds_read_b128 v[214:217], v155 offset:3072
	ds_read_b128 v[218:221], v155 offset:4096
	ds_read_b128 v[222:225], v155 offset:5120
	ds_read_b128 v[226:229], v155 offset:6144
	ds_read_b128 v[230:233], v155 offset:7168
	global_load_lds_dwordx4 v[166:167], off
	v_lshl_add_u64 v[166:167], s[20:21], 0, v[146:147]
	s_add_i32 m0, s27, 0xe000
	s_nop 0
	global_load_lds_dwordx4 v[166:167], off
	s_waitcnt vmcnt(8)
	s_waitcnt lgkmcnt(0)
	s_setprio 1
	s_barrier
	v_mfma_f32_16x16x32_bf16 v[124:127], v[156:159], v[202:205], 0
	v_mfma_f32_16x16x32_bf16 v[120:123], v[174:177], v[202:205], 0
	v_mfma_f32_16x16x32_bf16 v[112:115], v[156:159], v[210:213], 0
	v_mfma_f32_16x16x32_bf16 v[104:107], v[174:177], v[210:213], 0
	v_mfma_f32_16x16x32_bf16 v[96:99], v[156:159], v[218:221], 0
	v_mfma_f32_16x16x32_bf16 v[88:91], v[174:177], v[218:221], 0
	v_mfma_f32_16x16x32_bf16 v[80:83], v[156:159], v[226:229], 0
	v_mfma_f32_16x16x32_bf16 v[72:75], v[174:177], v[226:229], 0
	v_mfma_f32_16x16x32_bf16 v[124:127], v[160:163], v[206:209], v[124:127]
	v_mfma_f32_16x16x32_bf16 v[120:123], v[182:185], v[206:209], v[120:123]
	v_mfma_f32_16x16x32_bf16 v[112:115], v[160:163], v[214:217], v[112:115]
	v_mfma_f32_16x16x32_bf16 v[104:107], v[182:185], v[214:217], v[104:107]
	v_mfma_f32_16x16x32_bf16 v[96:99], v[160:163], v[222:225], v[96:99]
	v_mfma_f32_16x16x32_bf16 v[88:91], v[182:185], v[222:225], v[88:91]
	v_mfma_f32_16x16x32_bf16 v[80:83], v[160:163], v[230:233], v[80:83]
	v_mfma_f32_16x16x32_bf16 v[72:75], v[182:185], v[230:233], v[72:75]
	v_mfma_f32_16x16x32_bf16 v[116:119], v[186:189], v[202:205], 0
	v_mfma_f32_16x16x32_bf16 v[108:111], v[194:197], v[202:205], 0
	v_mfma_f32_16x16x32_bf16 v[100:103], v[186:189], v[210:213], 0
	v_mfma_f32_16x16x32_bf16 v[92:95], v[194:197], v[210:213], 0
	v_mfma_f32_16x16x32_bf16 v[84:87], v[186:189], v[218:221], 0
	v_mfma_f32_16x16x32_bf16 v[76:79], v[194:197], v[218:221], 0
	v_mfma_f32_16x16x32_bf16 v[68:71], v[186:189], v[226:229], 0
	v_mfma_f32_16x16x32_bf16 v[64:67], v[194:197], v[226:229], 0
	v_mfma_f32_16x16x32_bf16 v[116:119], v[190:193], v[206:209], v[116:119]
	v_mfma_f32_16x16x32_bf16 v[108:111], v[198:201], v[206:209], v[108:111]
	v_mfma_f32_16x16x32_bf16 v[100:103], v[190:193], v[214:217], v[100:103]
	v_mfma_f32_16x16x32_bf16 v[92:95], v[198:201], v[214:217], v[92:95]
	v_mfma_f32_16x16x32_bf16 v[84:87], v[190:193], v[222:225], v[84:87]
	v_mfma_f32_16x16x32_bf16 v[76:79], v[198:201], v[222:225], v[76:79]
	v_mfma_f32_16x16x32_bf16 v[68:71], v[190:193], v[230:233], v[68:71]
	v_mfma_f32_16x16x32_bf16 v[64:67], v[198:201], v[230:233], v[64:67]
	s_barrier
	s_setprio 0
	s_add_i32 s66, s60, s26
	v_lshl_add_u64 v[166:167], s[22:23], 0, v[140:141]
	s_mov_b32 m0, s66
	ds_read_b128 v[202:205], v155 offset:16384
	ds_read_b128 v[206:209], v155 offset:17408
	ds_read_b128 v[210:213], v155 offset:18432
	ds_read_b128 v[214:217], v155 offset:19456
	ds_read_b128 v[218:221], v155 offset:20480
	ds_read_b128 v[222:225], v155 offset:21504
	ds_read_b128 v[226:229], v155 offset:22528
	ds_read_b128 v[230:233], v155 offset:23552
	global_load_lds_dwordx4 v[166:167], off
	s_add_i32 m0, s66, 0x2000
	s_add_u32 s66, s22, 0x1000
	v_lshl_add_u64 v[178:179], s[22:23], 0, v[138:139]
	s_addc_u32 s67, s23, 0
	s_add_i32 s68, s61, s26
	global_load_lds_dwordx4 v[178:179], off
	v_lshl_add_u64 v[234:235], s[66:67], 0, v[140:141]
	s_mov_b32 m0, s68
	v_lshl_add_u64 v[236:237], s[24:25], 0, v[132:133]
	global_load_lds_dwordx4 v[234:235], off
	v_lshl_add_u64 v[234:235], s[66:67], 0, v[138:139]
	s_add_i32 m0, s68, 0x2000
	s_nop 0
	global_load_lds_dwordx4 v[234:235], off
	v_lshl_add_u64 v[234:235], s[24:25], 0, v[128:129]
	s_mov_b32 m0, s27
	s_nop 0
	global_load_lds_dwordx4 v[234:235], off
	s_mov_b32 m0, s37
	s_nop 0
	global_load_lds_dwordx4 v[236:237], off
	s_waitcnt vmcnt(8)
	s_waitcnt lgkmcnt(0)
	s_setprio 1
	s_barrier
	v_mfma_f32_16x16x32_bf16 v[60:63], v[156:159], v[202:205], 0
	v_mfma_f32_16x16x32_bf16 v[56:59], v[174:177], v[202:205], 0
	v_mfma_f32_16x16x32_bf16 v[48:51], v[156:159], v[210:213], 0
	v_mfma_f32_16x16x32_bf16 v[40:43], v[174:177], v[210:213], 0
	v_mfma_f32_16x16x32_bf16 v[32:35], v[156:159], v[218:221], 0
	v_mfma_f32_16x16x32_bf16 v[24:27], v[174:177], v[218:221], 0
	v_mfma_f32_16x16x32_bf16 v[16:19], v[156:159], v[226:229], 0
	v_mfma_f32_16x16x32_bf16 v[8:11], v[174:177], v[226:229], 0
	v_mfma_f32_16x16x32_bf16 v[60:63], v[160:163], v[206:209], v[60:63]
	v_mfma_f32_16x16x32_bf16 v[56:59], v[182:185], v[206:209], v[56:59]
	v_mfma_f32_16x16x32_bf16 v[48:51], v[160:163], v[214:217], v[48:51]
	v_mfma_f32_16x16x32_bf16 v[40:43], v[182:185], v[214:217], v[40:43]
	v_mfma_f32_16x16x32_bf16 v[32:35], v[160:163], v[222:225], v[32:35]
	v_mfma_f32_16x16x32_bf16 v[24:27], v[182:185], v[222:225], v[24:27]
	v_mfma_f32_16x16x32_bf16 v[16:19], v[160:163], v[230:233], v[16:19]
	v_mfma_f32_16x16x32_bf16 v[8:11], v[182:185], v[230:233], v[8:11]
	v_mfma_f32_16x16x32_bf16 v[52:55], v[186:189], v[202:205], 0
	v_mfma_f32_16x16x32_bf16 v[44:47], v[194:197], v[202:205], 0
	v_mfma_f32_16x16x32_bf16 v[36:39], v[186:189], v[210:213], 0
	v_mfma_f32_16x16x32_bf16 v[28:31], v[194:197], v[210:213], 0
	v_mfma_f32_16x16x32_bf16 v[20:23], v[186:189], v[218:221], 0
	v_mfma_f32_16x16x32_bf16 v[12:15], v[194:197], v[218:221], 0
	v_mfma_f32_16x16x32_bf16 v[4:7], v[186:189], v[226:229], 0
	v_mfma_f32_16x16x32_bf16 v[0:3], v[194:197], v[226:229], 0
	v_mfma_f32_16x16x32_bf16 v[52:55], v[190:193], v[206:209], v[52:55]
	v_mfma_f32_16x16x32_bf16 v[44:47], v[198:201], v[206:209], v[44:47]
	v_mfma_f32_16x16x32_bf16 v[36:39], v[190:193], v[214:217], v[36:39]
	v_mfma_f32_16x16x32_bf16 v[28:31], v[198:201], v[214:217], v[28:31]
	v_mfma_f32_16x16x32_bf16 v[20:23], v[190:193], v[222:225], v[20:23]
	v_mfma_f32_16x16x32_bf16 v[12:15], v[198:201], v[222:225], v[12:15]
	v_mfma_f32_16x16x32_bf16 v[4:7], v[190:193], v[230:233], v[4:7]
	v_mfma_f32_16x16x32_bf16 v[0:3], v[198:201], v[230:233], v[0:3]
	s_barrier
	s_setprio 0
	s_add_i32 s66, 0, 0x18000
	v_add_u32_e32 v181, s66, v131
	s_add_i32 s67, 0, 0x1c000
	ds_read_b128 v[156:159], v181
	ds_read_b128 v[160:163], v181 offset:1024
	ds_read_b128 v[174:177], v181 offset:2048
	ds_read_b128 v[182:185], v181 offset:3072
	v_add_u32_e32 v181, s67, v131
	ds_read_b128 v[186:189], v181
	ds_read_b128 v[190:193], v181 offset:1024
	ds_read_b128 v[194:197], v181 offset:2048
	ds_read_b128 v[198:201], v181 offset:3072
	s_add_u32 s24, s24, 0x40000
	s_addc_u32 s25, s25, 0
	s_mov_b32 m0, s44
	v_lshl_add_u64 v[238:239], s[24:25], 0, v[128:129]
	ds_read_b128 v[202:205], v155 offset:32768
	ds_read_b128 v[206:209], v155 offset:33792
	ds_read_b128 v[210:213], v155 offset:34816
	ds_read_b128 v[214:217], v155 offset:35840
	ds_read_b128 v[218:221], v155 offset:36864
	ds_read_b128 v[222:225], v155 offset:37888
	ds_read_b128 v[226:229], v155 offset:38912
	ds_read_b128 v[230:233], v155 offset:39936
	global_load_lds_dwordx4 v[238:239], off
	v_lshl_add_u64 v[238:239], s[24:25], 0, v[132:133]
	s_mov_b32 m0, s45
	s_nop 0
	global_load_lds_dwordx4 v[238:239], off
	s_waitcnt vmcnt(8)
	s_waitcnt lgkmcnt(0)
	s_setprio 1
	s_barrier
	v_mfma_f32_16x16x32_bf16 v[124:127], v[156:159], v[202:205], v[124:127]
	v_mfma_f32_16x16x32_bf16 v[120:123], v[174:177], v[202:205], v[120:123]
	v_mfma_f32_16x16x32_bf16 v[112:115], v[156:159], v[210:213], v[112:115]
	v_mfma_f32_16x16x32_bf16 v[104:107], v[174:177], v[210:213], v[104:107]
	v_mfma_f32_16x16x32_bf16 v[96:99], v[156:159], v[218:221], v[96:99]
	v_mfma_f32_16x16x32_bf16 v[88:91], v[174:177], v[218:221], v[88:91]
	v_mfma_f32_16x16x32_bf16 v[80:83], v[156:159], v[226:229], v[80:83]
	v_mfma_f32_16x16x32_bf16 v[72:75], v[174:177], v[226:229], v[72:75]
	v_mfma_f32_16x16x32_bf16 v[124:127], v[160:163], v[206:209], v[124:127]
	v_mfma_f32_16x16x32_bf16 v[120:123], v[182:185], v[206:209], v[120:123]
	v_mfma_f32_16x16x32_bf16 v[112:115], v[160:163], v[214:217], v[112:115]
	v_mfma_f32_16x16x32_bf16 v[104:107], v[182:185], v[214:217], v[104:107]
	v_mfma_f32_16x16x32_bf16 v[96:99], v[160:163], v[222:225], v[96:99]
	v_mfma_f32_16x16x32_bf16 v[88:91], v[182:185], v[222:225], v[88:91]
	v_mfma_f32_16x16x32_bf16 v[80:83], v[160:163], v[230:233], v[80:83]
	v_mfma_f32_16x16x32_bf16 v[72:75], v[182:185], v[230:233], v[72:75]
	v_mfma_f32_16x16x32_bf16 v[116:119], v[186:189], v[202:205], v[116:119]
	v_mfma_f32_16x16x32_bf16 v[108:111], v[194:197], v[202:205], v[108:111]
	v_mfma_f32_16x16x32_bf16 v[100:103], v[186:189], v[210:213], v[100:103]
	v_mfma_f32_16x16x32_bf16 v[92:95], v[194:197], v[210:213], v[92:95]
	v_mfma_f32_16x16x32_bf16 v[84:87], v[186:189], v[218:221], v[84:87]
	v_mfma_f32_16x16x32_bf16 v[76:79], v[194:197], v[218:221], v[76:79]
	v_mfma_f32_16x16x32_bf16 v[68:71], v[186:189], v[226:229], v[68:71]
	v_mfma_f32_16x16x32_bf16 v[64:67], v[194:197], v[226:229], v[64:67]
	v_mfma_f32_16x16x32_bf16 v[116:119], v[190:193], v[206:209], v[116:119]
	v_mfma_f32_16x16x32_bf16 v[108:111], v[198:201], v[206:209], v[108:111]
	v_mfma_f32_16x16x32_bf16 v[100:103], v[190:193], v[214:217], v[100:103]
	v_mfma_f32_16x16x32_bf16 v[92:95], v[198:201], v[214:217], v[92:95]
	v_mfma_f32_16x16x32_bf16 v[84:87], v[190:193], v[222:225], v[84:87]
	v_mfma_f32_16x16x32_bf16 v[76:79], v[198:201], v[222:225], v[76:79]
	v_mfma_f32_16x16x32_bf16 v[68:71], v[190:193], v[230:233], v[68:71]
	v_mfma_f32_16x16x32_bf16 v[64:67], v[198:201], v[230:233], v[64:67]
	s_barrier
	s_setprio 0
	s_add_i32 s24, s66, s26
	v_lshl_add_u64 v[166:167], v[166:167], 0, s[10:11]
	s_mov_b32 m0, s24
	ds_read_b128 v[202:205], v155 offset:49152
	ds_read_b128 v[206:209], v155 offset:50176
	ds_read_b128 v[210:213], v155 offset:51200
	ds_read_b128 v[214:217], v155 offset:52224
	ds_read_b128 v[218:221], v155 offset:53248
	ds_read_b128 v[222:225], v155 offset:54272
	ds_read_b128 v[226:229], v155 offset:55296
	ds_read_b128 v[230:233], v155 offset:56320
	global_load_lds_dwordx4 v[166:167], off
	s_add_i32 m0, s24, 0x2000
	s_add_u32 s22, s22, 0x1080
	v_lshl_add_u64 v[166:167], v[178:179], 0, s[10:11]
	s_addc_u32 s23, s23, 0
	s_add_i32 s24, s67, s26
	global_load_lds_dwordx4 v[166:167], off
	v_lshl_add_u64 v[166:167], s[22:23], 0, v[140:141]
	s_mov_b32 m0, s24
	s_nop 0
	global_load_lds_dwordx4 v[166:167], off
	v_lshl_add_u64 v[166:167], s[22:23], 0, v[138:139]
	s_add_i32 m0, s24, 0x2000
	s_nop 0
	global_load_lds_dwordx4 v[166:167], off
	v_lshl_add_u64 v[166:167], v[234:235], 0, s[10:11]
	s_mov_b32 m0, s50
	s_nop 0
	global_load_lds_dwordx4 v[166:167], off
	v_lshl_add_u64 v[166:167], v[236:237], 0, s[10:11]
	s_mov_b32 m0, s51
	s_nop 0
	global_load_lds_dwordx4 v[166:167], off
	s_waitcnt vmcnt(8)
	s_waitcnt lgkmcnt(0)
	s_setprio 1
	s_barrier
	v_mfma_f32_16x16x32_bf16 v[60:63], v[156:159], v[202:205], v[60:63]
	v_mfma_f32_16x16x32_bf16 v[56:59], v[174:177], v[202:205], v[56:59]
	v_mfma_f32_16x16x32_bf16 v[48:51], v[156:159], v[210:213], v[48:51]
	v_mfma_f32_16x16x32_bf16 v[40:43], v[174:177], v[210:213], v[40:43]
	v_mfma_f32_16x16x32_bf16 v[32:35], v[156:159], v[218:221], v[32:35]
	v_mfma_f32_16x16x32_bf16 v[24:27], v[174:177], v[218:221], v[24:27]
	v_mfma_f32_16x16x32_bf16 v[16:19], v[156:159], v[226:229], v[16:19]
	v_mfma_f32_16x16x32_bf16 v[8:11], v[174:177], v[226:229], v[8:11]
	v_mfma_f32_16x16x32_bf16 v[60:63], v[160:163], v[206:209], v[60:63]
	v_mfma_f32_16x16x32_bf16 v[56:59], v[182:185], v[206:209], v[56:59]
	v_mfma_f32_16x16x32_bf16 v[48:51], v[160:163], v[214:217], v[48:51]
	v_mfma_f32_16x16x32_bf16 v[40:43], v[182:185], v[214:217], v[40:43]
	v_mfma_f32_16x16x32_bf16 v[32:35], v[160:163], v[222:225], v[32:35]
	v_mfma_f32_16x16x32_bf16 v[24:27], v[182:185], v[222:225], v[24:27]
	v_mfma_f32_16x16x32_bf16 v[16:19], v[160:163], v[230:233], v[16:19]
	v_mfma_f32_16x16x32_bf16 v[8:11], v[182:185], v[230:233], v[8:11]
	v_mfma_f32_16x16x32_bf16 v[52:55], v[186:189], v[202:205], v[52:55]
	v_mfma_f32_16x16x32_bf16 v[44:47], v[194:197], v[202:205], v[44:47]
	v_mfma_f32_16x16x32_bf16 v[36:39], v[186:189], v[210:213], v[36:39]
	v_mfma_f32_16x16x32_bf16 v[28:31], v[194:197], v[210:213], v[28:31]
	v_mfma_f32_16x16x32_bf16 v[20:23], v[186:189], v[218:221], v[20:23]
	v_mfma_f32_16x16x32_bf16 v[12:15], v[194:197], v[218:221], v[12:15]
	v_mfma_f32_16x16x32_bf16 v[4:7], v[186:189], v[226:229], v[4:7]
	v_mfma_f32_16x16x32_bf16 v[0:3], v[194:197], v[226:229], v[0:3]
	v_mfma_f32_16x16x32_bf16 v[52:55], v[190:193], v[206:209], v[52:55]
	v_mfma_f32_16x16x32_bf16 v[44:47], v[198:201], v[206:209], v[44:47]
	v_mfma_f32_16x16x32_bf16 v[36:39], v[190:193], v[214:217], v[36:39]
	v_mfma_f32_16x16x32_bf16 v[28:31], v[198:201], v[214:217], v[28:31]
	v_mfma_f32_16x16x32_bf16 v[20:23], v[190:193], v[222:225], v[20:23]
	v_mfma_f32_16x16x32_bf16 v[12:15], v[198:201], v[222:225], v[12:15]
	v_mfma_f32_16x16x32_bf16 v[4:7], v[190:193], v[230:233], v[4:7]
	v_mfma_f32_16x16x32_bf16 v[0:3], v[198:201], v[230:233], v[0:3]
	s_barrier
	s_setprio 0
	s_add_i32 s65, s65, 2
	s_add_u32 s20, s20, 0x100
	s_addc_u32 s21, s21, 0
	s_add_u32 s39, s39, 0x100
	s_addc_u32 s64, s64, 0
	s_cmp_gt_u32 s65, 13
	s_cbranch_scc0 .LBB0_296
	s_branch .Lpeel_exit_up
.LBB0_296:
	ds_read_b128 v[156:159], v153
	ds_read_b128 v[160:163], v153 offset:1024
	ds_read_b128 v[174:177], v153 offset:2048
	ds_read_b128 v[182:185], v153 offset:3072
	ds_read_b128 v[186:189], v154
	ds_read_b128 v[190:193], v154 offset:1024
	ds_read_b128 v[194:197], v154 offset:2048
	ds_read_b128 v[198:201], v154 offset:3072
	s_add_u32 s22, s20, 0xfffc0080
	s_addc_u32 s23, s21, -1
	s_cmp_eq_u32 s65, 12
	s_cselect_b32 s25, s4, s23
	s_cselect_b32 s24, s38, s22
	s_cselect_b32 s23, s15, s64
	s_cselect_b32 s22, s14, s39
	s_mov_b32 m0, s62
	v_lshl_add_u64 v[166:167], s[20:21], 0, v[144:145]
	ds_read_b128 v[202:205], v155
	ds_read_b128 v[206:209], v155 offset:1024
	ds_read_b128 v[210:213], v155 offset:2048
	ds_read_b128 v[214:217], v155 offset:3072
	ds_read_b128 v[218:221], v155 offset:4096
	ds_read_b128 v[222:225], v155 offset:5120
	ds_read_b128 v[226:229], v155 offset:6144
	ds_read_b128 v[230:233], v155 offset:7168
	global_load_lds_dwordx4 v[166:167], off
	v_lshl_add_u64 v[166:167], s[20:21], 0, v[146:147]
	s_add_i32 m0, s27, 0xe000
	s_nop 0
	global_load_lds_dwordx4 v[166:167], off
	s_waitcnt vmcnt(8)
	s_waitcnt lgkmcnt(0)
	s_setprio 1
	s_barrier
	v_mfma_f32_16x16x32_bf16 v[124:127], v[156:159], v[202:205], v[124:127]
	v_mfma_f32_16x16x32_bf16 v[120:123], v[174:177], v[202:205], v[120:123]
	v_mfma_f32_16x16x32_bf16 v[112:115], v[156:159], v[210:213], v[112:115]
	v_mfma_f32_16x16x32_bf16 v[104:107], v[174:177], v[210:213], v[104:107]
	v_mfma_f32_16x16x32_bf16 v[96:99], v[156:159], v[218:221], v[96:99]
	v_mfma_f32_16x16x32_bf16 v[88:91], v[174:177], v[218:221], v[88:91]
	v_mfma_f32_16x16x32_bf16 v[80:83], v[156:159], v[226:229], v[80:83]
	v_mfma_f32_16x16x32_bf16 v[72:75], v[174:177], v[226:229], v[72:75]
	v_mfma_f32_16x16x32_bf16 v[124:127], v[160:163], v[206:209], v[124:127]
	v_mfma_f32_16x16x32_bf16 v[120:123], v[182:185], v[206:209], v[120:123]
	v_mfma_f32_16x16x32_bf16 v[112:115], v[160:163], v[214:217], v[112:115]
	v_mfma_f32_16x16x32_bf16 v[104:107], v[182:185], v[214:217], v[104:107]
	v_mfma_f32_16x16x32_bf16 v[96:99], v[160:163], v[222:225], v[96:99]
	v_mfma_f32_16x16x32_bf16 v[88:91], v[182:185], v[222:225], v[88:91]
	v_mfma_f32_16x16x32_bf16 v[80:83], v[160:163], v[230:233], v[80:83]
	v_mfma_f32_16x16x32_bf16 v[72:75], v[182:185], v[230:233], v[72:75]
	v_mfma_f32_16x16x32_bf16 v[116:119], v[186:189], v[202:205], v[116:119]
	v_mfma_f32_16x16x32_bf16 v[108:111], v[194:197], v[202:205], v[108:111]
	v_mfma_f32_16x16x32_bf16 v[100:103], v[186:189], v[210:213], v[100:103]
	v_mfma_f32_16x16x32_bf16 v[92:95], v[194:197], v[210:213], v[92:95]
	v_mfma_f32_16x16x32_bf16 v[84:87], v[186:189], v[218:221], v[84:87]
	v_mfma_f32_16x16x32_bf16 v[76:79], v[194:197], v[218:221], v[76:79]
	v_mfma_f32_16x16x32_bf16 v[68:71], v[186:189], v[226:229], v[68:71]
	v_mfma_f32_16x16x32_bf16 v[64:67], v[194:197], v[226:229], v[64:67]
	v_mfma_f32_16x16x32_bf16 v[116:119], v[190:193], v[206:209], v[116:119]
	v_mfma_f32_16x16x32_bf16 v[108:111], v[198:201], v[206:209], v[108:111]
	v_mfma_f32_16x16x32_bf16 v[100:103], v[190:193], v[214:217], v[100:103]
	v_mfma_f32_16x16x32_bf16 v[92:95], v[198:201], v[214:217], v[92:95]
	v_mfma_f32_16x16x32_bf16 v[84:87], v[190:193], v[222:225], v[84:87]
	v_mfma_f32_16x16x32_bf16 v[76:79], v[198:201], v[222:225], v[76:79]
	v_mfma_f32_16x16x32_bf16 v[68:71], v[190:193], v[230:233], v[68:71]
	v_mfma_f32_16x16x32_bf16 v[64:67], v[198:201], v[230:233], v[64:67]
	s_barrier
	s_setprio 0
	s_add_i32 s66, s60, s26
	v_lshl_add_u64 v[166:167], s[22:23], 0, v[140:141]
	s_mov_b32 m0, s66
	ds_read_b128 v[202:205], v155 offset:16384
	ds_read_b128 v[206:209], v155 offset:17408
	ds_read_b128 v[210:213], v155 offset:18432
	ds_read_b128 v[214:217], v155 offset:19456
	ds_read_b128 v[218:221], v155 offset:20480
	ds_read_b128 v[222:225], v155 offset:21504
	ds_read_b128 v[226:229], v155 offset:22528
	ds_read_b128 v[230:233], v155 offset:23552
	global_load_lds_dwordx4 v[166:167], off
	s_add_i32 m0, s66, 0x2000
	s_add_u32 s66, s22, 0x1000
	v_lshl_add_u64 v[178:179], s[22:23], 0, v[138:139]
	s_addc_u32 s67, s23, 0
	s_add_i32 s68, s61, s26
	global_load_lds_dwordx4 v[178:179], off
	v_lshl_add_u64 v[234:235], s[66:67], 0, v[140:141]
	s_mov_b32 m0, s68
	v_lshl_add_u64 v[236:237], s[24:25], 0, v[132:133]
	global_load_lds_dwordx4 v[234:235], off
	v_lshl_add_u64 v[234:235], s[66:67], 0, v[138:139]
	s_add_i32 m0, s68, 0x2000
	s_nop 0
	global_load_lds_dwordx4 v[234:235], off
	v_lshl_add_u64 v[234:235], s[24:25], 0, v[128:129]
	s_mov_b32 m0, s27
	s_nop 0
	global_load_lds_dwordx4 v[234:235], off
	s_mov_b32 m0, s37
	s_nop 0
	global_load_lds_dwordx4 v[236:237], off
	s_waitcnt vmcnt(8)
	s_waitcnt lgkmcnt(0)
	s_setprio 1
	s_barrier
	v_mfma_f32_16x16x32_bf16 v[60:63], v[156:159], v[202:205], v[60:63]
	v_mfma_f32_16x16x32_bf16 v[56:59], v[174:177], v[202:205], v[56:59]
	v_mfma_f32_16x16x32_bf16 v[48:51], v[156:159], v[210:213], v[48:51]
	v_mfma_f32_16x16x32_bf16 v[40:43], v[174:177], v[210:213], v[40:43]
	v_mfma_f32_16x16x32_bf16 v[32:35], v[156:159], v[218:221], v[32:35]
	v_mfma_f32_16x16x32_bf16 v[24:27], v[174:177], v[218:221], v[24:27]
	v_mfma_f32_16x16x32_bf16 v[16:19], v[156:159], v[226:229], v[16:19]
	v_mfma_f32_16x16x32_bf16 v[8:11], v[174:177], v[226:229], v[8:11]
	v_mfma_f32_16x16x32_bf16 v[60:63], v[160:163], v[206:209], v[60:63]
	v_mfma_f32_16x16x32_bf16 v[56:59], v[182:185], v[206:209], v[56:59]
	v_mfma_f32_16x16x32_bf16 v[48:51], v[160:163], v[214:217], v[48:51]
	v_mfma_f32_16x16x32_bf16 v[40:43], v[182:185], v[214:217], v[40:43]
	v_mfma_f32_16x16x32_bf16 v[32:35], v[160:163], v[222:225], v[32:35]
	v_mfma_f32_16x16x32_bf16 v[24:27], v[182:185], v[222:225], v[24:27]
	v_mfma_f32_16x16x32_bf16 v[16:19], v[160:163], v[230:233], v[16:19]
	v_mfma_f32_16x16x32_bf16 v[8:11], v[182:185], v[230:233], v[8:11]
	v_mfma_f32_16x16x32_bf16 v[52:55], v[186:189], v[202:205], v[52:55]
	v_mfma_f32_16x16x32_bf16 v[44:47], v[194:197], v[202:205], v[44:47]
	v_mfma_f32_16x16x32_bf16 v[36:39], v[186:189], v[210:213], v[36:39]
	v_mfma_f32_16x16x32_bf16 v[28:31], v[194:197], v[210:213], v[28:31]
	v_mfma_f32_16x16x32_bf16 v[20:23], v[186:189], v[218:221], v[20:23]
	v_mfma_f32_16x16x32_bf16 v[12:15], v[194:197], v[218:221], v[12:15]
	v_mfma_f32_16x16x32_bf16 v[4:7], v[186:189], v[226:229], v[4:7]
	v_mfma_f32_16x16x32_bf16 v[0:3], v[194:197], v[226:229], v[0:3]
	v_mfma_f32_16x16x32_bf16 v[52:55], v[190:193], v[206:209], v[52:55]
	v_mfma_f32_16x16x32_bf16 v[44:47], v[198:201], v[206:209], v[44:47]
	v_mfma_f32_16x16x32_bf16 v[36:39], v[190:193], v[214:217], v[36:39]
	v_mfma_f32_16x16x32_bf16 v[28:31], v[198:201], v[214:217], v[28:31]
	v_mfma_f32_16x16x32_bf16 v[20:23], v[190:193], v[222:225], v[20:23]
	v_mfma_f32_16x16x32_bf16 v[12:15], v[198:201], v[222:225], v[12:15]
	v_mfma_f32_16x16x32_bf16 v[4:7], v[190:193], v[230:233], v[4:7]
	v_mfma_f32_16x16x32_bf16 v[0:3], v[198:201], v[230:233], v[0:3]
	s_barrier
	s_setprio 0
	s_add_i32 s66, 0, 0x18000
	v_add_u32_e32 v181, s66, v131
	s_add_i32 s67, 0, 0x1c000
	ds_read_b128 v[156:159], v181
	ds_read_b128 v[160:163], v181 offset:1024
	ds_read_b128 v[174:177], v181 offset:2048
	ds_read_b128 v[182:185], v181 offset:3072
	v_add_u32_e32 v181, s67, v131
	ds_read_b128 v[186:189], v181
	ds_read_b128 v[190:193], v181 offset:1024
	ds_read_b128 v[194:197], v181 offset:2048
	ds_read_b128 v[198:201], v181 offset:3072
	s_add_u32 s24, s24, 0x40000
	s_addc_u32 s25, s25, 0
	s_mov_b32 m0, s44
	v_lshl_add_u64 v[238:239], s[24:25], 0, v[128:129]
	ds_read_b128 v[202:205], v155 offset:32768
	ds_read_b128 v[206:209], v155 offset:33792
	ds_read_b128 v[210:213], v155 offset:34816
	ds_read_b128 v[214:217], v155 offset:35840
	ds_read_b128 v[218:221], v155 offset:36864
	ds_read_b128 v[222:225], v155 offset:37888
	ds_read_b128 v[226:229], v155 offset:38912
	ds_read_b128 v[230:233], v155 offset:39936
	global_load_lds_dwordx4 v[238:239], off
	v_lshl_add_u64 v[238:239], s[24:25], 0, v[132:133]
	s_mov_b32 m0, s45
	s_nop 0
	global_load_lds_dwordx4 v[238:239], off
	s_waitcnt vmcnt(8)
	s_waitcnt lgkmcnt(0)
	s_setprio 1
	s_barrier
	v_mfma_f32_16x16x32_bf16 v[124:127], v[156:159], v[202:205], v[124:127]
	v_mfma_f32_16x16x32_bf16 v[120:123], v[174:177], v[202:205], v[120:123]
	v_mfma_f32_16x16x32_bf16 v[112:115], v[156:159], v[210:213], v[112:115]
	v_mfma_f32_16x16x32_bf16 v[104:107], v[174:177], v[210:213], v[104:107]
	v_mfma_f32_16x16x32_bf16 v[96:99], v[156:159], v[218:221], v[96:99]
	v_mfma_f32_16x16x32_bf16 v[88:91], v[174:177], v[218:221], v[88:91]
	v_mfma_f32_16x16x32_bf16 v[80:83], v[156:159], v[226:229], v[80:83]
	v_mfma_f32_16x16x32_bf16 v[72:75], v[174:177], v[226:229], v[72:75]
	v_mfma_f32_16x16x32_bf16 v[124:127], v[160:163], v[206:209], v[124:127]
	v_mfma_f32_16x16x32_bf16 v[120:123], v[182:185], v[206:209], v[120:123]
	v_mfma_f32_16x16x32_bf16 v[112:115], v[160:163], v[214:217], v[112:115]
	v_mfma_f32_16x16x32_bf16 v[104:107], v[182:185], v[214:217], v[104:107]
	v_mfma_f32_16x16x32_bf16 v[96:99], v[160:163], v[222:225], v[96:99]
	v_mfma_f32_16x16x32_bf16 v[88:91], v[182:185], v[222:225], v[88:91]
	v_mfma_f32_16x16x32_bf16 v[80:83], v[160:163], v[230:233], v[80:83]
	v_mfma_f32_16x16x32_bf16 v[72:75], v[182:185], v[230:233], v[72:75]
	v_mfma_f32_16x16x32_bf16 v[116:119], v[186:189], v[202:205], v[116:119]
	v_mfma_f32_16x16x32_bf16 v[108:111], v[194:197], v[202:205], v[108:111]
	v_mfma_f32_16x16x32_bf16 v[100:103], v[186:189], v[210:213], v[100:103]
	v_mfma_f32_16x16x32_bf16 v[92:95], v[194:197], v[210:213], v[92:95]
	v_mfma_f32_16x16x32_bf16 v[84:87], v[186:189], v[218:221], v[84:87]
	v_mfma_f32_16x16x32_bf16 v[76:79], v[194:197], v[218:221], v[76:79]
	v_mfma_f32_16x16x32_bf16 v[68:71], v[186:189], v[226:229], v[68:71]
	v_mfma_f32_16x16x32_bf16 v[64:67], v[194:197], v[226:229], v[64:67]
	v_mfma_f32_16x16x32_bf16 v[116:119], v[190:193], v[206:209], v[116:119]
	v_mfma_f32_16x16x32_bf16 v[108:111], v[198:201], v[206:209], v[108:111]
	v_mfma_f32_16x16x32_bf16 v[100:103], v[190:193], v[214:217], v[100:103]
	v_mfma_f32_16x16x32_bf16 v[92:95], v[198:201], v[214:217], v[92:95]
	v_mfma_f32_16x16x32_bf16 v[84:87], v[190:193], v[222:225], v[84:87]
	v_mfma_f32_16x16x32_bf16 v[76:79], v[198:201], v[222:225], v[76:79]
	v_mfma_f32_16x16x32_bf16 v[68:71], v[190:193], v[230:233], v[68:71]
	v_mfma_f32_16x16x32_bf16 v[64:67], v[198:201], v[230:233], v[64:67]
	s_barrier
	s_setprio 0
	s_add_i32 s24, s66, s26
	v_lshl_add_u64 v[166:167], v[166:167], 0, s[10:11]
	s_mov_b32 m0, s24
	ds_read_b128 v[202:205], v155 offset:49152
	ds_read_b128 v[206:209], v155 offset:50176
	ds_read_b128 v[210:213], v155 offset:51200
	ds_read_b128 v[214:217], v155 offset:52224
	ds_read_b128 v[218:221], v155 offset:53248
	ds_read_b128 v[222:225], v155 offset:54272
	ds_read_b128 v[226:229], v155 offset:55296
	ds_read_b128 v[230:233], v155 offset:56320
	global_load_lds_dwordx4 v[166:167], off
	s_add_i32 m0, s24, 0x2000
	s_add_u32 s22, s22, 0x1080
	v_lshl_add_u64 v[166:167], v[178:179], 0, s[10:11]
	s_addc_u32 s23, s23, 0
	s_add_i32 s24, s67, s26
	global_load_lds_dwordx4 v[166:167], off
	v_lshl_add_u64 v[166:167], s[22:23], 0, v[140:141]
	s_mov_b32 m0, s24
	s_nop 0
	global_load_lds_dwordx4 v[166:167], off
	v_lshl_add_u64 v[166:167], s[22:23], 0, v[138:139]
	s_add_i32 m0, s24, 0x2000
	s_nop 0
	global_load_lds_dwordx4 v[166:167], off
	v_lshl_add_u64 v[166:167], v[234:235], 0, s[10:11]
	s_mov_b32 m0, s50
	s_nop 0
	global_load_lds_dwordx4 v[166:167], off
	v_lshl_add_u64 v[166:167], v[236:237], 0, s[10:11]
	s_mov_b32 m0, s51
	s_nop 0
	global_load_lds_dwordx4 v[166:167], off
	s_waitcnt vmcnt(8)
	s_waitcnt lgkmcnt(0)
	s_setprio 1
	s_barrier
	v_mfma_f32_16x16x32_bf16 v[60:63], v[156:159], v[202:205], v[60:63]
	v_mfma_f32_16x16x32_bf16 v[56:59], v[174:177], v[202:205], v[56:59]
	v_mfma_f32_16x16x32_bf16 v[48:51], v[156:159], v[210:213], v[48:51]
	v_mfma_f32_16x16x32_bf16 v[40:43], v[174:177], v[210:213], v[40:43]
	v_mfma_f32_16x16x32_bf16 v[32:35], v[156:159], v[218:221], v[32:35]
	v_mfma_f32_16x16x32_bf16 v[24:27], v[174:177], v[218:221], v[24:27]
	v_mfma_f32_16x16x32_bf16 v[16:19], v[156:159], v[226:229], v[16:19]
	v_mfma_f32_16x16x32_bf16 v[8:11], v[174:177], v[226:229], v[8:11]
	v_mfma_f32_16x16x32_bf16 v[60:63], v[160:163], v[206:209], v[60:63]
	v_mfma_f32_16x16x32_bf16 v[56:59], v[182:185], v[206:209], v[56:59]
	v_mfma_f32_16x16x32_bf16 v[48:51], v[160:163], v[214:217], v[48:51]
	v_mfma_f32_16x16x32_bf16 v[40:43], v[182:185], v[214:217], v[40:43]
	v_mfma_f32_16x16x32_bf16 v[32:35], v[160:163], v[222:225], v[32:35]
	v_mfma_f32_16x16x32_bf16 v[24:27], v[182:185], v[222:225], v[24:27]
	v_mfma_f32_16x16x32_bf16 v[16:19], v[160:163], v[230:233], v[16:19]
	v_mfma_f32_16x16x32_bf16 v[8:11], v[182:185], v[230:233], v[8:11]
	v_mfma_f32_16x16x32_bf16 v[52:55], v[186:189], v[202:205], v[52:55]
	v_mfma_f32_16x16x32_bf16 v[44:47], v[194:197], v[202:205], v[44:47]
	v_mfma_f32_16x16x32_bf16 v[36:39], v[186:189], v[210:213], v[36:39]
	v_mfma_f32_16x16x32_bf16 v[28:31], v[194:197], v[210:213], v[28:31]
	v_mfma_f32_16x16x32_bf16 v[20:23], v[186:189], v[218:221], v[20:23]
	v_mfma_f32_16x16x32_bf16 v[12:15], v[194:197], v[218:221], v[12:15]
	v_mfma_f32_16x16x32_bf16 v[4:7], v[186:189], v[226:229], v[4:7]
	v_mfma_f32_16x16x32_bf16 v[0:3], v[194:197], v[226:229], v[0:3]
	v_mfma_f32_16x16x32_bf16 v[52:55], v[190:193], v[206:209], v[52:55]
	v_mfma_f32_16x16x32_bf16 v[44:47], v[198:201], v[206:209], v[44:47]
	v_mfma_f32_16x16x32_bf16 v[36:39], v[190:193], v[214:217], v[36:39]
	v_mfma_f32_16x16x32_bf16 v[28:31], v[198:201], v[214:217], v[28:31]
	v_mfma_f32_16x16x32_bf16 v[20:23], v[190:193], v[222:225], v[20:23]
	v_mfma_f32_16x16x32_bf16 v[12:15], v[198:201], v[222:225], v[12:15]
	v_mfma_f32_16x16x32_bf16 v[4:7], v[190:193], v[230:233], v[4:7]
	v_mfma_f32_16x16x32_bf16 v[0:3], v[198:201], v[230:233], v[0:3]
	s_barrier
	s_setprio 0
	s_add_i32 s65, s65, 2
	s_add_u32 s20, s20, 0x100
	s_addc_u32 s21, s21, 0
	s_add_u32 s39, s39, 0x100
	s_addc_u32 s64, s64, 0
	s_cmp_gt_u32 s65, 13
	s_cbranch_scc0 .LBB0_296
.Lpeel_exit_up:
	s_and_b64 vcc, exec, s[12:13]
	s_cbranch_vccz .LBB0_299
	s_barrier
.LBB0_299:
	s_lshl_b32 s4, s35, 8
	s_lshl_b32 s22, s36, 8
	s_and_b32 s4, s4, 0xf00
	s_add_i32 s22, s22, s48
	s_or_b32 s4, s4, s49
	s_and_b32 s23, s22, 0x1c0
	s_lshr_b32 s20, s4, 6
	s_lshl_b32 s4, s35, 5
	v_or_b32_e32 v156, s23, v172
	s_and_b32 s21, s4, 0xfffffe00
	v_or_b32_e32 v156, s21, v156
	v_lshl_or_b32 v156, v156, 6, s20
	v_ashrrev_i32_e32 v157, 31, v156
	v_cvt_pk_bf16_f32 v124, v124, v125
	v_cvt_pk_bf16_f32 v125, v126, v127
	v_cvt_pk_bf16_f32 v126, v120, v121
	v_lshlrev_b64 v[120:121], 8, v[156:157]
	s_lshr_b32 s4, s22, 2
	v_lshl_add_u64 v[120:121], s[8:9], 0, v[120:121]
	s_and_b32 s4, s4, 0x1fffff80
	v_lshl_add_u64 v[120:121], v[120:121], 0, s[4:5]
	v_lshl_add_u64 v[120:121], v[120:121], 0, v[142:143]
	v_cvt_pk_bf16_f32 v127, v122, v123
	global_store_dwordx4 v[120:121], v[124:127], off
	v_or_b32_e32 v120, 2, v156
	v_ashrrev_i32_e32 v121, 31, v120
	v_cvt_pk_bf16_f32 v116, v116, v117
	v_cvt_pk_bf16_f32 v117, v118, v119
	v_cvt_pk_bf16_f32 v118, v108, v109
	v_lshlrev_b64 v[108:109], 8, v[120:121]
	v_lshl_add_u64 v[108:109], s[8:9], 0, v[108:109]
	v_lshl_add_u64 v[108:109], v[108:109], 0, s[4:5]
	v_lshl_add_u64 v[108:109], v[108:109], 0, v[142:143]
	v_cvt_pk_bf16_f32 v119, v110, v111
	global_store_dwordx4 v[108:109], v[116:119], off
	v_or_b32_e32 v108, s23, v135
	v_or_b32_e32 v108, s21, v108
	v_lshl_or_b32 v116, v108, 6, s20
	v_ashrrev_i32_e32 v117, 31, v116
	v_cvt_pk_bf16_f32 v108, v112, v113
	v_cvt_pk_bf16_f32 v109, v114, v115
	v_cvt_pk_bf16_f32 v110, v104, v105
	v_lshlrev_b64 v[104:105], 8, v[116:117]
	v_lshl_add_u64 v[104:105], s[8:9], 0, v[104:105]
	v_lshl_add_u64 v[104:105], v[104:105], 0, s[4:5]
	v_lshl_add_u64 v[104:105], v[104:105], 0, v[142:143]
	v_cvt_pk_bf16_f32 v111, v106, v107
	global_store_dwordx4 v[104:105], v[108:111], off
	v_or_b32_e32 v104, 2, v116
	v_ashrrev_i32_e32 v105, 31, v104
	v_cvt_pk_bf16_f32 v100, v100, v101
	v_cvt_pk_bf16_f32 v101, v102, v103
	v_cvt_pk_bf16_f32 v102, v92, v93
	v_lshlrev_b64 v[92:93], 8, v[104:105]
	v_lshl_add_u64 v[92:93], s[8:9], 0, v[92:93]
	v_lshl_add_u64 v[92:93], v[92:93], 0, s[4:5]
	v_lshl_add_u64 v[92:93], v[92:93], 0, v[142:143]
	v_cvt_pk_bf16_f32 v103, v94, v95
	global_store_dwordx4 v[92:93], v[100:103], off
	v_or_b32_e32 v92, s23, v137
	v_or_b32_e32 v92, s21, v92
	v_lshl_or_b32 v100, v92, 6, s20
	v_ashrrev_i32_e32 v101, 31, v100
	v_cvt_pk_bf16_f32 v92, v96, v97
	v_cvt_pk_bf16_f32 v93, v98, v99
	v_cvt_pk_bf16_f32 v94, v88, v89
	v_lshlrev_b64 v[88:89], 8, v[100:101]
	v_lshl_add_u64 v[88:89], s[8:9], 0, v[88:89]
	v_lshl_add_u64 v[88:89], v[88:89], 0, s[4:5]
	v_lshl_add_u64 v[88:89], v[88:89], 0, v[142:143]
	v_cvt_pk_bf16_f32 v95, v90, v91
	global_store_dwordx4 v[88:89], v[92:95], off
	v_or_b32_e32 v88, 2, v100
	v_ashrrev_i32_e32 v89, 31, v88
	v_cvt_pk_bf16_f32 v84, v84, v85
	v_cvt_pk_bf16_f32 v85, v86, v87
	v_cvt_pk_bf16_f32 v86, v76, v77
	v_lshlrev_b64 v[76:77], 8, v[88:89]
	v_lshl_add_u64 v[76:77], s[8:9], 0, v[76:77]
	v_lshl_add_u64 v[76:77], v[76:77], 0, s[4:5]
	v_lshl_add_u64 v[76:77], v[76:77], 0, v[142:143]
	v_cvt_pk_bf16_f32 v87, v78, v79
	global_store_dwordx4 v[76:77], v[84:87], off
	v_or_b32_e32 v76, s23, v152
	v_or_b32_e32 v76, s21, v76
	v_lshl_or_b32 v84, v76, 6, s20
	v_ashrrev_i32_e32 v85, 31, v84
	v_cvt_pk_bf16_f32 v76, v80, v81
	v_cvt_pk_bf16_f32 v77, v82, v83
	v_cvt_pk_bf16_f32 v78, v72, v73
	v_lshlrev_b64 v[72:73], 8, v[84:85]
	v_lshl_add_u64 v[72:73], s[8:9], 0, v[72:73]
	v_lshl_add_u64 v[72:73], v[72:73], 0, s[4:5]
	v_lshl_add_u64 v[72:73], v[72:73], 0, v[142:143]
	v_cvt_pk_bf16_f32 v79, v74, v75
	global_store_dwordx4 v[72:73], v[76:79], off
	v_or_b32_e32 v72, 2, v84
	v_ashrrev_i32_e32 v73, 31, v72
	v_cvt_pk_bf16_f32 v68, v68, v69
	v_cvt_pk_bf16_f32 v69, v70, v71
	v_cvt_pk_bf16_f32 v70, v64, v65
	v_lshlrev_b64 v[64:65], 8, v[72:73]
	v_lshl_add_u64 v[64:65], s[8:9], 0, v[64:65]
	v_lshl_add_u64 v[64:65], v[64:65], 0, s[4:5]
	s_addk_i32 s22, 0x80
	v_lshl_add_u64 v[64:65], v[64:65], 0, v[142:143]
	s_and_b32 s23, s22, 0x1c0
	v_cvt_pk_bf16_f32 v71, v66, v67
	global_store_dwordx4 v[64:65], v[68:71], off
	v_or_b32_e32 v64, s23, v172
	v_or_b32_e32 v64, s21, v64
	v_lshl_or_b32 v64, v64, 6, s20
	v_ashrrev_i32_e32 v65, 31, v64
	v_cvt_pk_bf16_f32 v60, v60, v61
	v_cvt_pk_bf16_f32 v61, v62, v63
	v_cvt_pk_bf16_f32 v62, v56, v57
	v_lshlrev_b64 v[56:57], 8, v[64:65]
	s_lshr_b32 s4, s22, 2
	v_lshl_add_u64 v[56:57], s[8:9], 0, v[56:57]
	s_and_b32 s4, s4, 0x1fffff80
	v_lshl_add_u64 v[56:57], v[56:57], 0, s[4:5]
	v_lshl_add_u64 v[56:57], v[56:57], 0, v[142:143]
	v_cvt_pk_bf16_f32 v63, v58, v59
	global_store_dwordx4 v[56:57], v[60:63], off
	v_or_b32_e32 v56, 2, v64
	v_ashrrev_i32_e32 v57, 31, v56
	v_cvt_pk_bf16_f32 v52, v52, v53
	v_cvt_pk_bf16_f32 v53, v54, v55
	v_cvt_pk_bf16_f32 v54, v44, v45
	v_lshlrev_b64 v[44:45], 8, v[56:57]
	v_lshl_add_u64 v[44:45], s[8:9], 0, v[44:45]
	v_lshl_add_u64 v[44:45], v[44:45], 0, s[4:5]
	v_lshl_add_u64 v[44:45], v[44:45], 0, v[142:143]
	v_cvt_pk_bf16_f32 v55, v46, v47
	global_store_dwordx4 v[44:45], v[52:55], off
	v_or_b32_e32 v44, s23, v135
	v_or_b32_e32 v44, s21, v44
	v_lshl_or_b32 v52, v44, 6, s20
	v_ashrrev_i32_e32 v53, 31, v52
	v_cvt_pk_bf16_f32 v44, v48, v49
	v_cvt_pk_bf16_f32 v45, v50, v51
	v_cvt_pk_bf16_f32 v46, v40, v41
	v_lshlrev_b64 v[40:41], 8, v[52:53]
	v_lshl_add_u64 v[40:41], s[8:9], 0, v[40:41]
	v_lshl_add_u64 v[40:41], v[40:41], 0, s[4:5]
	v_lshl_add_u64 v[40:41], v[40:41], 0, v[142:143]
	v_cvt_pk_bf16_f32 v47, v42, v43
	global_store_dwordx4 v[40:41], v[44:47], off
	v_or_b32_e32 v40, 2, v52
	v_ashrrev_i32_e32 v41, 31, v40
	v_cvt_pk_bf16_f32 v36, v36, v37
	v_cvt_pk_bf16_f32 v37, v38, v39
	v_cvt_pk_bf16_f32 v38, v28, v29
	v_lshlrev_b64 v[28:29], 8, v[40:41]
	v_lshl_add_u64 v[28:29], s[8:9], 0, v[28:29]
	v_lshl_add_u64 v[28:29], v[28:29], 0, s[4:5]
	v_lshl_add_u64 v[28:29], v[28:29], 0, v[142:143]
	v_cvt_pk_bf16_f32 v39, v30, v31
	global_store_dwordx4 v[28:29], v[36:39], off
	v_or_b32_e32 v28, s23, v137
	v_or_b32_e32 v28, s21, v28
	v_lshl_or_b32 v36, v28, 6, s20
	v_ashrrev_i32_e32 v37, 31, v36
	v_cvt_pk_bf16_f32 v28, v32, v33
	v_cvt_pk_bf16_f32 v29, v34, v35
	v_cvt_pk_bf16_f32 v30, v24, v25
	v_lshlrev_b64 v[24:25], 8, v[36:37]
	v_lshl_add_u64 v[24:25], s[8:9], 0, v[24:25]
	v_lshl_add_u64 v[24:25], v[24:25], 0, s[4:5]
	v_lshl_add_u64 v[24:25], v[24:25], 0, v[142:143]
	v_cvt_pk_bf16_f32 v31, v26, v27
	global_store_dwordx4 v[24:25], v[28:31], off
	v_or_b32_e32 v24, 2, v36
	v_ashrrev_i32_e32 v25, 31, v24
	v_cvt_pk_bf16_f32 v20, v20, v21
	v_cvt_pk_bf16_f32 v21, v22, v23
	v_cvt_pk_bf16_f32 v22, v12, v13
	v_lshlrev_b64 v[12:13], 8, v[24:25]
	v_lshl_add_u64 v[12:13], s[8:9], 0, v[12:13]
	v_lshl_add_u64 v[12:13], v[12:13], 0, s[4:5]
	v_lshl_add_u64 v[12:13], v[12:13], 0, v[142:143]
	v_cvt_pk_bf16_f32 v23, v14, v15
	global_store_dwordx4 v[12:13], v[20:23], off
	v_or_b32_e32 v12, s23, v152
	v_or_b32_e32 v12, s21, v12
	v_lshl_or_b32 v20, v12, 6, s20
	v_ashrrev_i32_e32 v21, 31, v20
	v_cvt_pk_bf16_f32 v12, v16, v17
	v_cvt_pk_bf16_f32 v13, v18, v19
	v_cvt_pk_bf16_f32 v14, v8, v9
	v_lshlrev_b64 v[8:9], 8, v[20:21]
	v_lshl_add_u64 v[8:9], s[8:9], 0, v[8:9]
	v_lshl_add_u64 v[8:9], v[8:9], 0, s[4:5]
	v_lshl_add_u64 v[8:9], v[8:9], 0, v[142:143]
	v_cvt_pk_bf16_f32 v15, v10, v11
	global_store_dwordx4 v[8:9], v[12:15], off
	v_or_b32_e32 v8, 2, v20
	v_ashrrev_i32_e32 v9, 31, v8
	v_cvt_pk_bf16_f32 v4, v4, v5
	v_cvt_pk_bf16_f32 v5, v6, v7
	v_cvt_pk_bf16_f32 v6, v0, v1
	v_lshlrev_b64 v[0:1], 8, v[8:9]
	v_lshl_add_u64 v[0:1], s[8:9], 0, v[0:1]
	v_lshl_add_u64 v[0:1], v[0:1], 0, s[4:5]
	v_lshl_add_u64 v[0:1], v[0:1], 0, v[142:143]
	s_andn2_b64 vcc, exec, s[2:3]
	s_mov_b64 s[2:3], -1
	v_cvt_pk_bf16_f32 v7, v2, v3
	global_store_dwordx4 v[0:1], v[4:7], off
	s_cbranch_vccnz .LBB0_292
	s_andn2_b64 vcc, exec, s[6:7]
	s_cbranch_vccnz .LBB0_291
	s_barrier
	s_branch .LBB0_291

.LBB0_311:
	s_ashr_i32 s13, s12, 31
	s_lshl_b64 s[14:15], s[12:13], 19
	s_add_u32 s14, s26, s14
	s_addc_u32 s15, s27, s15
	s_and_b64 s[16:17], s[2:3], exec
	s_cselect_b32 s13, s15, s21
	s_cselect_b32 s39, s14, s20
	s_ashr_i32 s11, s10, 31
	s_lshl_b64 s[16:17], s[10:11], 19
	s_add_u32 s16, s28, s16
	s_addc_u32 s17, s29, s17
	s_and_b64 s[24:25], s[2:3], exec
	s_cselect_b32 s11, s17, s23
	s_cselect_b32 s60, s16, s22
	s_add_u32 s20, s20, 0x40080
	s_addc_u32 s21, s21, 0
	s_add_u32 s61, s22, 0x100
	s_addc_u32 s62, s23, 0
	s_mov_b32 s63, -2
	ds_read_b128 v[154:157], v150
	ds_read_b128 v[158:161], v150 offset:1024
	ds_read_b128 v[166:169], v150 offset:2048
	ds_read_b128 v[170:173], v150 offset:3072
	ds_read_b128 v[174:177], v151
	ds_read_b128 v[182:185], v151 offset:1024
	ds_read_b128 v[186:189], v151 offset:2048
	ds_read_b128 v[190:193], v151 offset:3072
	s_add_u32 s22, s20, 0xfffc0080
	s_addc_u32 s23, s21, -1
	s_cmp_eq_u32 s63, 12
	s_cselect_b32 s25, s13, s23
	s_cselect_b32 s24, s39, s22
	s_cselect_b32 s23, s11, s62
	s_cselect_b32 s22, s60, s61
	v_lshl_add_u64 v[146:147], s[20:21], 0, v[138:139]
	s_add_i32 m0, s19, 0xc000
	ds_read_b128 v[194:197], v152
	ds_read_b128 v[198:201], v152 offset:1024
	ds_read_b128 v[202:205], v152 offset:2048
	ds_read_b128 v[206:209], v152 offset:3072
	ds_read_b128 v[210:213], v152 offset:4096
	ds_read_b128 v[214:217], v152 offset:5120
	ds_read_b128 v[218:221], v152 offset:6144
	ds_read_b128 v[222:225], v152 offset:7168
	global_load_lds_dwordx4 v[146:147], off
	v_lshl_add_u64 v[146:147], s[20:21], 0, v[140:141]
	s_add_i32 m0, s19, 0xe000
	s_nop 0
	global_load_lds_dwordx4 v[146:147], off
	s_waitcnt vmcnt(8)
	s_waitcnt lgkmcnt(0)
	s_setprio 1
	s_barrier
	v_mfma_f32_16x16x32_bf16 v[124:127], v[154:157], v[194:197], 0
	v_mfma_f32_16x16x32_bf16 v[120:123], v[166:169], v[194:197], 0
	v_mfma_f32_16x16x32_bf16 v[116:119], v[154:157], v[202:205], 0
	v_mfma_f32_16x16x32_bf16 v[108:111], v[166:169], v[202:205], 0
	v_mfma_f32_16x16x32_bf16 v[100:103], v[154:157], v[210:213], 0
	v_mfma_f32_16x16x32_bf16 v[92:95], v[166:169], v[210:213], 0
	v_mfma_f32_16x16x32_bf16 v[84:87], v[154:157], v[218:221], 0
	v_mfma_f32_16x16x32_bf16 v[76:79], v[166:169], v[218:221], 0
	v_mfma_f32_16x16x32_bf16 v[124:127], v[158:161], v[198:201], v[124:127]
	v_mfma_f32_16x16x32_bf16 v[120:123], v[170:173], v[198:201], v[120:123]
	v_mfma_f32_16x16x32_bf16 v[116:119], v[158:161], v[206:209], v[116:119]
	v_mfma_f32_16x16x32_bf16 v[108:111], v[170:173], v[206:209], v[108:111]
	v_mfma_f32_16x16x32_bf16 v[100:103], v[158:161], v[214:217], v[100:103]
	v_mfma_f32_16x16x32_bf16 v[92:95], v[170:173], v[214:217], v[92:95]
	v_mfma_f32_16x16x32_bf16 v[84:87], v[158:161], v[222:225], v[84:87]
	v_mfma_f32_16x16x32_bf16 v[76:79], v[170:173], v[222:225], v[76:79]
	v_mfma_f32_16x16x32_bf16 v[112:115], v[174:177], v[194:197], 0
	v_mfma_f32_16x16x32_bf16 v[104:107], v[186:189], v[194:197], 0
	v_mfma_f32_16x16x32_bf16 v[96:99], v[174:177], v[202:205], 0
	v_mfma_f32_16x16x32_bf16 v[88:91], v[186:189], v[202:205], 0
	v_mfma_f32_16x16x32_bf16 v[80:83], v[174:177], v[210:213], 0
	v_mfma_f32_16x16x32_bf16 v[72:75], v[186:189], v[210:213], 0
	v_mfma_f32_16x16x32_bf16 v[68:71], v[174:177], v[218:221], 0
	v_mfma_f32_16x16x32_bf16 v[64:67], v[186:189], v[218:221], 0
	v_mfma_f32_16x16x32_bf16 v[112:115], v[182:185], v[198:201], v[112:115]
	v_mfma_f32_16x16x32_bf16 v[104:107], v[190:193], v[198:201], v[104:107]
	v_mfma_f32_16x16x32_bf16 v[96:99], v[182:185], v[206:209], v[96:99]
	v_mfma_f32_16x16x32_bf16 v[88:91], v[190:193], v[206:209], v[88:91]
	v_mfma_f32_16x16x32_bf16 v[80:83], v[182:185], v[214:217], v[80:83]
	v_mfma_f32_16x16x32_bf16 v[72:75], v[190:193], v[214:217], v[72:75]
	v_mfma_f32_16x16x32_bf16 v[68:71], v[182:185], v[222:225], v[68:71]
	v_mfma_f32_16x16x32_bf16 v[64:67], v[190:193], v[222:225], v[64:67]
	s_barrier
	s_setprio 0
	s_add_i32 s64, s51, s31
	v_lshl_add_u64 v[146:147], s[22:23], 0, v[130:131]
	s_mov_b32 m0, s64
	ds_read_b128 v[194:197], v152 offset:16384
	ds_read_b128 v[198:201], v152 offset:17408
	ds_read_b128 v[202:205], v152 offset:18432
	ds_read_b128 v[206:209], v152 offset:19456
	ds_read_b128 v[210:213], v152 offset:20480
	ds_read_b128 v[214:217], v152 offset:21504
	ds_read_b128 v[218:221], v152 offset:22528
	ds_read_b128 v[222:225], v152 offset:23552
	global_load_lds_dwordx4 v[146:147], off
	s_add_i32 m0, s64, 0x2000
	s_add_u32 s64, s22, 0x40000
	v_lshl_add_u64 v[162:163], s[22:23], 0, v[134:135]
	s_addc_u32 s65, s23, 0
	s_add_i32 s66, s52, s31
	global_load_lds_dwordx4 v[162:163], off
	v_lshl_add_u64 v[178:179], s[64:65], 0, v[130:131]
	s_mov_b32 m0, s66
	v_lshl_add_u64 v[226:227], s[24:25], 0, v[132:133]
	global_load_lds_dwordx4 v[178:179], off
	v_lshl_add_u64 v[178:179], s[64:65], 0, v[134:135]
	s_add_i32 m0, s66, 0x2000
	s_nop 0
	global_load_lds_dwordx4 v[178:179], off
	v_lshl_add_u64 v[178:179], s[24:25], 0, v[128:129]
	s_mov_b32 m0, s19
	s_nop 0
	global_load_lds_dwordx4 v[178:179], off
	s_mov_b32 m0, s35
	s_nop 0
	global_load_lds_dwordx4 v[226:227], off
	s_waitcnt vmcnt(8)
	s_waitcnt lgkmcnt(0)
	s_setprio 1
	s_barrier
	v_mfma_f32_16x16x32_bf16 v[60:63], v[154:157], v[194:197], 0
	v_mfma_f32_16x16x32_bf16 v[56:59], v[166:169], v[194:197], 0
	v_mfma_f32_16x16x32_bf16 v[52:55], v[154:157], v[202:205], 0
	v_mfma_f32_16x16x32_bf16 v[44:47], v[166:169], v[202:205], 0
	v_mfma_f32_16x16x32_bf16 v[36:39], v[154:157], v[210:213], 0
	v_mfma_f32_16x16x32_bf16 v[28:31], v[166:169], v[210:213], 0
	v_mfma_f32_16x16x32_bf16 v[20:23], v[154:157], v[218:221], 0
	v_mfma_f32_16x16x32_bf16 v[12:15], v[166:169], v[218:221], 0
	v_mfma_f32_16x16x32_bf16 v[60:63], v[158:161], v[198:201], v[60:63]
	v_mfma_f32_16x16x32_bf16 v[56:59], v[170:173], v[198:201], v[56:59]
	v_mfma_f32_16x16x32_bf16 v[52:55], v[158:161], v[206:209], v[52:55]
	v_mfma_f32_16x16x32_bf16 v[44:47], v[170:173], v[206:209], v[44:47]
	v_mfma_f32_16x16x32_bf16 v[36:39], v[158:161], v[214:217], v[36:39]
	v_mfma_f32_16x16x32_bf16 v[28:31], v[170:173], v[214:217], v[28:31]
	v_mfma_f32_16x16x32_bf16 v[20:23], v[158:161], v[222:225], v[20:23]
	v_mfma_f32_16x16x32_bf16 v[12:15], v[170:173], v[222:225], v[12:15]
	v_mfma_f32_16x16x32_bf16 v[48:51], v[174:177], v[194:197], 0
	v_mfma_f32_16x16x32_bf16 v[40:43], v[186:189], v[194:197], 0
	v_mfma_f32_16x16x32_bf16 v[32:35], v[174:177], v[202:205], 0
	v_mfma_f32_16x16x32_bf16 v[24:27], v[186:189], v[202:205], 0
	v_mfma_f32_16x16x32_bf16 v[16:19], v[174:177], v[210:213], 0
	v_mfma_f32_16x16x32_bf16 v[8:11], v[186:189], v[210:213], 0
	v_mfma_f32_16x16x32_bf16 v[4:7], v[174:177], v[218:221], 0
	v_mfma_f32_16x16x32_bf16 v[0:3], v[186:189], v[218:221], 0
	v_mfma_f32_16x16x32_bf16 v[48:51], v[182:185], v[198:201], v[48:51]
	v_mfma_f32_16x16x32_bf16 v[40:43], v[190:193], v[198:201], v[40:43]
	v_mfma_f32_16x16x32_bf16 v[32:35], v[182:185], v[206:209], v[32:35]
	v_mfma_f32_16x16x32_bf16 v[24:27], v[190:193], v[206:209], v[24:27]
	v_mfma_f32_16x16x32_bf16 v[16:19], v[182:185], v[214:217], v[16:19]
	v_mfma_f32_16x16x32_bf16 v[8:11], v[190:193], v[214:217], v[8:11]
	v_mfma_f32_16x16x32_bf16 v[4:7], v[182:185], v[222:225], v[4:7]
	v_mfma_f32_16x16x32_bf16 v[0:3], v[190:193], v[222:225], v[0:3]
	s_barrier
	s_setprio 0
	s_add_i32 s64, 0, 0x18000
	v_add_u32_e32 v153, s64, v149
	s_add_i32 s65, 0, 0x1c000
	ds_read_b128 v[154:157], v153
	ds_read_b128 v[158:161], v153 offset:1024
	ds_read_b128 v[166:169], v153 offset:2048
	ds_read_b128 v[170:173], v153 offset:3072
	v_add_u32_e32 v153, s65, v149
	ds_read_b128 v[174:177], v153
	ds_read_b128 v[182:185], v153 offset:1024
	ds_read_b128 v[186:189], v153 offset:2048
	ds_read_b128 v[190:193], v153 offset:3072
	s_add_u32 s24, s24, 0x40000
	s_addc_u32 s25, s25, 0
	s_mov_b32 m0, s36
	v_lshl_add_u64 v[228:229], s[24:25], 0, v[128:129]
	ds_read_b128 v[194:197], v152 offset:32768
	ds_read_b128 v[198:201], v152 offset:33792
	ds_read_b128 v[202:205], v152 offset:34816
	ds_read_b128 v[206:209], v152 offset:35840
	ds_read_b128 v[210:213], v152 offset:36864
	ds_read_b128 v[214:217], v152 offset:37888
	ds_read_b128 v[218:221], v152 offset:38912
	ds_read_b128 v[222:225], v152 offset:39936
	global_load_lds_dwordx4 v[228:229], off
	v_lshl_add_u64 v[228:229], s[24:25], 0, v[132:133]
	s_mov_b32 m0, s37
	s_nop 0
	global_load_lds_dwordx4 v[228:229], off
	s_waitcnt vmcnt(8)
	s_waitcnt lgkmcnt(0)
	s_setprio 1
	s_barrier
	v_mfma_f32_16x16x32_bf16 v[124:127], v[154:157], v[194:197], v[124:127]
	v_mfma_f32_16x16x32_bf16 v[120:123], v[166:169], v[194:197], v[120:123]
	v_mfma_f32_16x16x32_bf16 v[116:119], v[154:157], v[202:205], v[116:119]
	v_mfma_f32_16x16x32_bf16 v[108:111], v[166:169], v[202:205], v[108:111]
	v_mfma_f32_16x16x32_bf16 v[100:103], v[154:157], v[210:213], v[100:103]
	v_mfma_f32_16x16x32_bf16 v[92:95], v[166:169], v[210:213], v[92:95]
	v_mfma_f32_16x16x32_bf16 v[84:87], v[154:157], v[218:221], v[84:87]
	v_mfma_f32_16x16x32_bf16 v[76:79], v[166:169], v[218:221], v[76:79]
	v_mfma_f32_16x16x32_bf16 v[124:127], v[158:161], v[198:201], v[124:127]
	v_mfma_f32_16x16x32_bf16 v[120:123], v[170:173], v[198:201], v[120:123]
	v_mfma_f32_16x16x32_bf16 v[116:119], v[158:161], v[206:209], v[116:119]
	v_mfma_f32_16x16x32_bf16 v[108:111], v[170:173], v[206:209], v[108:111]
	v_mfma_f32_16x16x32_bf16 v[100:103], v[158:161], v[214:217], v[100:103]
	v_mfma_f32_16x16x32_bf16 v[92:95], v[170:173], v[214:217], v[92:95]
	v_mfma_f32_16x16x32_bf16 v[84:87], v[158:161], v[222:225], v[84:87]
	v_mfma_f32_16x16x32_bf16 v[76:79], v[170:173], v[222:225], v[76:79]
	v_mfma_f32_16x16x32_bf16 v[112:115], v[174:177], v[194:197], v[112:115]
	v_mfma_f32_16x16x32_bf16 v[104:107], v[186:189], v[194:197], v[104:107]
	v_mfma_f32_16x16x32_bf16 v[96:99], v[174:177], v[202:205], v[96:99]
	v_mfma_f32_16x16x32_bf16 v[88:91], v[186:189], v[202:205], v[88:91]
	v_mfma_f32_16x16x32_bf16 v[80:83], v[174:177], v[210:213], v[80:83]
	v_mfma_f32_16x16x32_bf16 v[72:75], v[186:189], v[210:213], v[72:75]
	v_mfma_f32_16x16x32_bf16 v[68:71], v[174:177], v[218:221], v[68:71]
	v_mfma_f32_16x16x32_bf16 v[64:67], v[186:189], v[218:221], v[64:67]
	v_mfma_f32_16x16x32_bf16 v[112:115], v[182:185], v[198:201], v[112:115]
	v_mfma_f32_16x16x32_bf16 v[104:107], v[190:193], v[198:201], v[104:107]
	v_mfma_f32_16x16x32_bf16 v[96:99], v[182:185], v[206:209], v[96:99]
	v_mfma_f32_16x16x32_bf16 v[88:91], v[190:193], v[206:209], v[88:91]
	v_mfma_f32_16x16x32_bf16 v[80:83], v[182:185], v[214:217], v[80:83]
	v_mfma_f32_16x16x32_bf16 v[72:75], v[190:193], v[214:217], v[72:75]
	v_mfma_f32_16x16x32_bf16 v[68:71], v[182:185], v[222:225], v[68:71]
	v_mfma_f32_16x16x32_bf16 v[64:67], v[190:193], v[222:225], v[64:67]
	s_barrier
	s_setprio 0
	s_add_i32 s24, s64, s31
	v_lshl_add_u64 v[146:147], v[146:147], 0, s[6:7]
	s_mov_b32 m0, s24
	ds_read_b128 v[194:197], v152 offset:49152
	ds_read_b128 v[198:201], v152 offset:50176
	ds_read_b128 v[202:205], v152 offset:51200
	ds_read_b128 v[206:209], v152 offset:52224
	ds_read_b128 v[210:213], v152 offset:53248
	ds_read_b128 v[214:217], v152 offset:54272
	ds_read_b128 v[218:221], v152 offset:55296
	ds_read_b128 v[222:225], v152 offset:56320
	global_load_lds_dwordx4 v[146:147], off
	s_add_i32 m0, s24, 0x2000
	s_add_u32 s22, s22, 0x40080
	v_lshl_add_u64 v[146:147], v[162:163], 0, s[6:7]
	s_addc_u32 s23, s23, 0
	s_add_i32 s24, s65, s31
	global_load_lds_dwordx4 v[146:147], off
	v_lshl_add_u64 v[146:147], s[22:23], 0, v[130:131]
	s_mov_b32 m0, s24
	s_nop 0
	global_load_lds_dwordx4 v[146:147], off
	v_lshl_add_u64 v[146:147], s[22:23], 0, v[134:135]
	s_add_i32 m0, s24, 0x2000
	s_nop 0
	global_load_lds_dwordx4 v[146:147], off
	v_lshl_add_u64 v[146:147], v[178:179], 0, s[6:7]
	s_mov_b32 m0, s45
	s_nop 0
	global_load_lds_dwordx4 v[146:147], off
	v_lshl_add_u64 v[146:147], v[226:227], 0, s[6:7]
	s_mov_b32 m0, s48
	s_nop 0
	global_load_lds_dwordx4 v[146:147], off
	s_waitcnt vmcnt(8)
	s_waitcnt lgkmcnt(0)
	s_setprio 1
	s_barrier
	v_mfma_f32_16x16x32_bf16 v[60:63], v[154:157], v[194:197], v[60:63]
	v_mfma_f32_16x16x32_bf16 v[56:59], v[166:169], v[194:197], v[56:59]
	v_mfma_f32_16x16x32_bf16 v[52:55], v[154:157], v[202:205], v[52:55]
	v_mfma_f32_16x16x32_bf16 v[44:47], v[166:169], v[202:205], v[44:47]
	v_mfma_f32_16x16x32_bf16 v[36:39], v[154:157], v[210:213], v[36:39]
	v_mfma_f32_16x16x32_bf16 v[28:31], v[166:169], v[210:213], v[28:31]
	v_mfma_f32_16x16x32_bf16 v[20:23], v[154:157], v[218:221], v[20:23]
	v_mfma_f32_16x16x32_bf16 v[12:15], v[166:169], v[218:221], v[12:15]
	v_mfma_f32_16x16x32_bf16 v[60:63], v[158:161], v[198:201], v[60:63]
	v_mfma_f32_16x16x32_bf16 v[56:59], v[170:173], v[198:201], v[56:59]
	v_mfma_f32_16x16x32_bf16 v[52:55], v[158:161], v[206:209], v[52:55]
	v_mfma_f32_16x16x32_bf16 v[44:47], v[170:173], v[206:209], v[44:47]
	v_mfma_f32_16x16x32_bf16 v[36:39], v[158:161], v[214:217], v[36:39]
	v_mfma_f32_16x16x32_bf16 v[28:31], v[170:173], v[214:217], v[28:31]
	v_mfma_f32_16x16x32_bf16 v[20:23], v[158:161], v[222:225], v[20:23]
	v_mfma_f32_16x16x32_bf16 v[12:15], v[170:173], v[222:225], v[12:15]
	v_mfma_f32_16x16x32_bf16 v[48:51], v[174:177], v[194:197], v[48:51]
	v_mfma_f32_16x16x32_bf16 v[40:43], v[186:189], v[194:197], v[40:43]
	v_mfma_f32_16x16x32_bf16 v[32:35], v[174:177], v[202:205], v[32:35]
	v_mfma_f32_16x16x32_bf16 v[24:27], v[186:189], v[202:205], v[24:27]
	v_mfma_f32_16x16x32_bf16 v[16:19], v[174:177], v[210:213], v[16:19]
	v_mfma_f32_16x16x32_bf16 v[8:11], v[186:189], v[210:213], v[8:11]
	v_mfma_f32_16x16x32_bf16 v[4:7], v[174:177], v[218:221], v[4:7]
	v_mfma_f32_16x16x32_bf16 v[0:3], v[186:189], v[218:221], v[0:3]
	v_mfma_f32_16x16x32_bf16 v[48:51], v[182:185], v[198:201], v[48:51]
	v_mfma_f32_16x16x32_bf16 v[40:43], v[190:193], v[198:201], v[40:43]
	v_mfma_f32_16x16x32_bf16 v[32:35], v[182:185], v[206:209], v[32:35]
	v_mfma_f32_16x16x32_bf16 v[24:27], v[190:193], v[206:209], v[24:27]
	v_mfma_f32_16x16x32_bf16 v[16:19], v[182:185], v[214:217], v[16:19]
	v_mfma_f32_16x16x32_bf16 v[8:11], v[190:193], v[214:217], v[8:11]
	v_mfma_f32_16x16x32_bf16 v[4:7], v[182:185], v[222:225], v[4:7]
	v_mfma_f32_16x16x32_bf16 v[0:3], v[190:193], v[222:225], v[0:3]
	s_barrier
	s_setprio 0
	s_add_i32 s63, s63, 2
	s_add_u32 s20, s20, 0x100
	s_addc_u32 s21, s21, 0
	s_add_u32 s61, s61, 0x100
	s_addc_u32 s62, s62, 0
	s_cmp_gt_u32 s63, 13
	s_cbranch_scc0 .LBB0_312
	s_branch .Lpeel_exit_v
.LBB0_312:
	ds_read_b128 v[154:157], v150
	ds_read_b128 v[158:161], v150 offset:1024
	ds_read_b128 v[166:169], v150 offset:2048
	ds_read_b128 v[170:173], v150 offset:3072
	ds_read_b128 v[174:177], v151
	ds_read_b128 v[182:185], v151 offset:1024
	ds_read_b128 v[186:189], v151 offset:2048
	ds_read_b128 v[190:193], v151 offset:3072
	s_add_u32 s22, s20, 0xfffc0080
	s_addc_u32 s23, s21, -1
	s_cmp_eq_u32 s63, 12
	s_cselect_b32 s25, s13, s23
	s_cselect_b32 s24, s39, s22
	s_cselect_b32 s23, s11, s62
	s_cselect_b32 s22, s60, s61
	v_lshl_add_u64 v[146:147], s[20:21], 0, v[138:139]
	s_add_i32 m0, s19, 0xc000
	ds_read_b128 v[194:197], v152
	ds_read_b128 v[198:201], v152 offset:1024
	ds_read_b128 v[202:205], v152 offset:2048
	ds_read_b128 v[206:209], v152 offset:3072
	ds_read_b128 v[210:213], v152 offset:4096
	ds_read_b128 v[214:217], v152 offset:5120
	ds_read_b128 v[218:221], v152 offset:6144
	ds_read_b128 v[222:225], v152 offset:7168
	global_load_lds_dwordx4 v[146:147], off
	v_lshl_add_u64 v[146:147], s[20:21], 0, v[140:141]
	s_add_i32 m0, s19, 0xe000
	s_nop 0
	global_load_lds_dwordx4 v[146:147], off
	s_waitcnt vmcnt(8)
	s_waitcnt lgkmcnt(0)
	s_setprio 1
	s_barrier
	v_mfma_f32_16x16x32_bf16 v[124:127], v[154:157], v[194:197], v[124:127]
	v_mfma_f32_16x16x32_bf16 v[120:123], v[166:169], v[194:197], v[120:123]
	v_mfma_f32_16x16x32_bf16 v[116:119], v[154:157], v[202:205], v[116:119]
	v_mfma_f32_16x16x32_bf16 v[108:111], v[166:169], v[202:205], v[108:111]
	v_mfma_f32_16x16x32_bf16 v[100:103], v[154:157], v[210:213], v[100:103]
	v_mfma_f32_16x16x32_bf16 v[92:95], v[166:169], v[210:213], v[92:95]
	v_mfma_f32_16x16x32_bf16 v[84:87], v[154:157], v[218:221], v[84:87]
	v_mfma_f32_16x16x32_bf16 v[76:79], v[166:169], v[218:221], v[76:79]
	v_mfma_f32_16x16x32_bf16 v[124:127], v[158:161], v[198:201], v[124:127]
	v_mfma_f32_16x16x32_bf16 v[120:123], v[170:173], v[198:201], v[120:123]
	v_mfma_f32_16x16x32_bf16 v[116:119], v[158:161], v[206:209], v[116:119]
	v_mfma_f32_16x16x32_bf16 v[108:111], v[170:173], v[206:209], v[108:111]
	v_mfma_f32_16x16x32_bf16 v[100:103], v[158:161], v[214:217], v[100:103]
	v_mfma_f32_16x16x32_bf16 v[92:95], v[170:173], v[214:217], v[92:95]
	v_mfma_f32_16x16x32_bf16 v[84:87], v[158:161], v[222:225], v[84:87]
	v_mfma_f32_16x16x32_bf16 v[76:79], v[170:173], v[222:225], v[76:79]
	v_mfma_f32_16x16x32_bf16 v[112:115], v[174:177], v[194:197], v[112:115]
	v_mfma_f32_16x16x32_bf16 v[104:107], v[186:189], v[194:197], v[104:107]
	v_mfma_f32_16x16x32_bf16 v[96:99], v[174:177], v[202:205], v[96:99]
	v_mfma_f32_16x16x32_bf16 v[88:91], v[186:189], v[202:205], v[88:91]
	v_mfma_f32_16x16x32_bf16 v[80:83], v[174:177], v[210:213], v[80:83]
	v_mfma_f32_16x16x32_bf16 v[72:75], v[186:189], v[210:213], v[72:75]
	v_mfma_f32_16x16x32_bf16 v[68:71], v[174:177], v[218:221], v[68:71]
	v_mfma_f32_16x16x32_bf16 v[64:67], v[186:189], v[218:221], v[64:67]
	v_mfma_f32_16x16x32_bf16 v[112:115], v[182:185], v[198:201], v[112:115]
	v_mfma_f32_16x16x32_bf16 v[104:107], v[190:193], v[198:201], v[104:107]
	v_mfma_f32_16x16x32_bf16 v[96:99], v[182:185], v[206:209], v[96:99]
	v_mfma_f32_16x16x32_bf16 v[88:91], v[190:193], v[206:209], v[88:91]
	v_mfma_f32_16x16x32_bf16 v[80:83], v[182:185], v[214:217], v[80:83]
	v_mfma_f32_16x16x32_bf16 v[72:75], v[190:193], v[214:217], v[72:75]
	v_mfma_f32_16x16x32_bf16 v[68:71], v[182:185], v[222:225], v[68:71]
	v_mfma_f32_16x16x32_bf16 v[64:67], v[190:193], v[222:225], v[64:67]
	s_barrier
	s_setprio 0
	s_add_i32 s64, s51, s31
	v_lshl_add_u64 v[146:147], s[22:23], 0, v[130:131]
	s_mov_b32 m0, s64
	ds_read_b128 v[194:197], v152 offset:16384
	ds_read_b128 v[198:201], v152 offset:17408
	ds_read_b128 v[202:205], v152 offset:18432
	ds_read_b128 v[206:209], v152 offset:19456
	ds_read_b128 v[210:213], v152 offset:20480
	ds_read_b128 v[214:217], v152 offset:21504
	ds_read_b128 v[218:221], v152 offset:22528
	ds_read_b128 v[222:225], v152 offset:23552
	global_load_lds_dwordx4 v[146:147], off
	s_add_i32 m0, s64, 0x2000
	s_add_u32 s64, s22, 0x40000
	v_lshl_add_u64 v[162:163], s[22:23], 0, v[134:135]
	s_addc_u32 s65, s23, 0
	s_add_i32 s66, s52, s31
	global_load_lds_dwordx4 v[162:163], off
	v_lshl_add_u64 v[178:179], s[64:65], 0, v[130:131]
	s_mov_b32 m0, s66
	v_lshl_add_u64 v[226:227], s[24:25], 0, v[132:133]
	global_load_lds_dwordx4 v[178:179], off
	v_lshl_add_u64 v[178:179], s[64:65], 0, v[134:135]
	s_add_i32 m0, s66, 0x2000
	s_nop 0
	global_load_lds_dwordx4 v[178:179], off
	v_lshl_add_u64 v[178:179], s[24:25], 0, v[128:129]
	s_mov_b32 m0, s19
	s_nop 0
	global_load_lds_dwordx4 v[178:179], off
	s_mov_b32 m0, s35
	s_nop 0
	global_load_lds_dwordx4 v[226:227], off
	s_waitcnt vmcnt(8)
	s_waitcnt lgkmcnt(0)
	s_setprio 1
	s_barrier
	v_mfma_f32_16x16x32_bf16 v[60:63], v[154:157], v[194:197], v[60:63]
	v_mfma_f32_16x16x32_bf16 v[56:59], v[166:169], v[194:197], v[56:59]
	v_mfma_f32_16x16x32_bf16 v[52:55], v[154:157], v[202:205], v[52:55]
	v_mfma_f32_16x16x32_bf16 v[44:47], v[166:169], v[202:205], v[44:47]
	v_mfma_f32_16x16x32_bf16 v[36:39], v[154:157], v[210:213], v[36:39]
	v_mfma_f32_16x16x32_bf16 v[28:31], v[166:169], v[210:213], v[28:31]
	v_mfma_f32_16x16x32_bf16 v[20:23], v[154:157], v[218:221], v[20:23]
	v_mfma_f32_16x16x32_bf16 v[12:15], v[166:169], v[218:221], v[12:15]
	v_mfma_f32_16x16x32_bf16 v[60:63], v[158:161], v[198:201], v[60:63]
	v_mfma_f32_16x16x32_bf16 v[56:59], v[170:173], v[198:201], v[56:59]
	v_mfma_f32_16x16x32_bf16 v[52:55], v[158:161], v[206:209], v[52:55]
	v_mfma_f32_16x16x32_bf16 v[44:47], v[170:173], v[206:209], v[44:47]
	v_mfma_f32_16x16x32_bf16 v[36:39], v[158:161], v[214:217], v[36:39]
	v_mfma_f32_16x16x32_bf16 v[28:31], v[170:173], v[214:217], v[28:31]
	v_mfma_f32_16x16x32_bf16 v[20:23], v[158:161], v[222:225], v[20:23]
	v_mfma_f32_16x16x32_bf16 v[12:15], v[170:173], v[222:225], v[12:15]
	v_mfma_f32_16x16x32_bf16 v[48:51], v[174:177], v[194:197], v[48:51]
	v_mfma_f32_16x16x32_bf16 v[40:43], v[186:189], v[194:197], v[40:43]
	v_mfma_f32_16x16x32_bf16 v[32:35], v[174:177], v[202:205], v[32:35]
	v_mfma_f32_16x16x32_bf16 v[24:27], v[186:189], v[202:205], v[24:27]
	v_mfma_f32_16x16x32_bf16 v[16:19], v[174:177], v[210:213], v[16:19]
	v_mfma_f32_16x16x32_bf16 v[8:11], v[186:189], v[210:213], v[8:11]
	v_mfma_f32_16x16x32_bf16 v[4:7], v[174:177], v[218:221], v[4:7]
	v_mfma_f32_16x16x32_bf16 v[0:3], v[186:189], v[218:221], v[0:3]
	v_mfma_f32_16x16x32_bf16 v[48:51], v[182:185], v[198:201], v[48:51]
	v_mfma_f32_16x16x32_bf16 v[40:43], v[190:193], v[198:201], v[40:43]
	v_mfma_f32_16x16x32_bf16 v[32:35], v[182:185], v[206:209], v[32:35]
	v_mfma_f32_16x16x32_bf16 v[24:27], v[190:193], v[206:209], v[24:27]
	v_mfma_f32_16x16x32_bf16 v[16:19], v[182:185], v[214:217], v[16:19]
	v_mfma_f32_16x16x32_bf16 v[8:11], v[190:193], v[214:217], v[8:11]
	v_mfma_f32_16x16x32_bf16 v[4:7], v[182:185], v[222:225], v[4:7]
	v_mfma_f32_16x16x32_bf16 v[0:3], v[190:193], v[222:225], v[0:3]
	s_barrier
	s_setprio 0
	s_add_i32 s64, 0, 0x18000
	v_add_u32_e32 v153, s64, v149
	s_add_i32 s65, 0, 0x1c000
	ds_read_b128 v[154:157], v153
	ds_read_b128 v[158:161], v153 offset:1024
	ds_read_b128 v[166:169], v153 offset:2048
	ds_read_b128 v[170:173], v153 offset:3072
	v_add_u32_e32 v153, s65, v149
	ds_read_b128 v[174:177], v153
	ds_read_b128 v[182:185], v153 offset:1024
	ds_read_b128 v[186:189], v153 offset:2048
	ds_read_b128 v[190:193], v153 offset:3072
	s_add_u32 s24, s24, 0x40000
	s_addc_u32 s25, s25, 0
	s_mov_b32 m0, s36
	v_lshl_add_u64 v[228:229], s[24:25], 0, v[128:129]
	ds_read_b128 v[194:197], v152 offset:32768
	ds_read_b128 v[198:201], v152 offset:33792
	ds_read_b128 v[202:205], v152 offset:34816
	ds_read_b128 v[206:209], v152 offset:35840
	ds_read_b128 v[210:213], v152 offset:36864
	ds_read_b128 v[214:217], v152 offset:37888
	ds_read_b128 v[218:221], v152 offset:38912
	ds_read_b128 v[222:225], v152 offset:39936
	global_load_lds_dwordx4 v[228:229], off
	v_lshl_add_u64 v[228:229], s[24:25], 0, v[132:133]
	s_mov_b32 m0, s37
	s_nop 0
	global_load_lds_dwordx4 v[228:229], off
	s_waitcnt vmcnt(8)
	s_waitcnt lgkmcnt(0)
	s_setprio 1
	s_barrier
	v_mfma_f32_16x16x32_bf16 v[124:127], v[154:157], v[194:197], v[124:127]
	v_mfma_f32_16x16x32_bf16 v[120:123], v[166:169], v[194:197], v[120:123]
	v_mfma_f32_16x16x32_bf16 v[116:119], v[154:157], v[202:205], v[116:119]
	v_mfma_f32_16x16x32_bf16 v[108:111], v[166:169], v[202:205], v[108:111]
	v_mfma_f32_16x16x32_bf16 v[100:103], v[154:157], v[210:213], v[100:103]
	v_mfma_f32_16x16x32_bf16 v[92:95], v[166:169], v[210:213], v[92:95]
	v_mfma_f32_16x16x32_bf16 v[84:87], v[154:157], v[218:221], v[84:87]
	v_mfma_f32_16x16x32_bf16 v[76:79], v[166:169], v[218:221], v[76:79]
	v_mfma_f32_16x16x32_bf16 v[124:127], v[158:161], v[198:201], v[124:127]
	v_mfma_f32_16x16x32_bf16 v[120:123], v[170:173], v[198:201], v[120:123]
	v_mfma_f32_16x16x32_bf16 v[116:119], v[158:161], v[206:209], v[116:119]
	v_mfma_f32_16x16x32_bf16 v[108:111], v[170:173], v[206:209], v[108:111]
	v_mfma_f32_16x16x32_bf16 v[100:103], v[158:161], v[214:217], v[100:103]
	v_mfma_f32_16x16x32_bf16 v[92:95], v[170:173], v[214:217], v[92:95]
	v_mfma_f32_16x16x32_bf16 v[84:87], v[158:161], v[222:225], v[84:87]
	v_mfma_f32_16x16x32_bf16 v[76:79], v[170:173], v[222:225], v[76:79]
	v_mfma_f32_16x16x32_bf16 v[112:115], v[174:177], v[194:197], v[112:115]
	v_mfma_f32_16x16x32_bf16 v[104:107], v[186:189], v[194:197], v[104:107]
	v_mfma_f32_16x16x32_bf16 v[96:99], v[174:177], v[202:205], v[96:99]
	v_mfma_f32_16x16x32_bf16 v[88:91], v[186:189], v[202:205], v[88:91]
	v_mfma_f32_16x16x32_bf16 v[80:83], v[174:177], v[210:213], v[80:83]
	v_mfma_f32_16x16x32_bf16 v[72:75], v[186:189], v[210:213], v[72:75]
	v_mfma_f32_16x16x32_bf16 v[68:71], v[174:177], v[218:221], v[68:71]
	v_mfma_f32_16x16x32_bf16 v[64:67], v[186:189], v[218:221], v[64:67]
	v_mfma_f32_16x16x32_bf16 v[112:115], v[182:185], v[198:201], v[112:115]
	v_mfma_f32_16x16x32_bf16 v[104:107], v[190:193], v[198:201], v[104:107]
	v_mfma_f32_16x16x32_bf16 v[96:99], v[182:185], v[206:209], v[96:99]
	v_mfma_f32_16x16x32_bf16 v[88:91], v[190:193], v[206:209], v[88:91]
	v_mfma_f32_16x16x32_bf16 v[80:83], v[182:185], v[214:217], v[80:83]
	v_mfma_f32_16x16x32_bf16 v[72:75], v[190:193], v[214:217], v[72:75]
	v_mfma_f32_16x16x32_bf16 v[68:71], v[182:185], v[222:225], v[68:71]
	v_mfma_f32_16x16x32_bf16 v[64:67], v[190:193], v[222:225], v[64:67]
	s_barrier
	s_setprio 0
	s_add_i32 s24, s64, s31
	v_lshl_add_u64 v[146:147], v[146:147], 0, s[6:7]
	s_mov_b32 m0, s24
	ds_read_b128 v[194:197], v152 offset:49152
	ds_read_b128 v[198:201], v152 offset:50176
	ds_read_b128 v[202:205], v152 offset:51200
	ds_read_b128 v[206:209], v152 offset:52224
	ds_read_b128 v[210:213], v152 offset:53248
	ds_read_b128 v[214:217], v152 offset:54272
	ds_read_b128 v[218:221], v152 offset:55296
	ds_read_b128 v[222:225], v152 offset:56320
	global_load_lds_dwordx4 v[146:147], off
	s_add_i32 m0, s24, 0x2000
	s_add_u32 s22, s22, 0x40080
	v_lshl_add_u64 v[146:147], v[162:163], 0, s[6:7]
	s_addc_u32 s23, s23, 0
	s_add_i32 s24, s65, s31
	global_load_lds_dwordx4 v[146:147], off
	v_lshl_add_u64 v[146:147], s[22:23], 0, v[130:131]
	s_mov_b32 m0, s24
	s_nop 0
	global_load_lds_dwordx4 v[146:147], off
	v_lshl_add_u64 v[146:147], s[22:23], 0, v[134:135]
	s_add_i32 m0, s24, 0x2000
	s_nop 0
	global_load_lds_dwordx4 v[146:147], off
	v_lshl_add_u64 v[146:147], v[178:179], 0, s[6:7]
	s_mov_b32 m0, s45
	s_nop 0
	global_load_lds_dwordx4 v[146:147], off
	v_lshl_add_u64 v[146:147], v[226:227], 0, s[6:7]
	s_mov_b32 m0, s48
	s_nop 0
	global_load_lds_dwordx4 v[146:147], off
	s_waitcnt vmcnt(8)
	s_waitcnt lgkmcnt(0)
	s_setprio 1
	s_barrier
	v_mfma_f32_16x16x32_bf16 v[60:63], v[154:157], v[194:197], v[60:63]
	v_mfma_f32_16x16x32_bf16 v[56:59], v[166:169], v[194:197], v[56:59]
	v_mfma_f32_16x16x32_bf16 v[52:55], v[154:157], v[202:205], v[52:55]
	v_mfma_f32_16x16x32_bf16 v[44:47], v[166:169], v[202:205], v[44:47]
	v_mfma_f32_16x16x32_bf16 v[36:39], v[154:157], v[210:213], v[36:39]
	v_mfma_f32_16x16x32_bf16 v[28:31], v[166:169], v[210:213], v[28:31]
	v_mfma_f32_16x16x32_bf16 v[20:23], v[154:157], v[218:221], v[20:23]
	v_mfma_f32_16x16x32_bf16 v[12:15], v[166:169], v[218:221], v[12:15]
	v_mfma_f32_16x16x32_bf16 v[60:63], v[158:161], v[198:201], v[60:63]
	v_mfma_f32_16x16x32_bf16 v[56:59], v[170:173], v[198:201], v[56:59]
	v_mfma_f32_16x16x32_bf16 v[52:55], v[158:161], v[206:209], v[52:55]
	v_mfma_f32_16x16x32_bf16 v[44:47], v[170:173], v[206:209], v[44:47]
	v_mfma_f32_16x16x32_bf16 v[36:39], v[158:161], v[214:217], v[36:39]
	v_mfma_f32_16x16x32_bf16 v[28:31], v[170:173], v[214:217], v[28:31]
	v_mfma_f32_16x16x32_bf16 v[20:23], v[158:161], v[222:225], v[20:23]
	v_mfma_f32_16x16x32_bf16 v[12:15], v[170:173], v[222:225], v[12:15]
	v_mfma_f32_16x16x32_bf16 v[48:51], v[174:177], v[194:197], v[48:51]
	v_mfma_f32_16x16x32_bf16 v[40:43], v[186:189], v[194:197], v[40:43]
	v_mfma_f32_16x16x32_bf16 v[32:35], v[174:177], v[202:205], v[32:35]
	v_mfma_f32_16x16x32_bf16 v[24:27], v[186:189], v[202:205], v[24:27]
	v_mfma_f32_16x16x32_bf16 v[16:19], v[174:177], v[210:213], v[16:19]
	v_mfma_f32_16x16x32_bf16 v[8:11], v[186:189], v[210:213], v[8:11]
	v_mfma_f32_16x16x32_bf16 v[4:7], v[174:177], v[218:221], v[4:7]
	v_mfma_f32_16x16x32_bf16 v[0:3], v[186:189], v[218:221], v[0:3]
	v_mfma_f32_16x16x32_bf16 v[48:51], v[182:185], v[198:201], v[48:51]
	v_mfma_f32_16x16x32_bf16 v[40:43], v[190:193], v[198:201], v[40:43]
	v_mfma_f32_16x16x32_bf16 v[32:35], v[182:185], v[206:209], v[32:35]
	v_mfma_f32_16x16x32_bf16 v[24:27], v[190:193], v[206:209], v[24:27]
	v_mfma_f32_16x16x32_bf16 v[16:19], v[182:185], v[214:217], v[16:19]
	v_mfma_f32_16x16x32_bf16 v[8:11], v[190:193], v[214:217], v[8:11]
	v_mfma_f32_16x16x32_bf16 v[4:7], v[182:185], v[222:225], v[4:7]
	v_mfma_f32_16x16x32_bf16 v[0:3], v[190:193], v[222:225], v[0:3]
	s_barrier
	s_setprio 0
	s_add_i32 s63, s63, 2
	s_add_u32 s20, s20, 0x100
	s_addc_u32 s21, s21, 0
	s_add_u32 s61, s61, 0x100
	s_addc_u32 s62, s62, 0
	s_cmp_gt_u32 s63, 13
	s_cbranch_scc0 .LBB0_312
.Lpeel_exit_v:
	s_and_b64 vcc, exec, s[8:9]
	s_cbranch_vccz .LBB0_315
	s_barrier
.LBB0_315:
	s_lshl_b32 s11, s38, 8
	s_cmp_gt_i32 s38, 63
	s_mov_b64 s[20:21], -1
	s_cbranch_scc0 .LBB0_318
	s_add_i32 s13, s11, 0xffffc000
	s_lshr_b32 s13, s13, 13
	s_cbranch_execz .LBB0_319

.LBB0_1028:
	s_ashr_i32 s13, s12, 31
	s_lshl_b64 s[16:17], s[12:13], 14
	s_add_u32 s16, s26, s16
	s_addc_u32 s17, s27, s17
	s_and_b64 s[2:3], s[2:3], exec
	s_cselect_b32 s13, s17, s23
	s_cselect_b32 s52, s16, s22
	s_add_u32 s53, s20, 0x100
	s_addc_u32 s54, s21, 0
	s_add_u32 s2, s22, 0xa02000
	s_addc_u32 s3, s23, 0
	s_mov_b32 s55, -2
	ds_read_b128 v[72:75], v173
	ds_read_b128 v[76:79], v173 offset:1024
	ds_read_b128 v[88:91], v173 offset:2048
	ds_read_b128 v[92:95], v173 offset:3072
	ds_read_b128 v[166:169], v174
	ds_read_b128 v[178:181], v174 offset:1024
	ds_read_b128 v[182:185], v174 offset:2048
	ds_read_b128 v[186:189], v174 offset:3072
	s_add_u32 s20, s2, 0x9fe000
	s_addc_u32 s21, s3, 0
	s_cmp_eq_u32 s55, 40
	s_cselect_b32 s24, s52, s20
	s_cselect_b32 s25, s13, s21
	s_cselect_b32 s22, s14, s53
	s_cselect_b32 s23, s15, s54
	s_add_u32 s20, s24, 0xa00000
	s_addc_u32 s21, s25, 0
	v_lshl_add_u64 v[222:223], s[2:3], 0, v[158:159]
	s_add_i32 m0, s19, 0xc000
	ds_read_b128 v[190:193], v175
	ds_read_b128 v[194:197], v175 offset:1024
	ds_read_b128 v[198:201], v175 offset:2048
	ds_read_b128 v[202:205], v175 offset:3072
	ds_read_b128 v[206:209], v175 offset:4096
	ds_read_b128 v[210:213], v175 offset:5120
	ds_read_b128 v[214:217], v175 offset:6144
	ds_read_b128 v[218:221], v175 offset:7168
	global_load_lds_dwordx4 v[222:223], off
	v_lshl_add_u64 v[222:223], s[2:3], 0, v[160:161]
	s_add_i32 m0, s19, 0xe000
	s_nop 0
	global_load_lds_dwordx4 v[222:223], off
	s_waitcnt vmcnt(8)
	s_waitcnt lgkmcnt(0)
	s_setprio 1
	s_barrier
	v_mfma_f32_16x16x32_bf16 v[140:143], v[72:75], v[190:193], 0
	v_mfma_f32_16x16x32_bf16 v[136:139], v[88:91], v[190:193], 0
	v_mfma_f32_16x16x32_bf16 v[124:127], v[72:75], v[198:201], 0
	v_mfma_f32_16x16x32_bf16 v[120:123], v[88:91], v[198:201], 0
	v_mfma_f32_16x16x32_bf16 v[108:111], v[72:75], v[206:209], 0
	v_mfma_f32_16x16x32_bf16 v[104:107], v[88:91], v[206:209], 0
	v_mfma_f32_16x16x32_bf16 v[84:87], v[72:75], v[214:217], 0
	v_mfma_f32_16x16x32_bf16 v[80:83], v[88:91], v[214:217], 0
	v_mfma_f32_16x16x32_bf16 v[140:143], v[76:79], v[194:197], v[140:143]
	v_mfma_f32_16x16x32_bf16 v[136:139], v[92:95], v[194:197], v[136:139]
	v_mfma_f32_16x16x32_bf16 v[124:127], v[76:79], v[202:205], v[124:127]
	v_mfma_f32_16x16x32_bf16 v[120:123], v[92:95], v[202:205], v[120:123]
	v_mfma_f32_16x16x32_bf16 v[108:111], v[76:79], v[210:213], v[108:111]
	v_mfma_f32_16x16x32_bf16 v[104:107], v[92:95], v[210:213], v[104:107]
	v_mfma_f32_16x16x32_bf16 v[84:87], v[76:79], v[218:221], v[84:87]
	v_mfma_f32_16x16x32_bf16 v[80:83], v[92:95], v[218:221], v[80:83]
	v_mfma_f32_16x16x32_bf16 v[132:135], v[166:169], v[190:193], 0
	v_mfma_f32_16x16x32_bf16 v[128:131], v[182:185], v[190:193], 0
	v_mfma_f32_16x16x32_bf16 v[116:119], v[166:169], v[198:201], 0
	v_mfma_f32_16x16x32_bf16 v[112:115], v[182:185], v[198:201], 0
	v_mfma_f32_16x16x32_bf16 v[100:103], v[166:169], v[206:209], 0
	v_mfma_f32_16x16x32_bf16 v[96:99], v[182:185], v[206:209], 0
	v_mfma_f32_16x16x32_bf16 v[68:71], v[166:169], v[214:217], 0
	v_mfma_f32_16x16x32_bf16 v[64:67], v[182:185], v[214:217], 0
	v_mfma_f32_16x16x32_bf16 v[132:135], v[178:181], v[194:197], v[132:135]
	v_mfma_f32_16x16x32_bf16 v[128:131], v[186:189], v[194:197], v[128:131]
	v_mfma_f32_16x16x32_bf16 v[116:119], v[178:181], v[202:205], v[116:119]
	v_mfma_f32_16x16x32_bf16 v[112:115], v[186:189], v[202:205], v[112:115]
	v_mfma_f32_16x16x32_bf16 v[100:103], v[178:181], v[210:213], v[100:103]
	v_mfma_f32_16x16x32_bf16 v[96:99], v[186:189], v[210:213], v[96:99]
	v_mfma_f32_16x16x32_bf16 v[68:71], v[178:181], v[218:221], v[68:71]
	v_mfma_f32_16x16x32_bf16 v[64:67], v[186:189], v[218:221], v[64:67]
	s_barrier
	s_setprio 0
	s_add_i32 s56, s47, s30
	v_lshl_add_u64 v[222:223], s[22:23], 0, v[148:149]
	s_mov_b32 m0, s56
	ds_read_b128 v[190:193], v175 offset:16384
	ds_read_b128 v[194:197], v175 offset:17408
	ds_read_b128 v[198:201], v175 offset:18432
	ds_read_b128 v[202:205], v175 offset:19456
	ds_read_b128 v[206:209], v175 offset:20480
	ds_read_b128 v[210:213], v175 offset:21504
	ds_read_b128 v[214:217], v175 offset:22528
	ds_read_b128 v[218:221], v175 offset:23552
	global_load_lds_dwordx4 v[222:223], off
	s_add_i32 m0, s56, 0x2000
	s_add_u32 s56, s22, 0xb0000
	v_lshl_add_u64 v[224:225], s[22:23], 0, v[144:145]
	s_addc_u32 s57, s23, 0
	s_add_i32 s58, s48, s30
	global_load_lds_dwordx4 v[224:225], off
	v_lshl_add_u64 v[226:227], s[56:57], 0, v[148:149]
	s_mov_b32 m0, s58
	s_nop 0
	global_load_lds_dwordx4 v[226:227], off
	v_lshl_add_u64 v[226:227], s[56:57], 0, v[144:145]
	s_add_i32 m0, s58, 0x2000
	s_nop 0
	global_load_lds_dwordx4 v[226:227], off
	v_lshl_add_u64 v[226:227], s[24:25], 0, v[150:151]
	s_mov_b32 m0, s19
	s_nop 0
	global_load_lds_dwordx4 v[226:227], off
	v_lshl_add_u64 v[226:227], s[24:25], 0, v[146:147]
	s_mov_b32 m0, s35
	s_nop 0
	global_load_lds_dwordx4 v[226:227], off
	s_waitcnt vmcnt(8)
	s_waitcnt lgkmcnt(0)
	s_setprio 1
	s_barrier
	v_mfma_f32_16x16x32_bf16 v[60:63], v[72:75], v[190:193], 0
	v_mfma_f32_16x16x32_bf16 v[56:59], v[88:91], v[190:193], 0
	v_mfma_f32_16x16x32_bf16 v[44:47], v[72:75], v[198:201], 0
	v_mfma_f32_16x16x32_bf16 v[40:43], v[88:91], v[198:201], 0
	v_mfma_f32_16x16x32_bf16 v[28:31], v[72:75], v[206:209], 0
	v_mfma_f32_16x16x32_bf16 v[24:27], v[88:91], v[206:209], 0
	v_mfma_f32_16x16x32_bf16 v[12:15], v[72:75], v[214:217], 0
	v_mfma_f32_16x16x32_bf16 v[8:11], v[88:91], v[214:217], 0
	v_mfma_f32_16x16x32_bf16 v[60:63], v[76:79], v[194:197], v[60:63]
	v_mfma_f32_16x16x32_bf16 v[56:59], v[92:95], v[194:197], v[56:59]
	v_mfma_f32_16x16x32_bf16 v[44:47], v[76:79], v[202:205], v[44:47]
	v_mfma_f32_16x16x32_bf16 v[40:43], v[92:95], v[202:205], v[40:43]
	v_mfma_f32_16x16x32_bf16 v[28:31], v[76:79], v[210:213], v[28:31]
	v_mfma_f32_16x16x32_bf16 v[24:27], v[92:95], v[210:213], v[24:27]
	v_mfma_f32_16x16x32_bf16 v[12:15], v[76:79], v[218:221], v[12:15]
	v_mfma_f32_16x16x32_bf16 v[8:11], v[92:95], v[218:221], v[8:11]
	v_mfma_f32_16x16x32_bf16 v[52:55], v[166:169], v[190:193], 0
	v_mfma_f32_16x16x32_bf16 v[48:51], v[182:185], v[190:193], 0
	v_mfma_f32_16x16x32_bf16 v[36:39], v[166:169], v[198:201], 0
	v_mfma_f32_16x16x32_bf16 v[32:35], v[182:185], v[198:201], 0
	v_mfma_f32_16x16x32_bf16 v[20:23], v[166:169], v[206:209], 0
	v_mfma_f32_16x16x32_bf16 v[16:19], v[182:185], v[206:209], 0
	v_mfma_f32_16x16x32_bf16 v[4:7], v[166:169], v[214:217], 0
	v_mfma_f32_16x16x32_bf16 v[0:3], v[182:185], v[214:217], 0
	v_mfma_f32_16x16x32_bf16 v[52:55], v[178:181], v[194:197], v[52:55]
	v_mfma_f32_16x16x32_bf16 v[48:51], v[186:189], v[194:197], v[48:51]
	v_mfma_f32_16x16x32_bf16 v[36:39], v[178:181], v[202:205], v[36:39]
	v_mfma_f32_16x16x32_bf16 v[32:35], v[186:189], v[202:205], v[32:35]
	v_mfma_f32_16x16x32_bf16 v[20:23], v[178:181], v[210:213], v[20:23]
	v_mfma_f32_16x16x32_bf16 v[16:19], v[186:189], v[210:213], v[16:19]
	v_mfma_f32_16x16x32_bf16 v[4:7], v[178:181], v[218:221], v[4:7]
	v_mfma_f32_16x16x32_bf16 v[0:3], v[186:189], v[218:221], v[0:3]
	s_barrier
	s_setprio 0
	s_add_i32 s56, 0, 0x18000
	s_add_i32 s57, 0, 0x1c000
	v_add_u32_e32 v92, s56, v155
	v_add_u32_e32 v152, s57, v155
	ds_read_b128 v[72:75], v92
	ds_read_b128 v[76:79], v92 offset:1024
	ds_read_b128 v[88:91], v92 offset:2048
	ds_read_b128 v[92:95], v92 offset:3072
	ds_read_b128 v[166:169], v152
	ds_read_b128 v[178:181], v152 offset:1024
	ds_read_b128 v[182:185], v152 offset:2048
	ds_read_b128 v[186:189], v152 offset:3072
	s_add_u32 s24, s24, 0x2000
	s_addc_u32 s25, s25, 0
	s_mov_b32 m0, s36
	v_lshl_add_u64 v[226:227], s[24:25], 0, v[150:151]
	ds_read_b128 v[190:193], v175 offset:32768
	ds_read_b128 v[194:197], v175 offset:33792
	ds_read_b128 v[198:201], v175 offset:34816
	ds_read_b128 v[202:205], v175 offset:35840
	ds_read_b128 v[206:209], v175 offset:36864
	ds_read_b128 v[210:213], v175 offset:37888
	ds_read_b128 v[214:217], v175 offset:38912
	ds_read_b128 v[218:221], v175 offset:39936
	global_load_lds_dwordx4 v[226:227], off
	v_lshl_add_u64 v[226:227], s[24:25], 0, v[146:147]
	s_mov_b32 m0, s37
	s_nop 0
	global_load_lds_dwordx4 v[226:227], off
	s_waitcnt vmcnt(8)
	s_waitcnt lgkmcnt(0)
	s_setprio 1
	s_barrier
	v_mfma_f32_16x16x32_bf16 v[140:143], v[72:75], v[190:193], v[140:143]
	v_mfma_f32_16x16x32_bf16 v[136:139], v[88:91], v[190:193], v[136:139]
	v_mfma_f32_16x16x32_bf16 v[124:127], v[72:75], v[198:201], v[124:127]
	v_mfma_f32_16x16x32_bf16 v[120:123], v[88:91], v[198:201], v[120:123]
	v_mfma_f32_16x16x32_bf16 v[108:111], v[72:75], v[206:209], v[108:111]
	v_mfma_f32_16x16x32_bf16 v[104:107], v[88:91], v[206:209], v[104:107]
	v_mfma_f32_16x16x32_bf16 v[84:87], v[72:75], v[214:217], v[84:87]
	v_mfma_f32_16x16x32_bf16 v[80:83], v[88:91], v[214:217], v[80:83]
	v_mfma_f32_16x16x32_bf16 v[140:143], v[76:79], v[194:197], v[140:143]
	v_mfma_f32_16x16x32_bf16 v[136:139], v[92:95], v[194:197], v[136:139]
	v_mfma_f32_16x16x32_bf16 v[124:127], v[76:79], v[202:205], v[124:127]
	v_mfma_f32_16x16x32_bf16 v[120:123], v[92:95], v[202:205], v[120:123]
	v_mfma_f32_16x16x32_bf16 v[108:111], v[76:79], v[210:213], v[108:111]
	v_mfma_f32_16x16x32_bf16 v[104:107], v[92:95], v[210:213], v[104:107]
	v_mfma_f32_16x16x32_bf16 v[84:87], v[76:79], v[218:221], v[84:87]
	v_mfma_f32_16x16x32_bf16 v[80:83], v[92:95], v[218:221], v[80:83]
	v_mfma_f32_16x16x32_bf16 v[132:135], v[166:169], v[190:193], v[132:135]
	v_mfma_f32_16x16x32_bf16 v[128:131], v[182:185], v[190:193], v[128:131]
	v_mfma_f32_16x16x32_bf16 v[116:119], v[166:169], v[198:201], v[116:119]
	v_mfma_f32_16x16x32_bf16 v[112:115], v[182:185], v[198:201], v[112:115]
	v_mfma_f32_16x16x32_bf16 v[100:103], v[166:169], v[206:209], v[100:103]
	v_mfma_f32_16x16x32_bf16 v[96:99], v[182:185], v[206:209], v[96:99]
	v_mfma_f32_16x16x32_bf16 v[68:71], v[166:169], v[214:217], v[68:71]
	v_mfma_f32_16x16x32_bf16 v[64:67], v[182:185], v[214:217], v[64:67]
	v_mfma_f32_16x16x32_bf16 v[132:135], v[178:181], v[194:197], v[132:135]
	v_mfma_f32_16x16x32_bf16 v[128:131], v[186:189], v[194:197], v[128:131]
	v_mfma_f32_16x16x32_bf16 v[116:119], v[178:181], v[202:205], v[116:119]
	v_mfma_f32_16x16x32_bf16 v[112:115], v[186:189], v[202:205], v[112:115]
	v_mfma_f32_16x16x32_bf16 v[100:103], v[178:181], v[210:213], v[100:103]
	v_mfma_f32_16x16x32_bf16 v[96:99], v[186:189], v[210:213], v[96:99]
	v_mfma_f32_16x16x32_bf16 v[68:71], v[178:181], v[218:221], v[68:71]
	v_mfma_f32_16x16x32_bf16 v[64:67], v[186:189], v[218:221], v[64:67]
	s_barrier
	s_setprio 0
	s_add_i32 s24, s56, s30
	v_lshl_add_u64 v[222:223], v[222:223], 0, s[6:7]
	s_mov_b32 m0, s24
	ds_read_b128 v[190:193], v175 offset:49152
	ds_read_b128 v[194:197], v175 offset:50176
	ds_read_b128 v[198:201], v175 offset:51200
	ds_read_b128 v[202:205], v175 offset:52224
	ds_read_b128 v[206:209], v175 offset:53248
	ds_read_b128 v[210:213], v175 offset:54272
	ds_read_b128 v[214:217], v175 offset:55296
	ds_read_b128 v[218:221], v175 offset:56320
	global_load_lds_dwordx4 v[222:223], off
	s_add_i32 m0, s24, 0x2000
	s_add_u32 s22, s22, 0xb0080
	v_lshl_add_u64 v[222:223], v[224:225], 0, s[6:7]
	s_addc_u32 s23, s23, 0
	s_add_i32 s24, s57, s30
	global_load_lds_dwordx4 v[222:223], off
	v_lshl_add_u64 v[222:223], s[22:23], 0, v[148:149]
	s_mov_b32 m0, s24
	s_nop 0
	global_load_lds_dwordx4 v[222:223], off
	v_lshl_add_u64 v[222:223], s[22:23], 0, v[144:145]
	s_add_i32 m0, s24, 0x2000
	s_nop 0
	global_load_lds_dwordx4 v[222:223], off
	v_lshl_add_u64 v[222:223], s[20:21], 0, v[150:151]
	s_mov_b32 m0, s43
	s_nop 0
	global_load_lds_dwordx4 v[222:223], off
	v_lshl_add_u64 v[222:223], s[20:21], 0, v[146:147]
	s_mov_b32 m0, s44
	s_nop 0
	global_load_lds_dwordx4 v[222:223], off
	s_waitcnt vmcnt(8)
	s_waitcnt lgkmcnt(0)
	s_setprio 1
	s_barrier
	v_mfma_f32_16x16x32_bf16 v[60:63], v[72:75], v[190:193], v[60:63]
	v_mfma_f32_16x16x32_bf16 v[56:59], v[88:91], v[190:193], v[56:59]
	v_mfma_f32_16x16x32_bf16 v[44:47], v[72:75], v[198:201], v[44:47]
	v_mfma_f32_16x16x32_bf16 v[40:43], v[88:91], v[198:201], v[40:43]
	v_mfma_f32_16x16x32_bf16 v[28:31], v[72:75], v[206:209], v[28:31]
	v_mfma_f32_16x16x32_bf16 v[24:27], v[88:91], v[206:209], v[24:27]
	v_mfma_f32_16x16x32_bf16 v[12:15], v[72:75], v[214:217], v[12:15]
	v_mfma_f32_16x16x32_bf16 v[8:11], v[88:91], v[214:217], v[8:11]
	v_mfma_f32_16x16x32_bf16 v[60:63], v[76:79], v[194:197], v[60:63]
	v_mfma_f32_16x16x32_bf16 v[56:59], v[92:95], v[194:197], v[56:59]
	v_mfma_f32_16x16x32_bf16 v[44:47], v[76:79], v[202:205], v[44:47]
	v_mfma_f32_16x16x32_bf16 v[40:43], v[92:95], v[202:205], v[40:43]
	v_mfma_f32_16x16x32_bf16 v[28:31], v[76:79], v[210:213], v[28:31]
	v_mfma_f32_16x16x32_bf16 v[24:27], v[92:95], v[210:213], v[24:27]
	v_mfma_f32_16x16x32_bf16 v[12:15], v[76:79], v[218:221], v[12:15]
	v_mfma_f32_16x16x32_bf16 v[8:11], v[92:95], v[218:221], v[8:11]
	v_mfma_f32_16x16x32_bf16 v[52:55], v[166:169], v[190:193], v[52:55]
	v_mfma_f32_16x16x32_bf16 v[48:51], v[182:185], v[190:193], v[48:51]
	v_mfma_f32_16x16x32_bf16 v[36:39], v[166:169], v[198:201], v[36:39]
	v_mfma_f32_16x16x32_bf16 v[32:35], v[182:185], v[198:201], v[32:35]
	v_mfma_f32_16x16x32_bf16 v[20:23], v[166:169], v[206:209], v[20:23]
	v_mfma_f32_16x16x32_bf16 v[16:19], v[182:185], v[206:209], v[16:19]
	v_mfma_f32_16x16x32_bf16 v[4:7], v[166:169], v[214:217], v[4:7]
	v_mfma_f32_16x16x32_bf16 v[0:3], v[182:185], v[214:217], v[0:3]
	v_mfma_f32_16x16x32_bf16 v[52:55], v[178:181], v[194:197], v[52:55]
	v_mfma_f32_16x16x32_bf16 v[48:51], v[186:189], v[194:197], v[48:51]
	v_mfma_f32_16x16x32_bf16 v[36:39], v[178:181], v[202:205], v[36:39]
	v_mfma_f32_16x16x32_bf16 v[32:35], v[186:189], v[202:205], v[32:35]
	v_mfma_f32_16x16x32_bf16 v[20:23], v[178:181], v[210:213], v[20:23]
	v_mfma_f32_16x16x32_bf16 v[16:19], v[186:189], v[210:213], v[16:19]
	v_mfma_f32_16x16x32_bf16 v[4:7], v[178:181], v[218:221], v[4:7]
	v_mfma_f32_16x16x32_bf16 v[0:3], v[186:189], v[218:221], v[0:3]
	s_barrier
	s_setprio 0
	s_add_i32 s55, s55, 2
	s_add_u32 s53, s53, 0x100
	s_addc_u32 s54, s54, 0
	s_add_u32 s2, s2, 0x1400000
	s_addc_u32 s3, s3, 0
	s_cmp_gt_u32 s55, 41
	s_cbranch_scc0 .LBB0_1029
	s_branch .Lpeel_exit_p8
.LBB0_1029:
	ds_read_b128 v[72:75], v173
	ds_read_b128 v[76:79], v173 offset:1024
	ds_read_b128 v[88:91], v173 offset:2048
	ds_read_b128 v[92:95], v173 offset:3072
	ds_read_b128 v[166:169], v174
	ds_read_b128 v[178:181], v174 offset:1024
	ds_read_b128 v[182:185], v174 offset:2048
	ds_read_b128 v[186:189], v174 offset:3072
	s_add_u32 s20, s2, 0x9fe000
	s_addc_u32 s21, s3, 0
	s_cmp_eq_u32 s55, 40
	s_cselect_b32 s24, s52, s20
	s_cselect_b32 s25, s13, s21
	s_cselect_b32 s22, s14, s53
	s_cselect_b32 s23, s15, s54
	s_add_u32 s20, s24, 0xa00000
	s_addc_u32 s21, s25, 0
	v_lshl_add_u64 v[222:223], s[2:3], 0, v[158:159]
	s_add_i32 m0, s19, 0xc000
	ds_read_b128 v[190:193], v175
	ds_read_b128 v[194:197], v175 offset:1024
	ds_read_b128 v[198:201], v175 offset:2048
	ds_read_b128 v[202:205], v175 offset:3072
	ds_read_b128 v[206:209], v175 offset:4096
	ds_read_b128 v[210:213], v175 offset:5120
	ds_read_b128 v[214:217], v175 offset:6144
	ds_read_b128 v[218:221], v175 offset:7168
	global_load_lds_dwordx4 v[222:223], off
	v_lshl_add_u64 v[222:223], s[2:3], 0, v[160:161]
	s_add_i32 m0, s19, 0xe000
	s_nop 0
	global_load_lds_dwordx4 v[222:223], off
	s_waitcnt vmcnt(8)
	s_waitcnt lgkmcnt(0)
	s_setprio 1
	s_barrier
	v_mfma_f32_16x16x32_bf16 v[140:143], v[72:75], v[190:193], v[140:143]
	v_mfma_f32_16x16x32_bf16 v[136:139], v[88:91], v[190:193], v[136:139]
	v_mfma_f32_16x16x32_bf16 v[124:127], v[72:75], v[198:201], v[124:127]
	v_mfma_f32_16x16x32_bf16 v[120:123], v[88:91], v[198:201], v[120:123]
	v_mfma_f32_16x16x32_bf16 v[108:111], v[72:75], v[206:209], v[108:111]
	v_mfma_f32_16x16x32_bf16 v[104:107], v[88:91], v[206:209], v[104:107]
	v_mfma_f32_16x16x32_bf16 v[84:87], v[72:75], v[214:217], v[84:87]
	v_mfma_f32_16x16x32_bf16 v[80:83], v[88:91], v[214:217], v[80:83]
	v_mfma_f32_16x16x32_bf16 v[140:143], v[76:79], v[194:197], v[140:143]
	v_mfma_f32_16x16x32_bf16 v[136:139], v[92:95], v[194:197], v[136:139]
	v_mfma_f32_16x16x32_bf16 v[124:127], v[76:79], v[202:205], v[124:127]
	v_mfma_f32_16x16x32_bf16 v[120:123], v[92:95], v[202:205], v[120:123]
	v_mfma_f32_16x16x32_bf16 v[108:111], v[76:79], v[210:213], v[108:111]
	v_mfma_f32_16x16x32_bf16 v[104:107], v[92:95], v[210:213], v[104:107]
	v_mfma_f32_16x16x32_bf16 v[84:87], v[76:79], v[218:221], v[84:87]
	v_mfma_f32_16x16x32_bf16 v[80:83], v[92:95], v[218:221], v[80:83]
	v_mfma_f32_16x16x32_bf16 v[132:135], v[166:169], v[190:193], v[132:135]
	v_mfma_f32_16x16x32_bf16 v[128:131], v[182:185], v[190:193], v[128:131]
	v_mfma_f32_16x16x32_bf16 v[116:119], v[166:169], v[198:201], v[116:119]
	v_mfma_f32_16x16x32_bf16 v[112:115], v[182:185], v[198:201], v[112:115]
	v_mfma_f32_16x16x32_bf16 v[100:103], v[166:169], v[206:209], v[100:103]
	v_mfma_f32_16x16x32_bf16 v[96:99], v[182:185], v[206:209], v[96:99]
	v_mfma_f32_16x16x32_bf16 v[68:71], v[166:169], v[214:217], v[68:71]
	v_mfma_f32_16x16x32_bf16 v[64:67], v[182:185], v[214:217], v[64:67]
	v_mfma_f32_16x16x32_bf16 v[132:135], v[178:181], v[194:197], v[132:135]
	v_mfma_f32_16x16x32_bf16 v[128:131], v[186:189], v[194:197], v[128:131]
	v_mfma_f32_16x16x32_bf16 v[116:119], v[178:181], v[202:205], v[116:119]
	v_mfma_f32_16x16x32_bf16 v[112:115], v[186:189], v[202:205], v[112:115]
	v_mfma_f32_16x16x32_bf16 v[100:103], v[178:181], v[210:213], v[100:103]
	v_mfma_f32_16x16x32_bf16 v[96:99], v[186:189], v[210:213], v[96:99]
	v_mfma_f32_16x16x32_bf16 v[68:71], v[178:181], v[218:221], v[68:71]
	v_mfma_f32_16x16x32_bf16 v[64:67], v[186:189], v[218:221], v[64:67]
	s_barrier
	s_setprio 0
	s_add_i32 s56, s47, s30
	v_lshl_add_u64 v[222:223], s[22:23], 0, v[148:149]
	s_mov_b32 m0, s56
	ds_read_b128 v[190:193], v175 offset:16384
	ds_read_b128 v[194:197], v175 offset:17408
	ds_read_b128 v[198:201], v175 offset:18432
	ds_read_b128 v[202:205], v175 offset:19456
	ds_read_b128 v[206:209], v175 offset:20480
	ds_read_b128 v[210:213], v175 offset:21504
	ds_read_b128 v[214:217], v175 offset:22528
	ds_read_b128 v[218:221], v175 offset:23552
	global_load_lds_dwordx4 v[222:223], off
	s_add_i32 m0, s56, 0x2000
	s_add_u32 s56, s22, 0xb0000
	v_lshl_add_u64 v[224:225], s[22:23], 0, v[144:145]
	s_addc_u32 s57, s23, 0
	s_add_i32 s58, s48, s30
	global_load_lds_dwordx4 v[224:225], off
	v_lshl_add_u64 v[226:227], s[56:57], 0, v[148:149]
	s_mov_b32 m0, s58
	s_nop 0
	global_load_lds_dwordx4 v[226:227], off
	v_lshl_add_u64 v[226:227], s[56:57], 0, v[144:145]
	s_add_i32 m0, s58, 0x2000
	s_nop 0
	global_load_lds_dwordx4 v[226:227], off
	v_lshl_add_u64 v[226:227], s[24:25], 0, v[150:151]
	s_mov_b32 m0, s19
	s_nop 0
	global_load_lds_dwordx4 v[226:227], off
	v_lshl_add_u64 v[226:227], s[24:25], 0, v[146:147]
	s_mov_b32 m0, s35
	s_nop 0
	global_load_lds_dwordx4 v[226:227], off
	s_waitcnt vmcnt(8)
	s_waitcnt lgkmcnt(0)
	s_setprio 1
	s_barrier
	v_mfma_f32_16x16x32_bf16 v[60:63], v[72:75], v[190:193], v[60:63]
	v_mfma_f32_16x16x32_bf16 v[56:59], v[88:91], v[190:193], v[56:59]
	v_mfma_f32_16x16x32_bf16 v[44:47], v[72:75], v[198:201], v[44:47]
	v_mfma_f32_16x16x32_bf16 v[40:43], v[88:91], v[198:201], v[40:43]
	v_mfma_f32_16x16x32_bf16 v[28:31], v[72:75], v[206:209], v[28:31]
	v_mfma_f32_16x16x32_bf16 v[24:27], v[88:91], v[206:209], v[24:27]
	v_mfma_f32_16x16x32_bf16 v[12:15], v[72:75], v[214:217], v[12:15]
	v_mfma_f32_16x16x32_bf16 v[8:11], v[88:91], v[214:217], v[8:11]
	v_mfma_f32_16x16x32_bf16 v[60:63], v[76:79], v[194:197], v[60:63]
	v_mfma_f32_16x16x32_bf16 v[56:59], v[92:95], v[194:197], v[56:59]
	v_mfma_f32_16x16x32_bf16 v[44:47], v[76:79], v[202:205], v[44:47]
	v_mfma_f32_16x16x32_bf16 v[40:43], v[92:95], v[202:205], v[40:43]
	v_mfma_f32_16x16x32_bf16 v[28:31], v[76:79], v[210:213], v[28:31]
	v_mfma_f32_16x16x32_bf16 v[24:27], v[92:95], v[210:213], v[24:27]
	v_mfma_f32_16x16x32_bf16 v[12:15], v[76:79], v[218:221], v[12:15]
	v_mfma_f32_16x16x32_bf16 v[8:11], v[92:95], v[218:221], v[8:11]
	v_mfma_f32_16x16x32_bf16 v[52:55], v[166:169], v[190:193], v[52:55]
	v_mfma_f32_16x16x32_bf16 v[48:51], v[182:185], v[190:193], v[48:51]
	v_mfma_f32_16x16x32_bf16 v[36:39], v[166:169], v[198:201], v[36:39]
	v_mfma_f32_16x16x32_bf16 v[32:35], v[182:185], v[198:201], v[32:35]
	v_mfma_f32_16x16x32_bf16 v[20:23], v[166:169], v[206:209], v[20:23]
	v_mfma_f32_16x16x32_bf16 v[16:19], v[182:185], v[206:209], v[16:19]
	v_mfma_f32_16x16x32_bf16 v[4:7], v[166:169], v[214:217], v[4:7]
	v_mfma_f32_16x16x32_bf16 v[0:3], v[182:185], v[214:217], v[0:3]
	v_mfma_f32_16x16x32_bf16 v[52:55], v[178:181], v[194:197], v[52:55]
	v_mfma_f32_16x16x32_bf16 v[48:51], v[186:189], v[194:197], v[48:51]
	v_mfma_f32_16x16x32_bf16 v[36:39], v[178:181], v[202:205], v[36:39]
	v_mfma_f32_16x16x32_bf16 v[32:35], v[186:189], v[202:205], v[32:35]
	v_mfma_f32_16x16x32_bf16 v[20:23], v[178:181], v[210:213], v[20:23]
	v_mfma_f32_16x16x32_bf16 v[16:19], v[186:189], v[210:213], v[16:19]
	v_mfma_f32_16x16x32_bf16 v[4:7], v[178:181], v[218:221], v[4:7]
	v_mfma_f32_16x16x32_bf16 v[0:3], v[186:189], v[218:221], v[0:3]
	s_barrier
	s_setprio 0
	s_add_i32 s56, 0, 0x18000
	s_add_i32 s57, 0, 0x1c000
	v_add_u32_e32 v92, s56, v155
	v_add_u32_e32 v152, s57, v155
	ds_read_b128 v[72:75], v92
	ds_read_b128 v[76:79], v92 offset:1024
	ds_read_b128 v[88:91], v92 offset:2048
	ds_read_b128 v[92:95], v92 offset:3072
	ds_read_b128 v[166:169], v152
	ds_read_b128 v[178:181], v152 offset:1024
	ds_read_b128 v[182:185], v152 offset:2048
	ds_read_b128 v[186:189], v152 offset:3072
	s_add_u32 s24, s24, 0x2000
	s_addc_u32 s25, s25, 0
	s_mov_b32 m0, s36
	v_lshl_add_u64 v[226:227], s[24:25], 0, v[150:151]
	ds_read_b128 v[190:193], v175 offset:32768
	ds_read_b128 v[194:197], v175 offset:33792
	ds_read_b128 v[198:201], v175 offset:34816
	ds_read_b128 v[202:205], v175 offset:35840
	ds_read_b128 v[206:209], v175 offset:36864
	ds_read_b128 v[210:213], v175 offset:37888
	ds_read_b128 v[214:217], v175 offset:38912
	ds_read_b128 v[218:221], v175 offset:39936
	global_load_lds_dwordx4 v[226:227], off
	v_lshl_add_u64 v[226:227], s[24:25], 0, v[146:147]
	s_mov_b32 m0, s37
	s_nop 0
	global_load_lds_dwordx4 v[226:227], off
	s_waitcnt vmcnt(8)
	s_waitcnt lgkmcnt(0)
	s_setprio 1
	s_barrier
	v_mfma_f32_16x16x32_bf16 v[140:143], v[72:75], v[190:193], v[140:143]
	v_mfma_f32_16x16x32_bf16 v[136:139], v[88:91], v[190:193], v[136:139]
	v_mfma_f32_16x16x32_bf16 v[124:127], v[72:75], v[198:201], v[124:127]
	v_mfma_f32_16x16x32_bf16 v[120:123], v[88:91], v[198:201], v[120:123]
	v_mfma_f32_16x16x32_bf16 v[108:111], v[72:75], v[206:209], v[108:111]
	v_mfma_f32_16x16x32_bf16 v[104:107], v[88:91], v[206:209], v[104:107]
	v_mfma_f32_16x16x32_bf16 v[84:87], v[72:75], v[214:217], v[84:87]
	v_mfma_f32_16x16x32_bf16 v[80:83], v[88:91], v[214:217], v[80:83]
	v_mfma_f32_16x16x32_bf16 v[140:143], v[76:79], v[194:197], v[140:143]
	v_mfma_f32_16x16x32_bf16 v[136:139], v[92:95], v[194:197], v[136:139]
	v_mfma_f32_16x16x32_bf16 v[124:127], v[76:79], v[202:205], v[124:127]
	v_mfma_f32_16x16x32_bf16 v[120:123], v[92:95], v[202:205], v[120:123]
	v_mfma_f32_16x16x32_bf16 v[108:111], v[76:79], v[210:213], v[108:111]
	v_mfma_f32_16x16x32_bf16 v[104:107], v[92:95], v[210:213], v[104:107]
	v_mfma_f32_16x16x32_bf16 v[84:87], v[76:79], v[218:221], v[84:87]
	v_mfma_f32_16x16x32_bf16 v[80:83], v[92:95], v[218:221], v[80:83]
	v_mfma_f32_16x16x32_bf16 v[132:135], v[166:169], v[190:193], v[132:135]
	v_mfma_f32_16x16x32_bf16 v[128:131], v[182:185], v[190:193], v[128:131]
	v_mfma_f32_16x16x32_bf16 v[116:119], v[166:169], v[198:201], v[116:119]
	v_mfma_f32_16x16x32_bf16 v[112:115], v[182:185], v[198:201], v[112:115]
	v_mfma_f32_16x16x32_bf16 v[100:103], v[166:169], v[206:209], v[100:103]
	v_mfma_f32_16x16x32_bf16 v[96:99], v[182:185], v[206:209], v[96:99]
	v_mfma_f32_16x16x32_bf16 v[68:71], v[166:169], v[214:217], v[68:71]
	v_mfma_f32_16x16x32_bf16 v[64:67], v[182:185], v[214:217], v[64:67]
	v_mfma_f32_16x16x32_bf16 v[132:135], v[178:181], v[194:197], v[132:135]
	v_mfma_f32_16x16x32_bf16 v[128:131], v[186:189], v[194:197], v[128:131]
	v_mfma_f32_16x16x32_bf16 v[116:119], v[178:181], v[202:205], v[116:119]
	v_mfma_f32_16x16x32_bf16 v[112:115], v[186:189], v[202:205], v[112:115]
	v_mfma_f32_16x16x32_bf16 v[100:103], v[178:181], v[210:213], v[100:103]
	v_mfma_f32_16x16x32_bf16 v[96:99], v[186:189], v[210:213], v[96:99]
	v_mfma_f32_16x16x32_bf16 v[68:71], v[178:181], v[218:221], v[68:71]
	v_mfma_f32_16x16x32_bf16 v[64:67], v[186:189], v[218:221], v[64:67]
	s_barrier
	s_setprio 0
	s_add_i32 s24, s56, s30
	v_lshl_add_u64 v[222:223], v[222:223], 0, s[6:7]
	s_mov_b32 m0, s24
	ds_read_b128 v[190:193], v175 offset:49152
	ds_read_b128 v[194:197], v175 offset:50176
	ds_read_b128 v[198:201], v175 offset:51200
	ds_read_b128 v[202:205], v175 offset:52224
	ds_read_b128 v[206:209], v175 offset:53248
	ds_read_b128 v[210:213], v175 offset:54272
	ds_read_b128 v[214:217], v175 offset:55296
	ds_read_b128 v[218:221], v175 offset:56320
	global_load_lds_dwordx4 v[222:223], off
	s_add_i32 m0, s24, 0x2000
	s_add_u32 s22, s22, 0xb0080
	v_lshl_add_u64 v[222:223], v[224:225], 0, s[6:7]
	s_addc_u32 s23, s23, 0
	s_add_i32 s24, s57, s30
	global_load_lds_dwordx4 v[222:223], off
	v_lshl_add_u64 v[222:223], s[22:23], 0, v[148:149]
	s_mov_b32 m0, s24
	s_nop 0
	global_load_lds_dwordx4 v[222:223], off
	v_lshl_add_u64 v[222:223], s[22:23], 0, v[144:145]
	s_add_i32 m0, s24, 0x2000
	s_nop 0
	global_load_lds_dwordx4 v[222:223], off
	v_lshl_add_u64 v[222:223], s[20:21], 0, v[150:151]
	s_mov_b32 m0, s43
	s_nop 0
	global_load_lds_dwordx4 v[222:223], off
	v_lshl_add_u64 v[222:223], s[20:21], 0, v[146:147]
	s_mov_b32 m0, s44
	s_nop 0
	global_load_lds_dwordx4 v[222:223], off
	s_waitcnt vmcnt(8)
	s_waitcnt lgkmcnt(0)
	s_setprio 1
	s_barrier
	v_mfma_f32_16x16x32_bf16 v[60:63], v[72:75], v[190:193], v[60:63]
	v_mfma_f32_16x16x32_bf16 v[56:59], v[88:91], v[190:193], v[56:59]
	v_mfma_f32_16x16x32_bf16 v[44:47], v[72:75], v[198:201], v[44:47]
	v_mfma_f32_16x16x32_bf16 v[40:43], v[88:91], v[198:201], v[40:43]
	v_mfma_f32_16x16x32_bf16 v[28:31], v[72:75], v[206:209], v[28:31]
	v_mfma_f32_16x16x32_bf16 v[24:27], v[88:91], v[206:209], v[24:27]
	v_mfma_f32_16x16x32_bf16 v[12:15], v[72:75], v[214:217], v[12:15]
	v_mfma_f32_16x16x32_bf16 v[8:11], v[88:91], v[214:217], v[8:11]
	v_mfma_f32_16x16x32_bf16 v[60:63], v[76:79], v[194:197], v[60:63]
	v_mfma_f32_16x16x32_bf16 v[56:59], v[92:95], v[194:197], v[56:59]
	v_mfma_f32_16x16x32_bf16 v[44:47], v[76:79], v[202:205], v[44:47]
	v_mfma_f32_16x16x32_bf16 v[40:43], v[92:95], v[202:205], v[40:43]
	v_mfma_f32_16x16x32_bf16 v[28:31], v[76:79], v[210:213], v[28:31]
	v_mfma_f32_16x16x32_bf16 v[24:27], v[92:95], v[210:213], v[24:27]
	v_mfma_f32_16x16x32_bf16 v[12:15], v[76:79], v[218:221], v[12:15]
	v_mfma_f32_16x16x32_bf16 v[8:11], v[92:95], v[218:221], v[8:11]
	v_mfma_f32_16x16x32_bf16 v[52:55], v[166:169], v[190:193], v[52:55]
	v_mfma_f32_16x16x32_bf16 v[48:51], v[182:185], v[190:193], v[48:51]
	v_mfma_f32_16x16x32_bf16 v[36:39], v[166:169], v[198:201], v[36:39]
	v_mfma_f32_16x16x32_bf16 v[32:35], v[182:185], v[198:201], v[32:35]
	v_mfma_f32_16x16x32_bf16 v[20:23], v[166:169], v[206:209], v[20:23]
	v_mfma_f32_16x16x32_bf16 v[16:19], v[182:185], v[206:209], v[16:19]
	v_mfma_f32_16x16x32_bf16 v[4:7], v[166:169], v[214:217], v[4:7]
	v_mfma_f32_16x16x32_bf16 v[0:3], v[182:185], v[214:217], v[0:3]
	v_mfma_f32_16x16x32_bf16 v[52:55], v[178:181], v[194:197], v[52:55]
	v_mfma_f32_16x16x32_bf16 v[48:51], v[186:189], v[194:197], v[48:51]
	v_mfma_f32_16x16x32_bf16 v[36:39], v[178:181], v[202:205], v[36:39]
	v_mfma_f32_16x16x32_bf16 v[32:35], v[186:189], v[202:205], v[32:35]
	v_mfma_f32_16x16x32_bf16 v[20:23], v[178:181], v[210:213], v[20:23]
	v_mfma_f32_16x16x32_bf16 v[16:19], v[186:189], v[210:213], v[16:19]
	v_mfma_f32_16x16x32_bf16 v[4:7], v[178:181], v[218:221], v[4:7]
	v_mfma_f32_16x16x32_bf16 v[0:3], v[186:189], v[218:221], v[0:3]
	s_barrier
	s_setprio 0
	s_add_i32 s55, s55, 2
	s_add_u32 s53, s53, 0x100
	s_addc_u32 s54, s54, 0
	s_add_u32 s2, s2, 0x1400000
	s_addc_u32 s3, s3, 0
	s_cmp_gt_u32 s55, 41
	s_cbranch_scc0 .LBB0_1029
.Lpeel_exit_p8:
	s_and_b64 vcc, exec, s[8:9]
	s_cbranch_vccz .LBB0_1032
	s_barrier
.LBB0_1032:
	s_lshl_b32 s2, s18, 8
	s_add_i32 s13, s2, 0xffffc000
	s_lshr_b32 s13, s13, 13
	s_lshr_b32 s3, s18, 4
	s_add_i32 s13, s13, 4
	s_cmp_lt_i32 s18, 64
	s_cselect_b32 s3, s3, s13
	s_mul_i32 s22, s3, 0x1800
	s_ashr_i32 s23, s22, 31
	s_lshl_b32 s20, s51, 8
	s_lshl_b64 s[22:23], s[22:23], 2
	v_or_b32_e32 v72, s20, v170
	s_add_u32 s22, s80, s22
	s_addc_u32 s23, s81, s23
	v_ashrrev_i32_e32 v73, 31, v72
	s_ashr_i32 s3, s2, 31
	v_lshl_add_u64 v[72:73], v[72:73], 2, s[22:23]
	s_lshl_b64 s[22:23], s[2:3], 11
	s_add_u32 s13, s40, s22
	s_addc_u32 s18, s41, s23
	s_ashr_i32 s21, s20, 31
	s_lshl_b64 s[22:23], s[20:21], 1
	s_add_u32 s13, s13, s22
	v_lshl_add_u64 v[74:75], v[72:73], 0, s[10:11]
	v_add_co_u32_e32 v72, vcc, s49, v72
	s_addc_u32 s18, s18, s23
	s_lshl_b32 s22, s42, 1
	v_addc_co_u32_e32 v73, vcc, 0, v73, vcc
	s_add_u32 s22, s13, s22
	global_load_dwordx4 v[88:91], v[74:75], off offset:64
	global_load_dwordx4 v[76:79], v[74:75], off offset:512
	global_load_dwordx4 v[92:95], v[72:73], off
	s_nop 0
	global_load_dwordx4 v[72:75], v[74:75], off offset:576
	s_addc_u32 s23, s18, 0
	v_lshlrev_b32_e32 v152, 1, v154
	v_lshl_add_u64 v[168:169], s[22:23], 0, v[152:153]
	v_lshl_add_u64 v[166:167], v[156:157], 1, v[168:169]
	global_load_dwordx2 v[178:179], v[166:167], off
	v_add_co_u32_e32 v166, vcc, s39, v166
	s_lshl_b64 s[2:3], s[2:3], 12
	s_nop 0
	v_addc_co_u32_e32 v167, vcc, 0, v167, vcc
	global_load_dwordx2 v[180:181], v[166:167], off
	s_add_u32 s13, s78, s2
	s_addc_u32 s18, s79, s3
	s_lshl_b64 s[2:3], s[20:21], 2
	s_add_u32 s2, s13, s2
	s_addc_u32 s3, s18, s3
	s_lshl_b32 s13, s42, 2
	s_add_u32 s2, s2, s13
	s_addc_u32 s3, s3, 0
	v_lshlrev_b32_e32 v152, 2, v154
	v_lshl_add_u64 v[166:167], s[2:3], 0, v[152:153]
	v_mov_b32_e32 v152, v171
	v_lshl_add_u64 v[188:189], v[156:157], 2, v[166:167]
	v_lshl_add_u64 v[182:183], v[152:153], 1, v[168:169]
	global_load_dwordx2 v[184:185], v[182:183], off
	v_add_co_u32_e32 v182, vcc, s39, v182
	v_lshl_add_u64 v[192:193], v[152:153], 2, v[166:167]
	s_nop 0
	v_addc_co_u32_e32 v183, vcc, 0, v183, vcc
	global_load_dwordx2 v[182:183], v[182:183], off
	v_add_co_u32_e32 v190, vcc, s45, v188
	v_mov_b32_e32 v187, v153
	s_nop 0
	v_addc_co_u32_e32 v191, vcc, 0, v189, vcc
	v_add_u32_e32 v186, 0x3f80, v152
	v_add_co_u32_e32 v194, vcc, s45, v192
	s_waitcnt vmcnt(0)
	v_pk_mul_f32 v[138:139], v[138:139], v[90:91]
	v_pk_mul_f32 v[136:137], v[136:137], v[88:89]
	v_pk_mul_f32 v[142:143], v[142:143], v[94:95]
	v_pk_mul_f32 v[140:141], v[140:141], v[92:93]
	ds_write_b128 v176, v[140:143]
	ds_write_b128 v176, v[136:139] offset:64
	ds_read_b128 v[136:139], v172
	ds_read_b128 v[140:143], v172 offset:1152
	v_pk_mul_f32 v[134:135], v[134:135], v[78:79]
	v_pk_mul_f32 v[132:133], v[132:133], v[76:77]
	v_lshlrev_b32_e32 v196, 16, v178
	v_and_b32_e32 v197, 0xffff0000, v178
	v_lshlrev_b32_e32 v178, 16, v179
	v_and_b32_e32 v179, 0xffff0000, v179
	s_waitcnt lgkmcnt(1)
	v_pk_add_f32 v[136:137], v[136:137], v[196:197]
	v_pk_add_f32 v[138:139], v[138:139], v[178:179]
	v_lshlrev_b32_e32 v178, 16, v180
	v_and_b32_e32 v179, 0xffff0000, v180
	v_lshlrev_b32_e32 v180, 16, v181
	v_and_b32_e32 v181, 0xffff0000, v181
	global_store_dwordx4 v[188:189], v[136:139], off
	v_addc_co_u32_e32 v195, vcc, 0, v193, vcc
	s_waitcnt lgkmcnt(0)
	v_pk_add_f32 v[136:137], v[140:141], v[178:179]
	v_pk_add_f32 v[138:139], v[142:143], v[180:181]
	global_store_dwordx4 v[190:191], v[136:139], off
	v_pk_mul_f32 v[130:131], v[130:131], v[74:75]
	v_pk_mul_f32 v[128:129], v[128:129], v[72:73]
	ds_write_b128 v176, v[132:135]
	v_lshl_add_u64 v[132:133], v[186:187], 1, v[168:169]
	ds_write_b128 v176, v[128:131] offset:64
	v_add_co_u32_e32 v128, vcc, s39, v132
	global_load_dwordx2 v[136:137], v[132:133], off
	s_nop 0
	v_addc_co_u32_e32 v129, vcc, 0, v133, vcc
	global_load_dwordx2 v[138:139], v[128:129], off
	ds_read_b128 v[128:131], v172
	ds_read_b128 v[132:135], v172 offset:1152
	v_lshlrev_b32_e32 v140, 16, v184
	v_and_b32_e32 v141, 0xffff0000, v184
	v_lshlrev_b32_e32 v142, 16, v185
	v_and_b32_e32 v143, 0xffff0000, v185
	v_lshlrev_b32_e32 v178, 16, v182
	v_and_b32_e32 v179, 0xffff0000, v182
	v_lshlrev_b32_e32 v180, 16, v183
	v_and_b32_e32 v181, 0xffff0000, v183
	s_waitcnt lgkmcnt(1)
	v_pk_add_f32 v[128:129], v[128:129], v[140:141]
	v_pk_add_f32 v[130:131], v[130:131], v[142:143]
	v_add_u32_e32 v152, 0x80, v186
	s_waitcnt lgkmcnt(0)
	v_pk_add_f32 v[132:133], v[132:133], v[178:179]
	v_pk_add_f32 v[134:135], v[134:135], v[180:181]
	global_store_dwordx4 v[192:193], v[128:131], off
	global_store_dwordx4 v[194:195], v[132:135], off
	v_pk_mul_f32 v[126:127], v[126:127], v[94:95]
	v_lshl_add_u64 v[128:129], v[152:153], 1, v[168:169]
	global_load_dwordx2 v[130:131], v[128:129], off
	v_add_co_u32_e32 v128, vcc, s39, v128
	v_pk_mul_f32 v[124:125], v[124:125], v[92:93]
	s_nop 0
	v_addc_co_u32_e32 v129, vcc, 0, v129, vcc
	global_load_dwordx2 v[128:129], v[128:129], off
	v_pk_mul_f32 v[122:123], v[122:123], v[90:91]
	v_pk_mul_f32 v[120:121], v[120:121], v[88:89]
	ds_write_b128 v176, v[124:127]
	ds_write_b128 v176, v[120:123] offset:64
	ds_read_b128 v[120:123], v172
	ds_read_b128 v[124:127], v172 offset:1152
	v_lshl_add_u64 v[134:135], v[186:187], 2, v[166:167]
	v_add_co_u32_e32 v140, vcc, s45, v134
	v_lshl_add_u64 v[142:143], v[152:153], 2, v[166:167]
	s_nop 0
	v_addc_co_u32_e32 v141, vcc, 0, v135, vcc
	v_mov_b32_e32 v133, v153
	v_pk_mul_f32 v[118:119], v[118:119], v[78:79]
	v_pk_mul_f32 v[116:117], v[116:117], v[76:77]
	v_add_u32_e32 v132, 0x3f80, v152
	v_add_co_u32_e32 v178, vcc, s45, v142
	v_pk_mul_f32 v[114:115], v[114:115], v[74:75]
	v_pk_mul_f32 v[112:113], v[112:113], v[72:73]
	v_addc_co_u32_e32 v179, vcc, 0, v143, vcc
	v_pk_mul_f32 v[110:111], v[110:111], v[94:95]
	v_pk_mul_f32 v[108:109], v[108:109], v[92:93]
	v_pk_mul_f32 v[106:107], v[106:107], v[90:91]
	v_pk_mul_f32 v[104:105], v[104:105], v[88:89]
	v_pk_mul_f32 v[102:103], v[102:103], v[78:79]
	v_pk_mul_f32 v[100:101], v[100:101], v[76:77]
	v_pk_mul_f32 v[98:99], v[98:99], v[74:75]
	v_pk_mul_f32 v[96:97], v[96:97], v[72:73]
	v_pk_mul_f32 v[86:87], v[86:87], v[94:95]
	v_pk_mul_f32 v[84:85], v[84:85], v[92:93]
	v_pk_mul_f32 v[82:83], v[82:83], v[90:91]
	v_pk_mul_f32 v[80:81], v[80:81], v[88:89]
	v_pk_mul_f32 v[70:71], v[70:71], v[78:79]
	v_pk_mul_f32 v[68:69], v[68:69], v[76:77]
	v_pk_mul_f32 v[66:67], v[66:67], v[74:75]
	v_pk_mul_f32 v[64:65], v[64:65], v[72:73]
	v_pk_mul_f32 v[62:63], v[62:63], v[94:95]
	v_pk_mul_f32 v[60:61], v[60:61], v[92:93]
	v_pk_mul_f32 v[58:59], v[58:59], v[90:91]
	v_pk_mul_f32 v[56:57], v[56:57], v[88:89]
	v_pk_mul_f32 v[54:55], v[54:55], v[78:79]
	v_pk_mul_f32 v[52:53], v[52:53], v[76:77]
	v_pk_mul_f32 v[50:51], v[50:51], v[74:75]
	v_pk_mul_f32 v[48:49], v[48:49], v[72:73]
	v_pk_mul_f32 v[46:47], v[46:47], v[94:95]
	v_pk_mul_f32 v[44:45], v[44:45], v[92:93]
	v_pk_mul_f32 v[42:43], v[42:43], v[90:91]
	v_pk_mul_f32 v[40:41], v[40:41], v[88:89]
	v_pk_mul_f32 v[38:39], v[38:39], v[78:79]
	v_pk_mul_f32 v[36:37], v[36:37], v[76:77]
	s_waitcnt vmcnt(5)
	v_lshlrev_b32_e32 v180, 16, v136
	v_and_b32_e32 v181, 0xffff0000, v136
	v_lshlrev_b32_e32 v136, 16, v137
	v_and_b32_e32 v137, 0xffff0000, v137
	s_waitcnt lgkmcnt(1)
	v_pk_add_f32 v[120:121], v[120:121], v[180:181]
	v_pk_add_f32 v[122:123], v[122:123], v[136:137]
	s_waitcnt vmcnt(4)
	v_lshlrev_b32_e32 v136, 16, v138
	v_and_b32_e32 v137, 0xffff0000, v138
	v_lshlrev_b32_e32 v138, 16, v139
	v_and_b32_e32 v139, 0xffff0000, v139
	global_store_dwordx4 v[134:135], v[120:123], off
	v_pk_mul_f32 v[34:35], v[34:35], v[74:75]
	v_pk_mul_f32 v[32:33], v[32:33], v[72:73]
	s_waitcnt lgkmcnt(0)
	v_pk_add_f32 v[120:121], v[124:125], v[136:137]
	v_pk_add_f32 v[122:123], v[126:127], v[138:139]
	global_store_dwordx4 v[140:141], v[120:123], off
	ds_write_b128 v176, v[116:119]
	v_lshl_add_u64 v[116:117], v[132:133], 1, v[168:169]
	ds_write_b128 v176, v[112:115] offset:64
	v_add_co_u32_e32 v112, vcc, s39, v116
	global_load_dwordx2 v[120:121], v[116:117], off
	s_nop 0
	v_addc_co_u32_e32 v113, vcc, 0, v117, vcc
	global_load_dwordx2 v[122:123], v[112:113], off
	ds_read_b128 v[112:115], v172
	ds_read_b128 v[116:119], v172 offset:1152
	s_waitcnt vmcnt(5)
	v_lshlrev_b32_e32 v124, 16, v130
	v_and_b32_e32 v125, 0xffff0000, v130
	v_lshlrev_b32_e32 v126, 16, v131
	v_and_b32_e32 v127, 0xffff0000, v131
	s_waitcnt vmcnt(4)
	v_lshlrev_b32_e32 v130, 16, v128
	v_and_b32_e32 v131, 0xffff0000, v128
	v_lshlrev_b32_e32 v128, 16, v129
	v_and_b32_e32 v129, 0xffff0000, v129
	s_waitcnt lgkmcnt(1)
	v_pk_add_f32 v[112:113], v[112:113], v[124:125]
	v_pk_add_f32 v[114:115], v[114:115], v[126:127]
	v_add_u32_e32 v152, 0x80, v132
	s_waitcnt lgkmcnt(0)
	v_pk_add_f32 v[116:117], v[116:117], v[130:131]
	v_pk_add_f32 v[118:119], v[118:119], v[128:129]
	global_store_dwordx4 v[142:143], v[112:115], off
	global_store_dwordx4 v[178:179], v[116:119], off
	v_pk_mul_f32 v[30:31], v[30:31], v[94:95]
	v_lshl_add_u64 v[112:113], v[152:153], 1, v[168:169]
	global_load_dwordx2 v[114:115], v[112:113], off
	v_add_co_u32_e32 v112, vcc, s39, v112
	v_lshl_add_u64 v[118:119], v[132:133], 2, v[166:167]
	s_nop 0
	v_addc_co_u32_e32 v113, vcc, 0, v113, vcc
	global_load_dwordx2 v[112:113], v[112:113], off
	ds_write_b128 v176, v[108:111]
	ds_write_b128 v176, v[104:107] offset:64
	ds_read_b128 v[104:107], v172
	ds_read_b128 v[108:111], v172 offset:1152
	v_add_co_u32_e32 v124, vcc, s45, v118
	v_lshl_add_u64 v[126:127], v[152:153], 2, v[166:167]
	s_nop 0
	v_addc_co_u32_e32 v125, vcc, 0, v119, vcc
	v_mov_b32_e32 v117, v153
	v_add_u32_e32 v116, 0x3f80, v152
	v_add_co_u32_e32 v128, vcc, s45, v126
	v_pk_mul_f32 v[28:29], v[28:29], v[92:93]
	s_nop 0
	v_addc_co_u32_e32 v129, vcc, 0, v127, vcc
	v_pk_mul_f32 v[26:27], v[26:27], v[90:91]
	v_pk_mul_f32 v[24:25], v[24:25], v[88:89]
	v_pk_mul_f32 v[22:23], v[22:23], v[78:79]
	v_pk_mul_f32 v[20:21], v[20:21], v[76:77]
	v_pk_mul_f32 v[18:19], v[18:19], v[74:75]
	v_pk_mul_f32 v[16:17], v[16:17], v[72:73]
	v_pk_mul_f32 v[14:15], v[14:15], v[94:95]
	v_pk_mul_f32 v[12:13], v[12:13], v[92:93]
	v_pk_mul_f32 v[10:11], v[10:11], v[90:91]
	v_pk_mul_f32 v[8:9], v[8:9], v[88:89]
	v_pk_mul_f32 v[6:7], v[6:7], v[78:79]
	v_pk_mul_f32 v[4:5], v[4:5], v[76:77]
	v_pk_mul_f32 v[2:3], v[2:3], v[74:75]
	v_pk_mul_f32 v[0:1], v[0:1], v[72:73]
	s_waitcnt vmcnt(5)
	v_lshlrev_b32_e32 v130, 16, v120
	v_and_b32_e32 v131, 0xffff0000, v120
	v_lshlrev_b32_e32 v120, 16, v121
	v_and_b32_e32 v121, 0xffff0000, v121
	s_waitcnt lgkmcnt(1)
	v_pk_add_f32 v[104:105], v[104:105], v[130:131]
	v_pk_add_f32 v[106:107], v[106:107], v[120:121]
	s_waitcnt vmcnt(4)
	v_lshlrev_b32_e32 v120, 16, v122
	v_and_b32_e32 v121, 0xffff0000, v122
	v_lshlrev_b32_e32 v122, 16, v123
	v_and_b32_e32 v123, 0xffff0000, v123
	global_store_dwordx4 v[118:119], v[104:107], off
	s_waitcnt lgkmcnt(0)
	s_nop 0
	v_pk_add_f32 v[104:105], v[108:109], v[120:121]
	v_pk_add_f32 v[106:107], v[110:111], v[122:123]
	global_store_dwordx4 v[124:125], v[104:107], off
	ds_write_b128 v176, v[100:103]
	v_lshl_add_u64 v[100:101], v[116:117], 1, v[168:169]
	ds_write_b128 v176, v[96:99] offset:64
	v_add_co_u32_e32 v96, vcc, s39, v100
	global_load_dwordx2 v[104:105], v[100:101], off
	s_nop 0
	v_addc_co_u32_e32 v97, vcc, 0, v101, vcc
	global_load_dwordx2 v[106:107], v[96:97], off
	ds_read_b128 v[96:99], v172
	ds_read_b128 v[100:103], v172 offset:1152
	s_waitcnt vmcnt(5)
	v_lshlrev_b32_e32 v108, 16, v114
	v_and_b32_e32 v109, 0xffff0000, v114
	v_lshlrev_b32_e32 v110, 16, v115
	v_and_b32_e32 v111, 0xffff0000, v115
	s_waitcnt vmcnt(4)
	v_lshlrev_b32_e32 v114, 16, v112
	v_and_b32_e32 v115, 0xffff0000, v112
	v_lshlrev_b32_e32 v112, 16, v113
	v_and_b32_e32 v113, 0xffff0000, v113
	s_waitcnt lgkmcnt(1)
	v_pk_add_f32 v[96:97], v[96:97], v[108:109]
	v_pk_add_f32 v[98:99], v[98:99], v[110:111]
	v_add_u32_e32 v152, 0x80, v116
	s_waitcnt lgkmcnt(0)
	v_pk_add_f32 v[100:101], v[100:101], v[114:115]
	v_pk_add_f32 v[102:103], v[102:103], v[112:113]
	global_store_dwordx4 v[126:127], v[96:99], off
	global_store_dwordx4 v[128:129], v[100:103], off
	s_waitcnt vmcnt(3)
	v_lshlrev_b32_e32 v114, 16, v104
	v_lshl_add_u64 v[96:97], v[152:153], 1, v[168:169]
	global_load_dwordx2 v[98:99], v[96:97], off
	v_add_co_u32_e32 v96, vcc, s39, v96
	v_lshl_add_u64 v[102:103], v[116:117], 2, v[166:167]
	s_nop 0
	v_addc_co_u32_e32 v97, vcc, 0, v97, vcc
	global_load_dwordx2 v[96:97], v[96:97], off
	ds_write_b128 v176, v[84:87]
	ds_write_b128 v176, v[80:83] offset:64
	ds_read_b128 v[80:83], v172
	ds_read_b128 v[84:87], v172 offset:1152
	v_and_b32_e32 v115, 0xffff0000, v104
	v_lshlrev_b32_e32 v104, 16, v105
	v_and_b32_e32 v105, 0xffff0000, v105
	v_add_co_u32_e32 v108, vcc, s45, v102
	s_waitcnt lgkmcnt(1)
	v_pk_add_f32 v[80:81], v[80:81], v[114:115]
	v_pk_add_f32 v[82:83], v[82:83], v[104:105]
	s_waitcnt vmcnt(4)
	v_lshlrev_b32_e32 v104, 16, v106
	v_and_b32_e32 v105, 0xffff0000, v106
	v_lshlrev_b32_e32 v106, 16, v107
	v_and_b32_e32 v107, 0xffff0000, v107
	v_addc_co_u32_e32 v109, vcc, 0, v103, vcc
	v_lshl_add_u64 v[110:111], v[152:153], 2, v[166:167]
	global_store_dwordx4 v[102:103], v[80:83], off
	v_mov_b32_e32 v101, v153
	v_add_u32_e32 v100, 0x13f80, v152
	s_waitcnt lgkmcnt(0)
	v_pk_add_f32 v[80:81], v[84:85], v[104:105]
	v_pk_add_f32 v[82:83], v[86:87], v[106:107]
	v_add_co_u32_e32 v112, vcc, s45, v110
	global_store_dwordx4 v[108:109], v[80:83], off
	s_nop 0
	v_addc_co_u32_e32 v113, vcc, 0, v111, vcc
	ds_write_b128 v176, v[68:71]
	v_lshl_add_u64 v[68:69], v[100:101], 1, v[168:169]
	ds_write_b128 v176, v[64:67] offset:64
	v_add_co_u32_e32 v64, vcc, s39, v68
	global_load_dwordx2 v[80:81], v[68:69], off
	s_nop 0
	v_addc_co_u32_e32 v65, vcc, 0, v69, vcc
	global_load_dwordx2 v[82:83], v[64:65], off
	ds_read_b128 v[64:67], v172
	ds_read_b128 v[68:71], v172 offset:1152
	v_add_u32_e32 v152, 0x80, v100
	s_waitcnt vmcnt(5)
	v_lshlrev_b32_e32 v84, 16, v98
	v_and_b32_e32 v85, 0xffff0000, v98
	v_lshlrev_b32_e32 v86, 16, v99
	v_and_b32_e32 v87, 0xffff0000, v99
	s_waitcnt lgkmcnt(1)
	v_pk_add_f32 v[64:65], v[64:65], v[84:85]
	v_pk_add_f32 v[66:67], v[66:67], v[86:87]
	s_waitcnt vmcnt(4)
	v_lshlrev_b32_e32 v98, 16, v96
	v_and_b32_e32 v99, 0xffff0000, v96
	v_lshlrev_b32_e32 v96, 16, v97
	v_and_b32_e32 v97, 0xffff0000, v97
	s_waitcnt lgkmcnt(0)
	v_pk_add_f32 v[68:69], v[68:69], v[98:99]
	v_pk_add_f32 v[70:71], v[70:71], v[96:97]
	global_store_dwordx4 v[110:111], v[64:67], off
	global_store_dwordx4 v[112:113], v[68:71], off
	s_waitcnt vmcnt(3)
	v_lshlrev_b32_e32 v98, 16, v80
	v_lshl_add_u64 v[64:65], v[152:153], 1, v[168:169]
	global_load_dwordx2 v[66:67], v[64:65], off
	v_add_co_u32_e32 v64, vcc, s39, v64
	v_lshl_add_u64 v[70:71], v[100:101], 2, v[166:167]
	s_nop 0
	v_addc_co_u32_e32 v65, vcc, 0, v65, vcc
	global_load_dwordx2 v[64:65], v[64:65], off
	ds_write_b128 v176, v[60:63]
	ds_write_b128 v176, v[56:59] offset:64
	ds_read_b128 v[56:59], v172
	ds_read_b128 v[60:63], v172 offset:1152
	v_and_b32_e32 v99, 0xffff0000, v80
	v_lshlrev_b32_e32 v80, 16, v81
	v_and_b32_e32 v81, 0xffff0000, v81
	v_add_co_u32_e32 v84, vcc, s45, v70
	s_waitcnt lgkmcnt(1)
	v_pk_add_f32 v[56:57], v[56:57], v[98:99]
	v_pk_add_f32 v[58:59], v[58:59], v[80:81]
	s_waitcnt vmcnt(4)
	v_lshlrev_b32_e32 v80, 16, v82
	v_and_b32_e32 v81, 0xffff0000, v82
	v_lshlrev_b32_e32 v82, 16, v83
	v_and_b32_e32 v83, 0xffff0000, v83
	v_addc_co_u32_e32 v85, vcc, 0, v71, vcc
	v_lshl_add_u64 v[86:87], v[152:153], 2, v[166:167]
	global_store_dwordx4 v[70:71], v[56:59], off
	v_mov_b32_e32 v69, v153
	v_add_u32_e32 v68, 0x3f80, v152
	s_waitcnt lgkmcnt(0)
	v_pk_add_f32 v[56:57], v[60:61], v[80:81]
	v_pk_add_f32 v[58:59], v[62:63], v[82:83]
	v_add_co_u32_e32 v96, vcc, s45, v86
	global_store_dwordx4 v[84:85], v[56:59], off
	s_nop 0
	v_addc_co_u32_e32 v97, vcc, 0, v87, vcc
	ds_write_b128 v176, v[52:55]
	v_lshl_add_u64 v[52:53], v[68:69], 1, v[168:169]
	ds_write_b128 v176, v[48:51] offset:64
	v_add_co_u32_e32 v48, vcc, s39, v52
	global_load_dwordx2 v[56:57], v[52:53], off
	s_nop 0
	v_addc_co_u32_e32 v49, vcc, 0, v53, vcc
	global_load_dwordx2 v[58:59], v[48:49], off
	ds_read_b128 v[48:51], v172
	ds_read_b128 v[52:55], v172 offset:1152
	v_add_u32_e32 v152, 0x80, v68
	s_waitcnt vmcnt(5)
	v_lshlrev_b32_e32 v60, 16, v66
	v_and_b32_e32 v61, 0xffff0000, v66
	v_lshlrev_b32_e32 v62, 16, v67
	v_and_b32_e32 v63, 0xffff0000, v67
	s_waitcnt lgkmcnt(1)
	v_pk_add_f32 v[48:49], v[48:49], v[60:61]
	v_pk_add_f32 v[50:51], v[50:51], v[62:63]
	s_waitcnt vmcnt(4)
	v_lshlrev_b32_e32 v66, 16, v64
	v_and_b32_e32 v67, 0xffff0000, v64
	v_lshlrev_b32_e32 v64, 16, v65
	v_and_b32_e32 v65, 0xffff0000, v65
	s_waitcnt lgkmcnt(0)
	v_pk_add_f32 v[52:53], v[52:53], v[66:67]
	v_pk_add_f32 v[54:55], v[54:55], v[64:65]
	global_store_dwordx4 v[86:87], v[48:51], off
	global_store_dwordx4 v[96:97], v[52:55], off
	s_waitcnt vmcnt(3)
	v_lshlrev_b32_e32 v66, 16, v56
	v_lshl_add_u64 v[48:49], v[152:153], 1, v[168:169]
	global_load_dwordx2 v[50:51], v[48:49], off
	v_add_co_u32_e32 v48, vcc, s39, v48
	v_lshl_add_u64 v[54:55], v[68:69], 2, v[166:167]
	s_nop 0
	v_addc_co_u32_e32 v49, vcc, 0, v49, vcc
	global_load_dwordx2 v[48:49], v[48:49], off
	ds_write_b128 v176, v[44:47]
	ds_write_b128 v176, v[40:43] offset:64
	ds_read_b128 v[40:43], v172
	ds_read_b128 v[44:47], v172 offset:1152
	v_and_b32_e32 v67, 0xffff0000, v56
	v_lshlrev_b32_e32 v56, 16, v57
	v_and_b32_e32 v57, 0xffff0000, v57
	v_add_co_u32_e32 v60, vcc, s45, v54
	s_waitcnt lgkmcnt(1)
	v_pk_add_f32 v[40:41], v[40:41], v[66:67]
	v_pk_add_f32 v[42:43], v[42:43], v[56:57]
	s_waitcnt vmcnt(4)
	v_lshlrev_b32_e32 v56, 16, v58
	v_and_b32_e32 v57, 0xffff0000, v58
	v_lshlrev_b32_e32 v58, 16, v59
	v_and_b32_e32 v59, 0xffff0000, v59
	v_addc_co_u32_e32 v61, vcc, 0, v55, vcc
	v_lshl_add_u64 v[62:63], v[152:153], 2, v[166:167]
	global_store_dwordx4 v[54:55], v[40:43], off
	v_mov_b32_e32 v53, v153
	v_add_u32_e32 v52, 0x3f80, v152
	s_waitcnt lgkmcnt(0)
	v_pk_add_f32 v[40:41], v[44:45], v[56:57]
	v_pk_add_f32 v[42:43], v[46:47], v[58:59]
	v_add_co_u32_e32 v64, vcc, s45, v62
	global_store_dwordx4 v[60:61], v[40:43], off
	s_nop 0
	v_addc_co_u32_e32 v65, vcc, 0, v63, vcc
	ds_write_b128 v176, v[36:39]
	v_lshl_add_u64 v[36:37], v[52:53], 1, v[168:169]
	ds_write_b128 v176, v[32:35] offset:64
	v_add_co_u32_e32 v32, vcc, s39, v36
	global_load_dwordx2 v[40:41], v[36:37], off
	s_nop 0
	v_addc_co_u32_e32 v33, vcc, 0, v37, vcc
	global_load_dwordx2 v[42:43], v[32:33], off
	ds_read_b128 v[32:35], v172
	ds_read_b128 v[36:39], v172 offset:1152
	v_add_u32_e32 v152, 0x80, v52
	s_waitcnt vmcnt(5)
	v_lshlrev_b32_e32 v44, 16, v50
	v_and_b32_e32 v45, 0xffff0000, v50
	v_lshlrev_b32_e32 v46, 16, v51
	v_and_b32_e32 v47, 0xffff0000, v51
	s_waitcnt lgkmcnt(1)
	v_pk_add_f32 v[32:33], v[32:33], v[44:45]
	v_pk_add_f32 v[34:35], v[34:35], v[46:47]
	s_waitcnt vmcnt(4)
	v_lshlrev_b32_e32 v50, 16, v48
	v_and_b32_e32 v51, 0xffff0000, v48
	v_lshlrev_b32_e32 v48, 16, v49
	v_and_b32_e32 v49, 0xffff0000, v49
	s_waitcnt lgkmcnt(0)
	v_pk_add_f32 v[36:37], v[36:37], v[50:51]
	v_pk_add_f32 v[38:39], v[38:39], v[48:49]
	global_store_dwordx4 v[62:63], v[32:35], off
	global_store_dwordx4 v[64:65], v[36:39], off
	s_waitcnt vmcnt(3)
	v_lshlrev_b32_e32 v50, 16, v40
	v_lshl_add_u64 v[32:33], v[152:153], 1, v[168:169]
	global_load_dwordx2 v[34:35], v[32:33], off
	v_add_co_u32_e32 v32, vcc, s39, v32
	v_lshl_add_u64 v[38:39], v[52:53], 2, v[166:167]
	s_nop 0
	v_addc_co_u32_e32 v33, vcc, 0, v33, vcc
	global_load_dwordx2 v[32:33], v[32:33], off
	ds_write_b128 v176, v[28:31]
	ds_write_b128 v176, v[24:27] offset:64
	ds_read_b128 v[24:27], v172
	ds_read_b128 v[28:31], v172 offset:1152
	v_and_b32_e32 v51, 0xffff0000, v40
	v_lshlrev_b32_e32 v40, 16, v41
	v_and_b32_e32 v41, 0xffff0000, v41
	v_add_co_u32_e32 v44, vcc, s45, v38
	s_waitcnt lgkmcnt(1)
	v_pk_add_f32 v[24:25], v[24:25], v[50:51]
	v_pk_add_f32 v[26:27], v[26:27], v[40:41]
	s_waitcnt vmcnt(4)
	v_lshlrev_b32_e32 v40, 16, v42
	v_and_b32_e32 v41, 0xffff0000, v42
	v_lshlrev_b32_e32 v42, 16, v43
	v_and_b32_e32 v43, 0xffff0000, v43
	v_addc_co_u32_e32 v45, vcc, 0, v39, vcc
	v_lshl_add_u64 v[46:47], v[152:153], 2, v[166:167]
	global_store_dwordx4 v[38:39], v[24:27], off
	v_mov_b32_e32 v37, v153
	v_add_u32_e32 v36, 0x3f80, v152
	s_waitcnt lgkmcnt(0)
	v_pk_add_f32 v[24:25], v[28:29], v[40:41]
	v_pk_add_f32 v[26:27], v[30:31], v[42:43]
	v_add_co_u32_e32 v48, vcc, s45, v46
	global_store_dwordx4 v[44:45], v[24:27], off
	s_nop 0
	v_addc_co_u32_e32 v49, vcc, 0, v47, vcc
	ds_write_b128 v176, v[20:23]
	ds_write_b128 v176, v[16:19] offset:64
	v_lshl_add_u64 v[24:25], v[36:37], 1, v[168:169]
	ds_read_b128 v[16:19], v172
	ds_read_b128 v[20:23], v172 offset:1152
	v_add_co_u32_e32 v26, vcc, s39, v24
	v_add_u32_e32 v152, 0x80, v36
	s_nop 0
	v_addc_co_u32_e32 v27, vcc, 0, v25, vcc
	global_load_dwordx2 v[28:29], v[24:25], off
	global_load_dwordx2 v[30:31], v[26:27], off
	s_waitcnt vmcnt(5)
	v_lshlrev_b32_e32 v24, 16, v34
	v_and_b32_e32 v25, 0xffff0000, v34
	v_lshlrev_b32_e32 v26, 16, v35
	v_and_b32_e32 v27, 0xffff0000, v35
	s_waitcnt lgkmcnt(1)
	v_pk_add_f32 v[16:17], v[16:17], v[24:25]
	v_pk_add_f32 v[18:19], v[18:19], v[26:27]
	s_waitcnt vmcnt(4)
	v_lshlrev_b32_e32 v34, 16, v32
	v_and_b32_e32 v35, 0xffff0000, v32
	v_lshlrev_b32_e32 v32, 16, v33
	v_and_b32_e32 v33, 0xffff0000, v33
	s_waitcnt lgkmcnt(0)
	v_pk_add_f32 v[20:21], v[20:21], v[34:35]
	v_pk_add_f32 v[22:23], v[22:23], v[32:33]
	global_store_dwordx4 v[46:47], v[16:19], off
	global_store_dwordx4 v[48:49], v[20:23], off
	s_waitcnt vmcnt(3)
	v_lshlrev_b32_e32 v32, 16, v28
	v_lshl_add_u64 v[16:17], v[152:153], 1, v[168:169]
	global_load_dwordx2 v[18:19], v[16:17], off
	v_add_co_u32_e32 v16, vcc, s39, v16
	v_lshl_add_u64 v[20:21], v[36:37], 2, v[166:167]
	s_nop 0
	v_addc_co_u32_e32 v17, vcc, 0, v17, vcc
	global_load_dwordx2 v[16:17], v[16:17], off
	ds_write_b128 v176, v[12:15]
	ds_write_b128 v176, v[8:11] offset:64
	ds_read_b128 v[8:11], v172
	ds_read_b128 v[12:15], v172 offset:1152
	v_and_b32_e32 v33, 0xffff0000, v28
	v_lshlrev_b32_e32 v28, 16, v29
	v_and_b32_e32 v29, 0xffff0000, v29
	v_add_co_u32_e32 v22, vcc, s45, v20
	s_waitcnt lgkmcnt(1)
	v_pk_add_f32 v[8:9], v[8:9], v[32:33]
	v_pk_add_f32 v[10:11], v[10:11], v[28:29]
	s_waitcnt vmcnt(4)
	v_lshlrev_b32_e32 v28, 16, v30
	v_and_b32_e32 v29, 0xffff0000, v30
	v_lshlrev_b32_e32 v30, 16, v31
	v_and_b32_e32 v31, 0xffff0000, v31
	v_addc_co_u32_e32 v23, vcc, 0, v21, vcc
	global_store_dwordx4 v[20:21], v[8:11], off
	v_add_u32_e32 v34, 0x13f80, v152
	v_lshl_add_u64 v[24:25], v[152:153], 2, v[166:167]
	s_waitcnt lgkmcnt(0)
	v_pk_add_f32 v[8:9], v[12:13], v[28:29]
	v_pk_add_f32 v[10:11], v[14:15], v[30:31]
	global_store_dwordx4 v[22:23], v[8:11], off
	ds_write_b128 v176, v[4:7]
	ds_write_b128 v176, v[0:3] offset:64
	ds_read_b128 v[0:3], v172
	ds_read_b128 v[4:7], v172 offset:1152
	v_add_co_u32_e32 v26, vcc, 0x8000, v24
	s_waitcnt vmcnt(3)
	v_lshlrev_b32_e32 v8, 16, v18
	v_and_b32_e32 v9, 0xffff0000, v18
	v_lshlrev_b32_e32 v10, 16, v19
	v_and_b32_e32 v11, 0xffff0000, v19
	s_waitcnt lgkmcnt(1)
	v_pk_add_f32 v[0:1], v[0:1], v[8:9]
	v_pk_add_f32 v[2:3], v[2:3], v[10:11]
	s_waitcnt vmcnt(2)
	v_lshlrev_b32_e32 v12, 16, v16
	v_and_b32_e32 v13, 0xffff0000, v16
	v_lshlrev_b32_e32 v14, 16, v17
	v_and_b32_e32 v15, 0xffff0000, v17
	v_addc_co_u32_e32 v27, vcc, 0, v25, vcc
	s_waitcnt lgkmcnt(0)
	v_pk_add_f32 v[4:5], v[4:5], v[12:13]
	v_pk_add_f32 v[6:7], v[6:7], v[14:15]
	global_store_dwordx4 v[24:25], v[0:3], off
	global_store_dwordx4 v[26:27], v[4:7], off
	s_and_b64 vcc, exec, s[0:1]
	s_mov_b64 s[0:1], -1
	s_cbranch_vccnz .LBB0_1023
	s_andn2_b64 vcc, exec, s[4:5]
	s_cbranch_vccnz .LBB0_1022
	s_barrier
	s_branch .LBB0_1022
